# P8 gate-up epilogue hand-rewritten (DPP-fused conv fmac, -log2e folded), P0 rows + P11 pipelined, P4 tail waits recounted
# speedup vs baseline: 1.0214x; 1.0023x over previous
; __device__ __forceinline__ unsigned cvt_pk_bf16(float lo, float hi) { unsigned r; asm volatile("v_cvt_pk_bf16_f32 %0, %1, %2" : "=v"(r) : "v"(lo), "v"(hi)); return r; }
; __device__ __forceinline__ void rmsnorm_row_bf16(const float* __restrict__ src, const float* __restrict__ w, bf16_t* __restrict__ dst, int lane) {
;     f32x4 v[8]; float ss = 0.f;
; #pragma unroll
;     for (int i = 0; i < 8; ++i) { v[i] = __builtin_nontemporal_load((const f32x4*)(src + i * 256 + lane * 4)); ss += v[i][0] * v[i][0] + v[i][1] * v[i][1] + v[i][2] * v[i][2] + v[i][3] * v[i][3]; }
;     ss = wave_sum(ss);
;     const float rstd = rsqrtf(ss * (1.0f / D) + EPS);
; #pragma unroll
;     for (int i = 0; i < 8; ++i) {
;         const f32x4 g = *(const f32x4*)(w + i * 256 + lane * 4);
;         u32x2 o; o.x = cvt_pk_bf16(v[i][0] * rstd * g[0], v[i][1] * rstd * g[1]); o.y = cvt_pk_bf16(v[i][2] * rstd * g[2], v[i][3] * rstd * g[3]);
;         *(u32x2*)(dst + i * 256 + lane * 4) = o;
;     }
; }
; __device__ void phase_prep(const Params& p, LAS unsigned char* lds) {
;     ...
;     for (int r = blockIdx.x * 8 + w; r < T + 1024; r += gridDim.x * 8) {
;         if (r < T) rmsnorm_row_bf16(p.x + (size_t)r * D, p.norm1_w, (bf16_t*)(ws + WS_H) + (size_t)r * D, lane);
;         else rmsnorm_row_bf16(p.mem + (size_t)(r - T) * D, p.mem_norm_w, (bf16_t*)(ws + WS_MEMN) + (size_t)(r - T) * D, lane);
.LBB0_51:
	s_mov_b64 s[4:5], exec
	s_load_dword s12, s[96:97], 0xc0
	v_and_b32_e32 v1, 63, v206
	v_lshlrev_b32_e32 v2, 4, v1
	v_lshlrev_b32_e32 v3, 3, v1
	v_mov_b32_e32 v4, 0x358637bd
	v_lshl_add_u32 v16, s78, 3, v176
	s_nop 1
	v_readfirstlane_b32 s0, v16
	s_waitcnt lgkmcnt(0)
	s_lshl_b32 s1, s12, 3
	s_add_u32 s12, s72, 0x3c400000
	s_addc_u32 s13, s73, 0
	s_cmp_lt_i32 s0, 0x8000
	s_cbranch_scc0 .Lp0_mem
	global_load_dwordx4 v[100:103], v2, s[58:59]
	global_load_dwordx4 v[104:107], v2, s[58:59] offset:1024
	global_load_dwordx4 v[108:111], v2, s[58:59] offset:2048
	global_load_dwordx4 v[112:115], v2, s[58:59] offset:3072
	s_add_u32 s14, s58, 0x1000
	s_addc_u32 s15, s59, 0
	global_load_dwordx4 v[116:119], v2, s[14:15]
	global_load_dwordx4 v[120:123], v2, s[14:15] offset:1024
	global_load_dwordx4 v[124:127], v2, s[14:15] offset:2048
	global_load_dwordx4 v[128:131], v2, s[14:15] offset:3072
	s_lshl_b32 s8, s0, 13
	s_add_u32 s14, s52, s8
	s_addc_u32 s15, s53, 0
	global_load_dwordx4 v[20:23], v2, s[14:15] nt
	global_load_dwordx4 v[24:27], v2, s[14:15] offset:1024 nt
	global_load_dwordx4 v[28:31], v2, s[14:15] offset:2048 nt
	global_load_dwordx4 v[32:35], v2, s[14:15] offset:3072 nt
	s_add_u32 s14, s14, 0x1000
	s_addc_u32 s15, s15, 0
	global_load_dwordx4 v[36:39], v2, s[14:15] nt
	global_load_dwordx4 v[40:43], v2, s[14:15] offset:1024 nt
	global_load_dwordx4 v[44:47], v2, s[14:15] offset:2048 nt
	global_load_dwordx4 v[48:51], v2, s[14:15] offset:3072 nt
	s_add_i32 s2, s0, s1
	s_cmp_lt_i32 s2, 0x8000
	s_cbranch_scc0 .Lp0_tailA
	s_lshl_b32 s8, s2, 13
	s_add_u32 s14, s52, s8
	s_addc_u32 s15, s53, 0
	global_load_dwordx4 v[52:55], v2, s[14:15] nt
	global_load_dwordx4 v[56:59], v2, s[14:15] offset:1024 nt
	global_load_dwordx4 v[60:63], v2, s[14:15] offset:2048 nt
	global_load_dwordx4 v[64:67], v2, s[14:15] offset:3072 nt
	s_add_u32 s14, s14, 0x1000
	s_addc_u32 s15, s15, 0
	global_load_dwordx4 v[68:71], v2, s[14:15] nt
	global_load_dwordx4 v[72:75], v2, s[14:15] offset:1024 nt
	global_load_dwordx4 v[76:79], v2, s[14:15] offset:2048 nt
	global_load_dwordx4 v[80:83], v2, s[14:15] offset:3072 nt
	s_waitcnt vmcnt(8)
	s_lshl_b32 s8, s0, 12
	s_add_u32 s10, s86, s8
	s_addc_u32 s11, s87, 0
	v_mul_f32_e32 v132, v20, v20
	v_mul_f32_e32 v133, v21, v21
	v_mul_f32_e32 v134, v22, v22
	v_mul_f32_e32 v135, v23, v23
	v_fmac_f32_e32 v132, v24, v24
	v_fmac_f32_e32 v133, v25, v25
	v_fmac_f32_e32 v134, v26, v26
	v_fmac_f32_e32 v135, v27, v27
	v_fmac_f32_e32 v132, v28, v28
	v_fmac_f32_e32 v133, v29, v29
	v_fmac_f32_e32 v134, v30, v30
	v_fmac_f32_e32 v135, v31, v31
	v_fmac_f32_e32 v132, v32, v32
	v_fmac_f32_e32 v133, v33, v33
	v_fmac_f32_e32 v134, v34, v34
	v_fmac_f32_e32 v135, v35, v35
	v_fmac_f32_e32 v132, v36, v36
	v_fmac_f32_e32 v133, v37, v37
	v_fmac_f32_e32 v134, v38, v38
	v_fmac_f32_e32 v135, v39, v39
	v_fmac_f32_e32 v132, v40, v40
	v_fmac_f32_e32 v133, v41, v41
	v_fmac_f32_e32 v134, v42, v42
	v_fmac_f32_e32 v135, v43, v43
	v_fmac_f32_e32 v132, v44, v44
	v_fmac_f32_e32 v133, v45, v45
	v_fmac_f32_e32 v134, v46, v46
	v_fmac_f32_e32 v135, v47, v47
	v_fmac_f32_e32 v132, v48, v48
	v_fmac_f32_e32 v133, v49, v49
	v_fmac_f32_e32 v134, v50, v50
	v_fmac_f32_e32 v135, v51, v51
	v_add_f32_e32 v132, v132, v133
	v_add_f32_e32 v134, v134, v135
	v_add_f32_e32 v132, v132, v134
	s_nop 1
	v_add_f32_dpp v132, v132, v132 quad_perm:[1,0,3,2] row_mask:0xf bank_mask:0xf
	s_nop 1
	v_add_f32_dpp v132, v132, v132 quad_perm:[2,3,0,1] row_mask:0xf bank_mask:0xf
	s_nop 1
	v_add_f32_dpp v132, v132, v132 row_ror:4 row_mask:0xf bank_mask:0xf
	s_nop 1
	v_add_f32_dpp v132, v132, v132 row_ror:8 row_mask:0xf bank_mask:0xf
	s_nop 1
	v_add_f32_dpp v132, v132, v132 row_bcast:15 row_mask:0xa bank_mask:0xf
	s_nop 1
	v_add_f32_dpp v132, v132, v132 row_bcast:31 row_mask:0xc bank_mask:0xf
	s_nop 1
	v_readlane_b32 s8, v132, 63
	s_nop 3
	v_mov_b32_e32 v136, s8
	v_fmamk_f32 v136, v136, 0x3a000000, v4
	v_rsq_f32_e32 v136, v136
	s_nop 1
	v_mul_f32_e32 v20, v20, v136
	v_mul_f32_e32 v21, v21, v136
	v_mul_f32_e32 v22, v22, v136
	v_mul_f32_e32 v23, v23, v136
	v_mul_f32_e32 v24, v24, v136
	v_mul_f32_e32 v25, v25, v136
	v_mul_f32_e32 v26, v26, v136
	v_mul_f32_e32 v27, v27, v136
	v_mul_f32_e32 v28, v28, v136
	v_mul_f32_e32 v29, v29, v136
	v_mul_f32_e32 v30, v30, v136
	v_mul_f32_e32 v31, v31, v136
	v_mul_f32_e32 v32, v32, v136
	v_mul_f32_e32 v33, v33, v136
	v_mul_f32_e32 v34, v34, v136
	v_mul_f32_e32 v35, v35, v136
	v_mul_f32_e32 v36, v36, v136
	v_mul_f32_e32 v37, v37, v136
	v_mul_f32_e32 v38, v38, v136
	v_mul_f32_e32 v39, v39, v136
	v_mul_f32_e32 v40, v40, v136
	v_mul_f32_e32 v41, v41, v136
	v_mul_f32_e32 v42, v42, v136
	v_mul_f32_e32 v43, v43, v136
	v_mul_f32_e32 v44, v44, v136
	v_mul_f32_e32 v45, v45, v136
	v_mul_f32_e32 v46, v46, v136
	v_mul_f32_e32 v47, v47, v136
	v_mul_f32_e32 v48, v48, v136
	v_mul_f32_e32 v49, v49, v136
	v_mul_f32_e32 v50, v50, v136
	v_mul_f32_e32 v51, v51, v136
	v_mul_f32_e32 v20, v20, v100
	v_mul_f32_e32 v21, v21, v101
	v_mul_f32_e32 v22, v22, v102
	v_mul_f32_e32 v23, v23, v103
	v_mul_f32_e32 v24, v24, v104
	v_mul_f32_e32 v25, v25, v105
	v_mul_f32_e32 v26, v26, v106
	v_mul_f32_e32 v27, v27, v107
	v_mul_f32_e32 v28, v28, v108
	v_mul_f32_e32 v29, v29, v109
	v_mul_f32_e32 v30, v30, v110
	v_mul_f32_e32 v31, v31, v111
	v_mul_f32_e32 v32, v32, v112
	v_mul_f32_e32 v33, v33, v113
	v_mul_f32_e32 v34, v34, v114
	v_mul_f32_e32 v35, v35, v115
	v_mul_f32_e32 v36, v36, v116
	v_mul_f32_e32 v37, v37, v117
	v_mul_f32_e32 v38, v38, v118
	v_mul_f32_e32 v39, v39, v119
	v_mul_f32_e32 v40, v40, v120
	v_mul_f32_e32 v41, v41, v121
	v_mul_f32_e32 v42, v42, v122
	v_mul_f32_e32 v43, v43, v123
	v_mul_f32_e32 v44, v44, v124
	v_mul_f32_e32 v45, v45, v125
	v_mul_f32_e32 v46, v46, v126
	v_mul_f32_e32 v47, v47, v127
	v_mul_f32_e32 v48, v48, v128
	v_mul_f32_e32 v49, v49, v129
	v_mul_f32_e32 v50, v50, v130
	v_mul_f32_e32 v51, v51, v131
	v_cvt_pk_bf16_f32 v84, v20, v21
	v_cvt_pk_bf16_f32 v85, v22, v23
	v_cvt_pk_bf16_f32 v86, v24, v25
	v_cvt_pk_bf16_f32 v87, v26, v27
	v_cvt_pk_bf16_f32 v88, v28, v29
	v_cvt_pk_bf16_f32 v89, v30, v31
	v_cvt_pk_bf16_f32 v90, v32, v33
	v_cvt_pk_bf16_f32 v91, v34, v35
	v_cvt_pk_bf16_f32 v92, v36, v37
	v_cvt_pk_bf16_f32 v93, v38, v39
	v_cvt_pk_bf16_f32 v94, v40, v41
	v_cvt_pk_bf16_f32 v95, v42, v43
	v_cvt_pk_bf16_f32 v96, v44, v45
	v_cvt_pk_bf16_f32 v97, v46, v47
	v_cvt_pk_bf16_f32 v98, v48, v49
	v_cvt_pk_bf16_f32 v99, v50, v51
	s_nop 0
	global_store_dwordx2 v3, v[84:85], s[10:11]
	global_store_dwordx2 v3, v[86:87], s[10:11] offset:512
	global_store_dwordx2 v3, v[88:89], s[10:11] offset:1024
	global_store_dwordx2 v3, v[90:91], s[10:11] offset:1536
	global_store_dwordx2 v3, v[92:93], s[10:11] offset:2048
	global_store_dwordx2 v3, v[94:95], s[10:11] offset:2560
	global_store_dwordx2 v3, v[96:97], s[10:11] offset:3072
	global_store_dwordx2 v3, v[98:99], s[10:11] offset:3584
	s_add_i32 s0, s2, s1
; __device__ __forceinline__ unsigned cvt_pk_bf16(float lo, float hi) { unsigned r; asm volatile("v_cvt_pk_bf16_f32 %0, %1, %2" : "=v"(r) : "v"(lo), "v"(hi)); return r; }
; __device__ __forceinline__ void rmsnorm_row_bf16(const float* __restrict__ src, const float* __restrict__ w, bf16_t* __restrict__ dst, int lane) {
;     f32x4 v[8]; float ss = 0.f;
; #pragma unroll
;     for (int i = 0; i < 8; ++i) { v[i] = __builtin_nontemporal_load((const f32x4*)(src + i * 256 + lane * 4)); ss += v[i][0] * v[i][0] + v[i][1] * v[i][1] + v[i][2] * v[i][2] + v[i][3] * v[i][3]; }
;     ss = wave_sum(ss);
;     const float rstd = rsqrtf(ss * (1.0f / D) + EPS);
; #pragma unroll
;     for (int i = 0; i < 8; ++i) {
;         const f32x4 g = *(const f32x4*)(w + i * 256 + lane * 4);
;         u32x2 o; o.x = cvt_pk_bf16(v[i][0] * rstd * g[0], v[i][1] * rstd * g[1]); o.y = cvt_pk_bf16(v[i][2] * rstd * g[2], v[i][3] * rstd * g[3]);
;         *(u32x2*)(dst + i * 256 + lane * 4) = o;
;     }
; }
.Lp0_loop:
	s_cmp_lt_i32 s0, 0x8000
	s_cbranch_scc0 .Lp0_tailB
	s_lshl_b32 s8, s0, 13
	s_add_u32 s14, s52, s8
	s_addc_u32 s15, s53, 0
	global_load_dwordx4 v[20:23], v2, s[14:15] nt
	global_load_dwordx4 v[24:27], v2, s[14:15] offset:1024 nt
	global_load_dwordx4 v[28:31], v2, s[14:15] offset:2048 nt
	global_load_dwordx4 v[32:35], v2, s[14:15] offset:3072 nt
	s_add_u32 s14, s14, 0x1000
	s_addc_u32 s15, s15, 0
	global_load_dwordx4 v[36:39], v2, s[14:15] nt
	global_load_dwordx4 v[40:43], v2, s[14:15] offset:1024 nt
	global_load_dwordx4 v[44:47], v2, s[14:15] offset:2048 nt
	global_load_dwordx4 v[48:51], v2, s[14:15] offset:3072 nt
	s_waitcnt vmcnt(16)
	s_lshl_b32 s8, s2, 12
	s_add_u32 s10, s86, s8
	s_addc_u32 s11, s87, 0
	v_mul_f32_e32 v132, v52, v52
	v_mul_f32_e32 v133, v53, v53
	v_mul_f32_e32 v134, v54, v54
	v_mul_f32_e32 v135, v55, v55
	v_fmac_f32_e32 v132, v56, v56
	v_fmac_f32_e32 v133, v57, v57
	v_fmac_f32_e32 v134, v58, v58
	v_fmac_f32_e32 v135, v59, v59
	v_fmac_f32_e32 v132, v60, v60
	v_fmac_f32_e32 v133, v61, v61
	v_fmac_f32_e32 v134, v62, v62
	v_fmac_f32_e32 v135, v63, v63
	v_fmac_f32_e32 v132, v64, v64
	v_fmac_f32_e32 v133, v65, v65
	v_fmac_f32_e32 v134, v66, v66
	v_fmac_f32_e32 v135, v67, v67
	v_fmac_f32_e32 v132, v68, v68
	v_fmac_f32_e32 v133, v69, v69
	v_fmac_f32_e32 v134, v70, v70
	v_fmac_f32_e32 v135, v71, v71
	v_fmac_f32_e32 v132, v72, v72
	v_fmac_f32_e32 v133, v73, v73
	v_fmac_f32_e32 v134, v74, v74
	v_fmac_f32_e32 v135, v75, v75
	v_fmac_f32_e32 v132, v76, v76
	v_fmac_f32_e32 v133, v77, v77
	v_fmac_f32_e32 v134, v78, v78
	v_fmac_f32_e32 v135, v79, v79
	v_fmac_f32_e32 v132, v80, v80
	v_fmac_f32_e32 v133, v81, v81
	v_fmac_f32_e32 v134, v82, v82
	v_fmac_f32_e32 v135, v83, v83
	v_add_f32_e32 v132, v132, v133
	v_add_f32_e32 v134, v134, v135
	v_add_f32_e32 v132, v132, v134
	s_nop 1
	v_add_f32_dpp v132, v132, v132 quad_perm:[1,0,3,2] row_mask:0xf bank_mask:0xf
	s_nop 1
	v_add_f32_dpp v132, v132, v132 quad_perm:[2,3,0,1] row_mask:0xf bank_mask:0xf
	s_nop 1
	v_add_f32_dpp v132, v132, v132 row_ror:4 row_mask:0xf bank_mask:0xf
	s_nop 1
	v_add_f32_dpp v132, v132, v132 row_ror:8 row_mask:0xf bank_mask:0xf
	s_nop 1
	v_add_f32_dpp v132, v132, v132 row_bcast:15 row_mask:0xa bank_mask:0xf
	s_nop 1
	v_add_f32_dpp v132, v132, v132 row_bcast:31 row_mask:0xc bank_mask:0xf
	s_nop 1
	v_readlane_b32 s8, v132, 63
	s_nop 3
	v_mov_b32_e32 v136, s8
	v_fmamk_f32 v136, v136, 0x3a000000, v4
	v_rsq_f32_e32 v136, v136
	s_nop 1
	v_mul_f32_e32 v52, v52, v136
	v_mul_f32_e32 v53, v53, v136
	v_mul_f32_e32 v54, v54, v136
	v_mul_f32_e32 v55, v55, v136
	v_mul_f32_e32 v56, v56, v136
	v_mul_f32_e32 v57, v57, v136
	v_mul_f32_e32 v58, v58, v136
	v_mul_f32_e32 v59, v59, v136
	v_mul_f32_e32 v60, v60, v136
	v_mul_f32_e32 v61, v61, v136
	v_mul_f32_e32 v62, v62, v136
	v_mul_f32_e32 v63, v63, v136
	v_mul_f32_e32 v64, v64, v136
	v_mul_f32_e32 v65, v65, v136
	v_mul_f32_e32 v66, v66, v136
	v_mul_f32_e32 v67, v67, v136
	v_mul_f32_e32 v68, v68, v136
	v_mul_f32_e32 v69, v69, v136
	v_mul_f32_e32 v70, v70, v136
	v_mul_f32_e32 v71, v71, v136
	v_mul_f32_e32 v72, v72, v136
	v_mul_f32_e32 v73, v73, v136
	v_mul_f32_e32 v74, v74, v136
	v_mul_f32_e32 v75, v75, v136
	v_mul_f32_e32 v76, v76, v136
	v_mul_f32_e32 v77, v77, v136
	v_mul_f32_e32 v78, v78, v136
	v_mul_f32_e32 v79, v79, v136
	v_mul_f32_e32 v80, v80, v136
	v_mul_f32_e32 v81, v81, v136
	v_mul_f32_e32 v82, v82, v136
	v_mul_f32_e32 v83, v83, v136
	v_mul_f32_e32 v52, v52, v100
	v_mul_f32_e32 v53, v53, v101
	v_mul_f32_e32 v54, v54, v102
	v_mul_f32_e32 v55, v55, v103
	v_mul_f32_e32 v56, v56, v104
	v_mul_f32_e32 v57, v57, v105
	v_mul_f32_e32 v58, v58, v106
	v_mul_f32_e32 v59, v59, v107
	v_mul_f32_e32 v60, v60, v108
	v_mul_f32_e32 v61, v61, v109
	v_mul_f32_e32 v62, v62, v110
	v_mul_f32_e32 v63, v63, v111
	v_mul_f32_e32 v64, v64, v112
	v_mul_f32_e32 v65, v65, v113
	v_mul_f32_e32 v66, v66, v114
	v_mul_f32_e32 v67, v67, v115
	v_mul_f32_e32 v68, v68, v116
	v_mul_f32_e32 v69, v69, v117
	v_mul_f32_e32 v70, v70, v118
	v_mul_f32_e32 v71, v71, v119
	v_mul_f32_e32 v72, v72, v120
	v_mul_f32_e32 v73, v73, v121
	v_mul_f32_e32 v74, v74, v122
	v_mul_f32_e32 v75, v75, v123
	v_mul_f32_e32 v76, v76, v124
	v_mul_f32_e32 v77, v77, v125
	v_mul_f32_e32 v78, v78, v126
	v_mul_f32_e32 v79, v79, v127
	v_mul_f32_e32 v80, v80, v128
	v_mul_f32_e32 v81, v81, v129
	v_mul_f32_e32 v82, v82, v130
	v_mul_f32_e32 v83, v83, v131
	v_cvt_pk_bf16_f32 v84, v52, v53
	v_cvt_pk_bf16_f32 v85, v54, v55
	v_cvt_pk_bf16_f32 v86, v56, v57
	v_cvt_pk_bf16_f32 v87, v58, v59
	v_cvt_pk_bf16_f32 v88, v60, v61
	v_cvt_pk_bf16_f32 v89, v62, v63
	v_cvt_pk_bf16_f32 v90, v64, v65
	v_cvt_pk_bf16_f32 v91, v66, v67
	v_cvt_pk_bf16_f32 v92, v68, v69
	v_cvt_pk_bf16_f32 v93, v70, v71
	v_cvt_pk_bf16_f32 v94, v72, v73
	v_cvt_pk_bf16_f32 v95, v74, v75
	v_cvt_pk_bf16_f32 v96, v76, v77
	v_cvt_pk_bf16_f32 v97, v78, v79
	v_cvt_pk_bf16_f32 v98, v80, v81
	v_cvt_pk_bf16_f32 v99, v82, v83
	s_nop 0
	global_store_dwordx2 v3, v[84:85], s[10:11]
	global_store_dwordx2 v3, v[86:87], s[10:11] offset:512
	global_store_dwordx2 v3, v[88:89], s[10:11] offset:1024
	global_store_dwordx2 v3, v[90:91], s[10:11] offset:1536
	global_store_dwordx2 v3, v[92:93], s[10:11] offset:2048
	global_store_dwordx2 v3, v[94:95], s[10:11] offset:2560
	global_store_dwordx2 v3, v[96:97], s[10:11] offset:3072
	global_store_dwordx2 v3, v[98:99], s[10:11] offset:3584
	s_add_i32 s2, s0, s1
	s_cmp_lt_i32 s2, 0x8000
	s_cbranch_scc0 .Lp0_tailA
; __device__ __forceinline__ unsigned cvt_pk_bf16(float lo, float hi) { unsigned r; asm volatile("v_cvt_pk_bf16_f32 %0, %1, %2" : "=v"(r) : "v"(lo), "v"(hi)); return r; }
; __device__ __forceinline__ void rmsnorm_row_bf16(const float* __restrict__ src, const float* __restrict__ w, bf16_t* __restrict__ dst, int lane) {
;     f32x4 v[8]; float ss = 0.f;
; #pragma unroll
;     for (int i = 0; i < 8; ++i) { v[i] = __builtin_nontemporal_load((const f32x4*)(src + i * 256 + lane * 4)); ss += v[i][0] * v[i][0] + v[i][1] * v[i][1] + v[i][2] * v[i][2] + v[i][3] * v[i][3]; }
;     ss = wave_sum(ss);
;     const float rstd = rsqrtf(ss * (1.0f / D) + EPS);
; #pragma unroll
;     for (int i = 0; i < 8; ++i) {
;         const f32x4 g = *(const f32x4*)(w + i * 256 + lane * 4);
;         u32x2 o; o.x = cvt_pk_bf16(v[i][0] * rstd * g[0], v[i][1] * rstd * g[1]); o.y = cvt_pk_bf16(v[i][2] * rstd * g[2], v[i][3] * rstd * g[3]);
;         *(u32x2*)(dst + i * 256 + lane * 4) = o;
;     }
; }
	s_lshl_b32 s8, s2, 13
	s_add_u32 s14, s52, s8
	s_addc_u32 s15, s53, 0
	global_load_dwordx4 v[52:55], v2, s[14:15] nt
	global_load_dwordx4 v[56:59], v2, s[14:15] offset:1024 nt
	global_load_dwordx4 v[60:63], v2, s[14:15] offset:2048 nt
	global_load_dwordx4 v[64:67], v2, s[14:15] offset:3072 nt
	s_add_u32 s14, s14, 0x1000
	s_addc_u32 s15, s15, 0
	global_load_dwordx4 v[68:71], v2, s[14:15] nt
	global_load_dwordx4 v[72:75], v2, s[14:15] offset:1024 nt
	global_load_dwordx4 v[76:79], v2, s[14:15] offset:2048 nt
	global_load_dwordx4 v[80:83], v2, s[14:15] offset:3072 nt
	s_waitcnt vmcnt(16)
	s_lshl_b32 s8, s0, 12
	s_add_u32 s10, s86, s8
	s_addc_u32 s11, s87, 0
	v_mul_f32_e32 v132, v20, v20
	v_mul_f32_e32 v133, v21, v21
	v_mul_f32_e32 v134, v22, v22
	v_mul_f32_e32 v135, v23, v23
	v_fmac_f32_e32 v132, v24, v24
	v_fmac_f32_e32 v133, v25, v25
	v_fmac_f32_e32 v134, v26, v26
	v_fmac_f32_e32 v135, v27, v27
	v_fmac_f32_e32 v132, v28, v28
	v_fmac_f32_e32 v133, v29, v29
	v_fmac_f32_e32 v134, v30, v30
	v_fmac_f32_e32 v135, v31, v31
	v_fmac_f32_e32 v132, v32, v32
	v_fmac_f32_e32 v133, v33, v33
	v_fmac_f32_e32 v134, v34, v34
	v_fmac_f32_e32 v135, v35, v35
	v_fmac_f32_e32 v132, v36, v36
	v_fmac_f32_e32 v133, v37, v37
	v_fmac_f32_e32 v134, v38, v38
	v_fmac_f32_e32 v135, v39, v39
	v_fmac_f32_e32 v132, v40, v40
	v_fmac_f32_e32 v133, v41, v41
	v_fmac_f32_e32 v134, v42, v42
	v_fmac_f32_e32 v135, v43, v43
	v_fmac_f32_e32 v132, v44, v44
	v_fmac_f32_e32 v133, v45, v45
	v_fmac_f32_e32 v134, v46, v46
	v_fmac_f32_e32 v135, v47, v47
	v_fmac_f32_e32 v132, v48, v48
	v_fmac_f32_e32 v133, v49, v49
	v_fmac_f32_e32 v134, v50, v50
	v_fmac_f32_e32 v135, v51, v51
	v_add_f32_e32 v132, v132, v133
	v_add_f32_e32 v134, v134, v135
	v_add_f32_e32 v132, v132, v134
	s_nop 1
	v_add_f32_dpp v132, v132, v132 quad_perm:[1,0,3,2] row_mask:0xf bank_mask:0xf
	s_nop 1
	v_add_f32_dpp v132, v132, v132 quad_perm:[2,3,0,1] row_mask:0xf bank_mask:0xf
	s_nop 1
	v_add_f32_dpp v132, v132, v132 row_ror:4 row_mask:0xf bank_mask:0xf
	s_nop 1
	v_add_f32_dpp v132, v132, v132 row_ror:8 row_mask:0xf bank_mask:0xf
	s_nop 1
	v_add_f32_dpp v132, v132, v132 row_bcast:15 row_mask:0xa bank_mask:0xf
	s_nop 1
	v_add_f32_dpp v132, v132, v132 row_bcast:31 row_mask:0xc bank_mask:0xf
	s_nop 1
	v_readlane_b32 s8, v132, 63
	s_nop 3
	v_mov_b32_e32 v136, s8
	v_fmamk_f32 v136, v136, 0x3a000000, v4
	v_rsq_f32_e32 v136, v136
	s_nop 1
	v_mul_f32_e32 v20, v20, v136
	v_mul_f32_e32 v21, v21, v136
	v_mul_f32_e32 v22, v22, v136
	v_mul_f32_e32 v23, v23, v136
	v_mul_f32_e32 v24, v24, v136
	v_mul_f32_e32 v25, v25, v136
	v_mul_f32_e32 v26, v26, v136
	v_mul_f32_e32 v27, v27, v136
	v_mul_f32_e32 v28, v28, v136
	v_mul_f32_e32 v29, v29, v136
	v_mul_f32_e32 v30, v30, v136
	v_mul_f32_e32 v31, v31, v136
	v_mul_f32_e32 v32, v32, v136
	v_mul_f32_e32 v33, v33, v136
	v_mul_f32_e32 v34, v34, v136
	v_mul_f32_e32 v35, v35, v136
	v_mul_f32_e32 v36, v36, v136
	v_mul_f32_e32 v37, v37, v136
	v_mul_f32_e32 v38, v38, v136
	v_mul_f32_e32 v39, v39, v136
	v_mul_f32_e32 v40, v40, v136
	v_mul_f32_e32 v41, v41, v136
	v_mul_f32_e32 v42, v42, v136
	v_mul_f32_e32 v43, v43, v136
	v_mul_f32_e32 v44, v44, v136
	v_mul_f32_e32 v45, v45, v136
	v_mul_f32_e32 v46, v46, v136
	v_mul_f32_e32 v47, v47, v136
	v_mul_f32_e32 v48, v48, v136
	v_mul_f32_e32 v49, v49, v136
	v_mul_f32_e32 v50, v50, v136
	v_mul_f32_e32 v51, v51, v136
	v_mul_f32_e32 v20, v20, v100
	v_mul_f32_e32 v21, v21, v101
	v_mul_f32_e32 v22, v22, v102
	v_mul_f32_e32 v23, v23, v103
	v_mul_f32_e32 v24, v24, v104
	v_mul_f32_e32 v25, v25, v105
	v_mul_f32_e32 v26, v26, v106
	v_mul_f32_e32 v27, v27, v107
	v_mul_f32_e32 v28, v28, v108
	v_mul_f32_e32 v29, v29, v109
	v_mul_f32_e32 v30, v30, v110
	v_mul_f32_e32 v31, v31, v111
	v_mul_f32_e32 v32, v32, v112
	v_mul_f32_e32 v33, v33, v113
	v_mul_f32_e32 v34, v34, v114
	v_mul_f32_e32 v35, v35, v115
	v_mul_f32_e32 v36, v36, v116
	v_mul_f32_e32 v37, v37, v117
	v_mul_f32_e32 v38, v38, v118
	v_mul_f32_e32 v39, v39, v119
	v_mul_f32_e32 v40, v40, v120
	v_mul_f32_e32 v41, v41, v121
	v_mul_f32_e32 v42, v42, v122
	v_mul_f32_e32 v43, v43, v123
	v_mul_f32_e32 v44, v44, v124
	v_mul_f32_e32 v45, v45, v125
	v_mul_f32_e32 v46, v46, v126
	v_mul_f32_e32 v47, v47, v127
	v_mul_f32_e32 v48, v48, v128
	v_mul_f32_e32 v49, v49, v129
	v_mul_f32_e32 v50, v50, v130
	v_mul_f32_e32 v51, v51, v131
	v_cvt_pk_bf16_f32 v84, v20, v21
	v_cvt_pk_bf16_f32 v85, v22, v23
	v_cvt_pk_bf16_f32 v86, v24, v25
	v_cvt_pk_bf16_f32 v87, v26, v27
	v_cvt_pk_bf16_f32 v88, v28, v29
	v_cvt_pk_bf16_f32 v89, v30, v31
	v_cvt_pk_bf16_f32 v90, v32, v33
	v_cvt_pk_bf16_f32 v91, v34, v35
	v_cvt_pk_bf16_f32 v92, v36, v37
	v_cvt_pk_bf16_f32 v93, v38, v39
	v_cvt_pk_bf16_f32 v94, v40, v41
	v_cvt_pk_bf16_f32 v95, v42, v43
	v_cvt_pk_bf16_f32 v96, v44, v45
	v_cvt_pk_bf16_f32 v97, v46, v47
	v_cvt_pk_bf16_f32 v98, v48, v49
	v_cvt_pk_bf16_f32 v99, v50, v51
	s_nop 0
	global_store_dwordx2 v3, v[84:85], s[10:11]
	global_store_dwordx2 v3, v[86:87], s[10:11] offset:512
	global_store_dwordx2 v3, v[88:89], s[10:11] offset:1024
	global_store_dwordx2 v3, v[90:91], s[10:11] offset:1536
	global_store_dwordx2 v3, v[92:93], s[10:11] offset:2048
	global_store_dwordx2 v3, v[94:95], s[10:11] offset:2560
	global_store_dwordx2 v3, v[96:97], s[10:11] offset:3072
	global_store_dwordx2 v3, v[98:99], s[10:11] offset:3584
	s_add_i32 s0, s2, s1
	s_branch .Lp0_loop
; __device__ __forceinline__ unsigned cvt_pk_bf16(float lo, float hi) { unsigned r; asm volatile("v_cvt_pk_bf16_f32 %0, %1, %2" : "=v"(r) : "v"(lo), "v"(hi)); return r; }
; __device__ __forceinline__ void rmsnorm_row_bf16(const float* __restrict__ src, const float* __restrict__ w, bf16_t* __restrict__ dst, int lane) {
;     f32x4 v[8]; float ss = 0.f;
; #pragma unroll
;     for (int i = 0; i < 8; ++i) { v[i] = __builtin_nontemporal_load((const f32x4*)(src + i * 256 + lane * 4)); ss += v[i][0] * v[i][0] + v[i][1] * v[i][1] + v[i][2] * v[i][2] + v[i][3] * v[i][3]; }
;     ss = wave_sum(ss);
;     const float rstd = rsqrtf(ss * (1.0f / D) + EPS);
; #pragma unroll
;     for (int i = 0; i < 8; ++i) {
;         const f32x4 g = *(const f32x4*)(w + i * 256 + lane * 4);
;         u32x2 o; o.x = cvt_pk_bf16(v[i][0] * rstd * g[0], v[i][1] * rstd * g[1]); o.y = cvt_pk_bf16(v[i][2] * rstd * g[2], v[i][3] * rstd * g[3]);
;         *(u32x2*)(dst + i * 256 + lane * 4) = o;
;     }
; }
.Lp0_tailB:
	s_waitcnt vmcnt(0)
	s_lshl_b32 s8, s2, 12
	s_add_u32 s10, s86, s8
	s_addc_u32 s11, s87, 0
	v_mul_f32_e32 v132, v52, v52
	v_mul_f32_e32 v133, v53, v53
	v_mul_f32_e32 v134, v54, v54
	v_mul_f32_e32 v135, v55, v55
	v_fmac_f32_e32 v132, v56, v56
	v_fmac_f32_e32 v133, v57, v57
	v_fmac_f32_e32 v134, v58, v58
	v_fmac_f32_e32 v135, v59, v59
	v_fmac_f32_e32 v132, v60, v60
	v_fmac_f32_e32 v133, v61, v61
	v_fmac_f32_e32 v134, v62, v62
	v_fmac_f32_e32 v135, v63, v63
	v_fmac_f32_e32 v132, v64, v64
	v_fmac_f32_e32 v133, v65, v65
	v_fmac_f32_e32 v134, v66, v66
	v_fmac_f32_e32 v135, v67, v67
	v_fmac_f32_e32 v132, v68, v68
	v_fmac_f32_e32 v133, v69, v69
	v_fmac_f32_e32 v134, v70, v70
	v_fmac_f32_e32 v135, v71, v71
	v_fmac_f32_e32 v132, v72, v72
	v_fmac_f32_e32 v133, v73, v73
	v_fmac_f32_e32 v134, v74, v74
	v_fmac_f32_e32 v135, v75, v75
	v_fmac_f32_e32 v132, v76, v76
	v_fmac_f32_e32 v133, v77, v77
	v_fmac_f32_e32 v134, v78, v78
	v_fmac_f32_e32 v135, v79, v79
	v_fmac_f32_e32 v132, v80, v80
	v_fmac_f32_e32 v133, v81, v81
	v_fmac_f32_e32 v134, v82, v82
	v_fmac_f32_e32 v135, v83, v83
	v_add_f32_e32 v132, v132, v133
	v_add_f32_e32 v134, v134, v135
	v_add_f32_e32 v132, v132, v134
	s_nop 1
	v_add_f32_dpp v132, v132, v132 quad_perm:[1,0,3,2] row_mask:0xf bank_mask:0xf
	s_nop 1
	v_add_f32_dpp v132, v132, v132 quad_perm:[2,3,0,1] row_mask:0xf bank_mask:0xf
	s_nop 1
	v_add_f32_dpp v132, v132, v132 row_ror:4 row_mask:0xf bank_mask:0xf
	s_nop 1
	v_add_f32_dpp v132, v132, v132 row_ror:8 row_mask:0xf bank_mask:0xf
	s_nop 1
	v_add_f32_dpp v132, v132, v132 row_bcast:15 row_mask:0xa bank_mask:0xf
	s_nop 1
	v_add_f32_dpp v132, v132, v132 row_bcast:31 row_mask:0xc bank_mask:0xf
	s_nop 1
	v_readlane_b32 s8, v132, 63
	s_nop 3
	v_mov_b32_e32 v136, s8
	v_fmamk_f32 v136, v136, 0x3a000000, v4
	v_rsq_f32_e32 v136, v136
	s_nop 1
	v_mul_f32_e32 v52, v52, v136
	v_mul_f32_e32 v53, v53, v136
	v_mul_f32_e32 v54, v54, v136
	v_mul_f32_e32 v55, v55, v136
	v_mul_f32_e32 v56, v56, v136
	v_mul_f32_e32 v57, v57, v136
	v_mul_f32_e32 v58, v58, v136
	v_mul_f32_e32 v59, v59, v136
	v_mul_f32_e32 v60, v60, v136
	v_mul_f32_e32 v61, v61, v136
	v_mul_f32_e32 v62, v62, v136
	v_mul_f32_e32 v63, v63, v136
	v_mul_f32_e32 v64, v64, v136
	v_mul_f32_e32 v65, v65, v136
	v_mul_f32_e32 v66, v66, v136
	v_mul_f32_e32 v67, v67, v136
	v_mul_f32_e32 v68, v68, v136
	v_mul_f32_e32 v69, v69, v136
	v_mul_f32_e32 v70, v70, v136
	v_mul_f32_e32 v71, v71, v136
	v_mul_f32_e32 v72, v72, v136
	v_mul_f32_e32 v73, v73, v136
	v_mul_f32_e32 v74, v74, v136
	v_mul_f32_e32 v75, v75, v136
	v_mul_f32_e32 v76, v76, v136
	v_mul_f32_e32 v77, v77, v136
	v_mul_f32_e32 v78, v78, v136
	v_mul_f32_e32 v79, v79, v136
	v_mul_f32_e32 v80, v80, v136
	v_mul_f32_e32 v81, v81, v136
	v_mul_f32_e32 v82, v82, v136
	v_mul_f32_e32 v83, v83, v136
	v_mul_f32_e32 v52, v52, v100
	v_mul_f32_e32 v53, v53, v101
	v_mul_f32_e32 v54, v54, v102
	v_mul_f32_e32 v55, v55, v103
	v_mul_f32_e32 v56, v56, v104
	v_mul_f32_e32 v57, v57, v105
	v_mul_f32_e32 v58, v58, v106
	v_mul_f32_e32 v59, v59, v107
	v_mul_f32_e32 v60, v60, v108
	v_mul_f32_e32 v61, v61, v109
	v_mul_f32_e32 v62, v62, v110
	v_mul_f32_e32 v63, v63, v111
	v_mul_f32_e32 v64, v64, v112
	v_mul_f32_e32 v65, v65, v113
	v_mul_f32_e32 v66, v66, v114
	v_mul_f32_e32 v67, v67, v115
	v_mul_f32_e32 v68, v68, v116
	v_mul_f32_e32 v69, v69, v117
	v_mul_f32_e32 v70, v70, v118
	v_mul_f32_e32 v71, v71, v119
	v_mul_f32_e32 v72, v72, v120
	v_mul_f32_e32 v73, v73, v121
	v_mul_f32_e32 v74, v74, v122
	v_mul_f32_e32 v75, v75, v123
	v_mul_f32_e32 v76, v76, v124
	v_mul_f32_e32 v77, v77, v125
	v_mul_f32_e32 v78, v78, v126
	v_mul_f32_e32 v79, v79, v127
	v_mul_f32_e32 v80, v80, v128
	v_mul_f32_e32 v81, v81, v129
	v_mul_f32_e32 v82, v82, v130
	v_mul_f32_e32 v83, v83, v131
	v_cvt_pk_bf16_f32 v84, v52, v53
	v_cvt_pk_bf16_f32 v85, v54, v55
	v_cvt_pk_bf16_f32 v86, v56, v57
	v_cvt_pk_bf16_f32 v87, v58, v59
	v_cvt_pk_bf16_f32 v88, v60, v61
	v_cvt_pk_bf16_f32 v89, v62, v63
	v_cvt_pk_bf16_f32 v90, v64, v65
	v_cvt_pk_bf16_f32 v91, v66, v67
	v_cvt_pk_bf16_f32 v92, v68, v69
	v_cvt_pk_bf16_f32 v93, v70, v71
	v_cvt_pk_bf16_f32 v94, v72, v73
	v_cvt_pk_bf16_f32 v95, v74, v75
	v_cvt_pk_bf16_f32 v96, v76, v77
	v_cvt_pk_bf16_f32 v97, v78, v79
	v_cvt_pk_bf16_f32 v98, v80, v81
	v_cvt_pk_bf16_f32 v99, v82, v83
	s_nop 0
	global_store_dwordx2 v3, v[84:85], s[10:11]
	global_store_dwordx2 v3, v[86:87], s[10:11] offset:512
	global_store_dwordx2 v3, v[88:89], s[10:11] offset:1024
	global_store_dwordx2 v3, v[90:91], s[10:11] offset:1536
	global_store_dwordx2 v3, v[92:93], s[10:11] offset:2048
	global_store_dwordx2 v3, v[94:95], s[10:11] offset:2560
	global_store_dwordx2 v3, v[96:97], s[10:11] offset:3072
	global_store_dwordx2 v3, v[98:99], s[10:11] offset:3584
	s_branch .Lp0_mem
; __device__ __forceinline__ unsigned cvt_pk_bf16(float lo, float hi) { unsigned r; asm volatile("v_cvt_pk_bf16_f32 %0, %1, %2" : "=v"(r) : "v"(lo), "v"(hi)); return r; }
; __device__ __forceinline__ void rmsnorm_row_bf16(const float* __restrict__ src, const float* __restrict__ w, bf16_t* __restrict__ dst, int lane) {
;     f32x4 v[8]; float ss = 0.f;
; #pragma unroll
;     for (int i = 0; i < 8; ++i) { v[i] = __builtin_nontemporal_load((const f32x4*)(src + i * 256 + lane * 4)); ss += v[i][0] * v[i][0] + v[i][1] * v[i][1] + v[i][2] * v[i][2] + v[i][3] * v[i][3]; }
;     ss = wave_sum(ss);
;     const float rstd = rsqrtf(ss * (1.0f / D) + EPS);
; #pragma unroll
;     for (int i = 0; i < 8; ++i) {
;         const f32x4 g = *(const f32x4*)(w + i * 256 + lane * 4);
;         u32x2 o; o.x = cvt_pk_bf16(v[i][0] * rstd * g[0], v[i][1] * rstd * g[1]); o.y = cvt_pk_bf16(v[i][2] * rstd * g[2], v[i][3] * rstd * g[3]);
;         *(u32x2*)(dst + i * 256 + lane * 4) = o;
;     }
; }
; __device__ void phase_prep(const Params& p, LAS unsigned char* lds) {
;     ...
;     for (int r = blockIdx.x * 8 + w; r < T + 1024; r += gridDim.x * 8) {
;         if (r < T) rmsnorm_row_bf16(p.x + (size_t)r * D, p.norm1_w, (bf16_t*)(ws + WS_H) + (size_t)r * D, lane);
;         else rmsnorm_row_bf16(p.mem + (size_t)(r - T) * D, p.mem_norm_w, (bf16_t*)(ws + WS_MEMN) + (size_t)(r - T) * D, lane);
.Lp0_tailA:
	s_waitcnt vmcnt(0)
	s_lshl_b32 s8, s0, 12
	s_add_u32 s10, s86, s8
	s_addc_u32 s11, s87, 0
	v_mul_f32_e32 v132, v20, v20
	v_mul_f32_e32 v133, v21, v21
	v_mul_f32_e32 v134, v22, v22
	v_mul_f32_e32 v135, v23, v23
	v_fmac_f32_e32 v132, v24, v24
	v_fmac_f32_e32 v133, v25, v25
	v_fmac_f32_e32 v134, v26, v26
	v_fmac_f32_e32 v135, v27, v27
	v_fmac_f32_e32 v132, v28, v28
	v_fmac_f32_e32 v133, v29, v29
	v_fmac_f32_e32 v134, v30, v30
	v_fmac_f32_e32 v135, v31, v31
	v_fmac_f32_e32 v132, v32, v32
	v_fmac_f32_e32 v133, v33, v33
	v_fmac_f32_e32 v134, v34, v34
	v_fmac_f32_e32 v135, v35, v35
	v_fmac_f32_e32 v132, v36, v36
	v_fmac_f32_e32 v133, v37, v37
	v_fmac_f32_e32 v134, v38, v38
	v_fmac_f32_e32 v135, v39, v39
	v_fmac_f32_e32 v132, v40, v40
	v_fmac_f32_e32 v133, v41, v41
	v_fmac_f32_e32 v134, v42, v42
	v_fmac_f32_e32 v135, v43, v43
	v_fmac_f32_e32 v132, v44, v44
	v_fmac_f32_e32 v133, v45, v45
	v_fmac_f32_e32 v134, v46, v46
	v_fmac_f32_e32 v135, v47, v47
	v_fmac_f32_e32 v132, v48, v48
	v_fmac_f32_e32 v133, v49, v49
	v_fmac_f32_e32 v134, v50, v50
	v_fmac_f32_e32 v135, v51, v51
	v_add_f32_e32 v132, v132, v133
	v_add_f32_e32 v134, v134, v135
	v_add_f32_e32 v132, v132, v134
	s_nop 1
	v_add_f32_dpp v132, v132, v132 quad_perm:[1,0,3,2] row_mask:0xf bank_mask:0xf
	s_nop 1
	v_add_f32_dpp v132, v132, v132 quad_perm:[2,3,0,1] row_mask:0xf bank_mask:0xf
	s_nop 1
	v_add_f32_dpp v132, v132, v132 row_ror:4 row_mask:0xf bank_mask:0xf
	s_nop 1
	v_add_f32_dpp v132, v132, v132 row_ror:8 row_mask:0xf bank_mask:0xf
	s_nop 1
	v_add_f32_dpp v132, v132, v132 row_bcast:15 row_mask:0xa bank_mask:0xf
	s_nop 1
	v_add_f32_dpp v132, v132, v132 row_bcast:31 row_mask:0xc bank_mask:0xf
	s_nop 1
	v_readlane_b32 s8, v132, 63
	s_nop 3
	v_mov_b32_e32 v136, s8
	v_fmamk_f32 v136, v136, 0x3a000000, v4
	v_rsq_f32_e32 v136, v136
	s_nop 1
	v_mul_f32_e32 v20, v20, v136
	v_mul_f32_e32 v21, v21, v136
	v_mul_f32_e32 v22, v22, v136
	v_mul_f32_e32 v23, v23, v136
	v_mul_f32_e32 v24, v24, v136
	v_mul_f32_e32 v25, v25, v136
	v_mul_f32_e32 v26, v26, v136
	v_mul_f32_e32 v27, v27, v136
	v_mul_f32_e32 v28, v28, v136
	v_mul_f32_e32 v29, v29, v136
	v_mul_f32_e32 v30, v30, v136
	v_mul_f32_e32 v31, v31, v136
	v_mul_f32_e32 v32, v32, v136
	v_mul_f32_e32 v33, v33, v136
	v_mul_f32_e32 v34, v34, v136
	v_mul_f32_e32 v35, v35, v136
	v_mul_f32_e32 v36, v36, v136
	v_mul_f32_e32 v37, v37, v136
	v_mul_f32_e32 v38, v38, v136
	v_mul_f32_e32 v39, v39, v136
	v_mul_f32_e32 v40, v40, v136
	v_mul_f32_e32 v41, v41, v136
	v_mul_f32_e32 v42, v42, v136
	v_mul_f32_e32 v43, v43, v136
	v_mul_f32_e32 v44, v44, v136
	v_mul_f32_e32 v45, v45, v136
	v_mul_f32_e32 v46, v46, v136
	v_mul_f32_e32 v47, v47, v136
	v_mul_f32_e32 v48, v48, v136
	v_mul_f32_e32 v49, v49, v136
	v_mul_f32_e32 v50, v50, v136
	v_mul_f32_e32 v51, v51, v136
	v_mul_f32_e32 v20, v20, v100
	v_mul_f32_e32 v21, v21, v101
	v_mul_f32_e32 v22, v22, v102
	v_mul_f32_e32 v23, v23, v103
	v_mul_f32_e32 v24, v24, v104
	v_mul_f32_e32 v25, v25, v105
	v_mul_f32_e32 v26, v26, v106
	v_mul_f32_e32 v27, v27, v107
	v_mul_f32_e32 v28, v28, v108
	v_mul_f32_e32 v29, v29, v109
	v_mul_f32_e32 v30, v30, v110
	v_mul_f32_e32 v31, v31, v111
	v_mul_f32_e32 v32, v32, v112
	v_mul_f32_e32 v33, v33, v113
	v_mul_f32_e32 v34, v34, v114
	v_mul_f32_e32 v35, v35, v115
	v_mul_f32_e32 v36, v36, v116
	v_mul_f32_e32 v37, v37, v117
	v_mul_f32_e32 v38, v38, v118
	v_mul_f32_e32 v39, v39, v119
	v_mul_f32_e32 v40, v40, v120
	v_mul_f32_e32 v41, v41, v121
	v_mul_f32_e32 v42, v42, v122
	v_mul_f32_e32 v43, v43, v123
	v_mul_f32_e32 v44, v44, v124
	v_mul_f32_e32 v45, v45, v125
	v_mul_f32_e32 v46, v46, v126
	v_mul_f32_e32 v47, v47, v127
	v_mul_f32_e32 v48, v48, v128
	v_mul_f32_e32 v49, v49, v129
	v_mul_f32_e32 v50, v50, v130
	v_mul_f32_e32 v51, v51, v131
	v_cvt_pk_bf16_f32 v84, v20, v21
	v_cvt_pk_bf16_f32 v85, v22, v23
	v_cvt_pk_bf16_f32 v86, v24, v25
	v_cvt_pk_bf16_f32 v87, v26, v27
	v_cvt_pk_bf16_f32 v88, v28, v29
	v_cvt_pk_bf16_f32 v89, v30, v31
	v_cvt_pk_bf16_f32 v90, v32, v33
	v_cvt_pk_bf16_f32 v91, v34, v35
	v_cvt_pk_bf16_f32 v92, v36, v37
	v_cvt_pk_bf16_f32 v93, v38, v39
	v_cvt_pk_bf16_f32 v94, v40, v41
	v_cvt_pk_bf16_f32 v95, v42, v43
	v_cvt_pk_bf16_f32 v96, v44, v45
	v_cvt_pk_bf16_f32 v97, v46, v47
	v_cvt_pk_bf16_f32 v98, v48, v49
	v_cvt_pk_bf16_f32 v99, v50, v51
	s_nop 0
	global_store_dwordx2 v3, v[84:85], s[10:11]
	global_store_dwordx2 v3, v[86:87], s[10:11] offset:512
	global_store_dwordx2 v3, v[88:89], s[10:11] offset:1024
	global_store_dwordx2 v3, v[90:91], s[10:11] offset:1536
	global_store_dwordx2 v3, v[92:93], s[10:11] offset:2048
	global_store_dwordx2 v3, v[94:95], s[10:11] offset:2560
	global_store_dwordx2 v3, v[96:97], s[10:11] offset:3072
	global_store_dwordx2 v3, v[98:99], s[10:11] offset:3584
	s_mov_b32 s0, s2
.Lp0_mem:
	s_cmp_lt_i32 s0, 0x8400
	s_cbranch_scc0 .LBB0_58
	global_load_dwordx4 v[100:103], v2, s[38:39]
	global_load_dwordx4 v[104:107], v2, s[38:39] offset:1024
	global_load_dwordx4 v[108:111], v2, s[38:39] offset:2048
	global_load_dwordx4 v[112:115], v2, s[38:39] offset:3072
	s_add_u32 s14, s38, 0x1000
	s_addc_u32 s15, s39, 0
	global_load_dwordx4 v[116:119], v2, s[14:15]
	global_load_dwordx4 v[120:123], v2, s[14:15] offset:1024
	global_load_dwordx4 v[124:127], v2, s[14:15] offset:2048
	global_load_dwordx4 v[128:131], v2, s[14:15] offset:3072
; __device__ __forceinline__ unsigned cvt_pk_bf16(float lo, float hi) { unsigned r; asm volatile("v_cvt_pk_bf16_f32 %0, %1, %2" : "=v"(r) : "v"(lo), "v"(hi)); return r; }
; __device__ __forceinline__ void rmsnorm_row_bf16(const float* __restrict__ src, const float* __restrict__ w, bf16_t* __restrict__ dst, int lane) {
;     f32x4 v[8]; float ss = 0.f;
; #pragma unroll
;     for (int i = 0; i < 8; ++i) { v[i] = __builtin_nontemporal_load((const f32x4*)(src + i * 256 + lane * 4)); ss += v[i][0] * v[i][0] + v[i][1] * v[i][1] + v[i][2] * v[i][2] + v[i][3] * v[i][3]; }
;     ss = wave_sum(ss);
;     const float rstd = rsqrtf(ss * (1.0f / D) + EPS);
; #pragma unroll
;     for (int i = 0; i < 8; ++i) {
;         const f32x4 g = *(const f32x4*)(w + i * 256 + lane * 4);
;         u32x2 o; o.x = cvt_pk_bf16(v[i][0] * rstd * g[0], v[i][1] * rstd * g[1]); o.y = cvt_pk_bf16(v[i][2] * rstd * g[2], v[i][3] * rstd * g[3]);
;         *(u32x2*)(dst + i * 256 + lane * 4) = o;
;     }
; }
; __device__ void phase_prep(const Params& p, LAS unsigned char* lds) {
;     ...
;         else rmsnorm_row_bf16(p.mem + (size_t)(r - T) * D, p.mem_norm_w, (bf16_t*)(ws + WS_MEMN) + (size_t)(r - T) * D, lane);
.Lp0_memloop:
	s_sub_i32 s8, s0, 0x8000
	s_lshl_b32 s8, s8, 13
	s_add_u32 s14, s54, s8
	s_addc_u32 s15, s55, 0
	global_load_dwordx4 v[20:23], v2, s[14:15] nt
	global_load_dwordx4 v[24:27], v2, s[14:15] offset:1024 nt
	global_load_dwordx4 v[28:31], v2, s[14:15] offset:2048 nt
	global_load_dwordx4 v[32:35], v2, s[14:15] offset:3072 nt
	s_add_u32 s14, s14, 0x1000
	s_addc_u32 s15, s15, 0
	global_load_dwordx4 v[36:39], v2, s[14:15] nt
	global_load_dwordx4 v[40:43], v2, s[14:15] offset:1024 nt
	global_load_dwordx4 v[44:47], v2, s[14:15] offset:2048 nt
	global_load_dwordx4 v[48:51], v2, s[14:15] offset:3072 nt
	s_waitcnt vmcnt(0)
	s_sub_i32 s8, s0, 0x8000
	s_lshl_b32 s8, s8, 12
	s_add_u32 s10, s12, s8
	s_addc_u32 s11, s13, 0
	v_mul_f32_e32 v132, v20, v20
	v_mul_f32_e32 v133, v21, v21
	v_mul_f32_e32 v134, v22, v22
	v_mul_f32_e32 v135, v23, v23
	v_fmac_f32_e32 v132, v24, v24
	v_fmac_f32_e32 v133, v25, v25
	v_fmac_f32_e32 v134, v26, v26
	v_fmac_f32_e32 v135, v27, v27
	v_fmac_f32_e32 v132, v28, v28
	v_fmac_f32_e32 v133, v29, v29
	v_fmac_f32_e32 v134, v30, v30
	v_fmac_f32_e32 v135, v31, v31
	v_fmac_f32_e32 v132, v32, v32
	v_fmac_f32_e32 v133, v33, v33
	v_fmac_f32_e32 v134, v34, v34
	v_fmac_f32_e32 v135, v35, v35
	v_fmac_f32_e32 v132, v36, v36
	v_fmac_f32_e32 v133, v37, v37
	v_fmac_f32_e32 v134, v38, v38
	v_fmac_f32_e32 v135, v39, v39
	v_fmac_f32_e32 v132, v40, v40
	v_fmac_f32_e32 v133, v41, v41
	v_fmac_f32_e32 v134, v42, v42
	v_fmac_f32_e32 v135, v43, v43
	v_fmac_f32_e32 v132, v44, v44
	v_fmac_f32_e32 v133, v45, v45
	v_fmac_f32_e32 v134, v46, v46
	v_fmac_f32_e32 v135, v47, v47
	v_fmac_f32_e32 v132, v48, v48
	v_fmac_f32_e32 v133, v49, v49
	v_fmac_f32_e32 v134, v50, v50
	v_fmac_f32_e32 v135, v51, v51
	v_add_f32_e32 v132, v132, v133
	v_add_f32_e32 v134, v134, v135
	v_add_f32_e32 v132, v132, v134
	s_nop 1
	v_add_f32_dpp v132, v132, v132 quad_perm:[1,0,3,2] row_mask:0xf bank_mask:0xf
	s_nop 1
	v_add_f32_dpp v132, v132, v132 quad_perm:[2,3,0,1] row_mask:0xf bank_mask:0xf
	s_nop 1
	v_add_f32_dpp v132, v132, v132 row_ror:4 row_mask:0xf bank_mask:0xf
	s_nop 1
	v_add_f32_dpp v132, v132, v132 row_ror:8 row_mask:0xf bank_mask:0xf
	s_nop 1
	v_add_f32_dpp v132, v132, v132 row_bcast:15 row_mask:0xa bank_mask:0xf
	s_nop 1
	v_add_f32_dpp v132, v132, v132 row_bcast:31 row_mask:0xc bank_mask:0xf
	s_nop 1
	v_readlane_b32 s8, v132, 63
	s_nop 3
	v_mov_b32_e32 v136, s8
	v_fmamk_f32 v136, v136, 0x3a000000, v4
	v_rsq_f32_e32 v136, v136
	s_nop 1
	v_mul_f32_e32 v20, v20, v136
	v_mul_f32_e32 v21, v21, v136
	v_mul_f32_e32 v22, v22, v136
	v_mul_f32_e32 v23, v23, v136
	v_mul_f32_e32 v24, v24, v136
	v_mul_f32_e32 v25, v25, v136
	v_mul_f32_e32 v26, v26, v136
	v_mul_f32_e32 v27, v27, v136
	v_mul_f32_e32 v28, v28, v136
	v_mul_f32_e32 v29, v29, v136
	v_mul_f32_e32 v30, v30, v136
	v_mul_f32_e32 v31, v31, v136
	v_mul_f32_e32 v32, v32, v136
	v_mul_f32_e32 v33, v33, v136
	v_mul_f32_e32 v34, v34, v136
	v_mul_f32_e32 v35, v35, v136
	v_mul_f32_e32 v36, v36, v136
	v_mul_f32_e32 v37, v37, v136
	v_mul_f32_e32 v38, v38, v136
	v_mul_f32_e32 v39, v39, v136
	v_mul_f32_e32 v40, v40, v136
	v_mul_f32_e32 v41, v41, v136
	v_mul_f32_e32 v42, v42, v136
	v_mul_f32_e32 v43, v43, v136
	v_mul_f32_e32 v44, v44, v136
	v_mul_f32_e32 v45, v45, v136
	v_mul_f32_e32 v46, v46, v136
	v_mul_f32_e32 v47, v47, v136
	v_mul_f32_e32 v48, v48, v136
	v_mul_f32_e32 v49, v49, v136
	v_mul_f32_e32 v50, v50, v136
	v_mul_f32_e32 v51, v51, v136
	v_mul_f32_e32 v20, v20, v100
	v_mul_f32_e32 v21, v21, v101
	v_mul_f32_e32 v22, v22, v102
	v_mul_f32_e32 v23, v23, v103
	v_mul_f32_e32 v24, v24, v104
	v_mul_f32_e32 v25, v25, v105
	v_mul_f32_e32 v26, v26, v106
	v_mul_f32_e32 v27, v27, v107
	v_mul_f32_e32 v28, v28, v108
	v_mul_f32_e32 v29, v29, v109
	v_mul_f32_e32 v30, v30, v110
	v_mul_f32_e32 v31, v31, v111
	v_mul_f32_e32 v32, v32, v112
	v_mul_f32_e32 v33, v33, v113
	v_mul_f32_e32 v34, v34, v114
	v_mul_f32_e32 v35, v35, v115
	v_mul_f32_e32 v36, v36, v116
	v_mul_f32_e32 v37, v37, v117
	v_mul_f32_e32 v38, v38, v118
	v_mul_f32_e32 v39, v39, v119
	v_mul_f32_e32 v40, v40, v120
	v_mul_f32_e32 v41, v41, v121
	v_mul_f32_e32 v42, v42, v122
	v_mul_f32_e32 v43, v43, v123
	v_mul_f32_e32 v44, v44, v124
	v_mul_f32_e32 v45, v45, v125
	v_mul_f32_e32 v46, v46, v126
	v_mul_f32_e32 v47, v47, v127
	v_mul_f32_e32 v48, v48, v128
	v_mul_f32_e32 v49, v49, v129
	v_mul_f32_e32 v50, v50, v130
	v_mul_f32_e32 v51, v51, v131
	v_cvt_pk_bf16_f32 v84, v20, v21
	v_cvt_pk_bf16_f32 v85, v22, v23
	v_cvt_pk_bf16_f32 v86, v24, v25
	v_cvt_pk_bf16_f32 v87, v26, v27
	v_cvt_pk_bf16_f32 v88, v28, v29
	v_cvt_pk_bf16_f32 v89, v30, v31
	v_cvt_pk_bf16_f32 v90, v32, v33
	v_cvt_pk_bf16_f32 v91, v34, v35
	v_cvt_pk_bf16_f32 v92, v36, v37
	v_cvt_pk_bf16_f32 v93, v38, v39
	v_cvt_pk_bf16_f32 v94, v40, v41
	v_cvt_pk_bf16_f32 v95, v42, v43
	v_cvt_pk_bf16_f32 v96, v44, v45
	v_cvt_pk_bf16_f32 v97, v46, v47
	v_cvt_pk_bf16_f32 v98, v48, v49
	v_cvt_pk_bf16_f32 v99, v50, v51
	s_nop 0
	global_store_dwordx2 v3, v[84:85], s[10:11]
	global_store_dwordx2 v3, v[86:87], s[10:11] offset:512
	global_store_dwordx2 v3, v[88:89], s[10:11] offset:1024
	global_store_dwordx2 v3, v[90:91], s[10:11] offset:1536
	global_store_dwordx2 v3, v[92:93], s[10:11] offset:2048
	global_store_dwordx2 v3, v[94:95], s[10:11] offset:2560
	global_store_dwordx2 v3, v[96:97], s[10:11] offset:3072
	global_store_dwordx2 v3, v[98:99], s[10:11] offset:3584
	s_add_i32 s0, s0, s1
	s_cmp_lt_i32 s0, 0x8400
	s_cbranch_scc1 .Lp0_memloop

; __device__ void phase_hgrn_out(const Params& p, LAS unsigned char* lds) {
;     ...
;     if ((int)blockIdx.x < 4096) HG_LOAD_PRE(blockIdx.x);
;     for (int item = blockIdx.x; item < 4096; item += gridDim.x) {
;         const int bh = item >> 7, n = item & 127, b = bh >> 3, h = bh & 7;
;     ...
;             const f32x4 nw = *(const f32x4*)(p.hgrn_norm_w + v0);
.LBB0_449:
	s_cmp_lt_i32 s74, 5
	s_cselect_b64 s[0:1], -1, 0
	v_writelane_b32 v250, s0, 42
	s_nop 1
	v_writelane_b32 v250, s1, 43
	s_and_b64 s[0:1], s[0:1], s[20:21]
	s_xor_b64 s[0:1], s[0:1], -1
	s_cmpk_gt_i32 s78, 0xfff
	s_cselect_b64 s[2:3], -1, 0
	s_or_b64 s[0:1], s[2:3], s[0:1]
	s_and_b64 vcc, exec, s[0:1]
	s_cbranch_vccnz .LBB0_465
	s_add_u32 s4, s72, 0x24400000
	s_addc_u32 s5, s73, 0
	s_ashr_i32 s0, s78, 10
	s_ashr_i32 s1, s0, 31
	s_lshl_b32 s3, s78, 6
	s_lshl_b64 s[0:1], s[0:1], 13
	s_and_b32 s3, s3, 0x1fc0
	s_waitcnt vmcnt(0)
	v_mov_b32_e32 v19, 0
	s_and_b32 s2, s78, 0x380
	s_or_b32 s0, s0, s3
	v_lshlrev_b32_e32 v16, 3, v176
	v_mov_b32_e32 v17, v19
	v_lshl_add_u64 v[2:3], s[0:1], 0, v[16:17]
	s_lshl_b32 s0, s2, 2
	v_and_b32_e32 v1, 63, v206
	s_add_u32 s0, s4, s0
	s_addc_u32 s1, s5, 0
	v_lshlrev_b32_e32 v18, 3, v1
	s_movk_i32 s50, 0x3000
	v_mov_b64_e32 v[10:11], s[44:45]
	v_lshl_add_u64 v[4:5], s[0:1], 0, v[18:19]
	v_mad_u64_u32 v[10:11], s[0:1], v2, s50, v[10:11]
	s_waitcnt lgkmcnt(0)
	s_mov_b32 s55, 0
	v_lshlrev_b64 v[6:7], 12, v[2:3]
	v_mad_i32_i24 v11, v3, s50, v11
	s_lshl_b32 s54, s2, 1
	v_lshl_add_u64 v[10:11], v[10:11], 0, s[54:55]
	v_lshlrev_b32_e32 v2, 2, v1
	v_mov_b32_e32 v3, v19
	v_or_b32_e32 v12, 0x1000, v6
	v_mov_b32_e32 v13, v7
	v_lshl_add_u64 v[8:9], v[4:5], 0, v[6:7]
	v_lshl_add_u64 v[10:11], v[10:11], 0, v[2:3]
	v_lshl_add_u64 v[12:13], v[4:5], 0, v[12:13]
	v_bfe_u32 v224, v206, 6, 1
	v_lshrrev_b32_e32 v225, 2, v206
	v_and_b32_e32 v225, 12, v225
	v_lshl_or_b32 v224, v224, 6, v225
	v_lshlrev_b32_e32 v224, 2, v224
	global_load_dwordx4 v[208:211], v224, s[62:63]
	global_load_dwordx4 v[212:215], v224, s[62:63] offset:64
	global_load_dwordx4 v[216:219], v224, s[62:63] offset:128
	global_load_dwordx4 v[220:223], v224, s[62:63] offset:192
	global_load_dwordx2 v[20:21], v[8:9], off nt
	global_load_dword v17, v[10:11], off nt
	global_load_dword v67, v[10:11], off offset:2048 nt
	global_load_dwordx2 v[22:23], v[12:13], off nt
	s_mov_b64 s[0:1], 0x3000
	v_add_co_u32_e32 v12, vcc, s50, v10
	v_lshl_add_u64 v[8:9], v[10:11], 0, s[0:1]
	s_nop 0
	v_addc_co_u32_e32 v13, vcc, 0, v11, vcc
	s_mov_b64 s[0:1], 0x6000
	s_movk_i32 s51, 0x6000
	v_or_b32_e32 v14, 0x2000, v6
	v_mov_b32_e32 v15, v7
	v_lshl_add_u64 v[26:27], v[10:11], 0, s[0:1]
	v_add_co_u32_e32 v28, vcc, s51, v10
	s_mov_b64 s[0:1], 0x9000
	v_lshl_add_u64 v[14:15], v[4:5], 0, v[14:15]
	v_addc_co_u32_e32 v29, vcc, 0, v11, vcc
	global_load_dword v134, v[12:13], off nt
	global_load_dwordx2 v[24:25], v[14:15], off nt
	global_load_dword v135, v[28:29], off nt
	global_load_dword v136, v[26:27], off offset:2048 nt
	global_load_dword v137, v[8:9], off offset:2048 nt
	v_lshl_add_u64 v[12:13], v[10:11], 0, s[0:1]
	s_mov_b32 s0, 0x9000
	v_or_b32_e32 v8, 0x3000, v6
	v_mov_b32_e32 v9, v7
	v_add_co_u32_e32 v14, vcc, s0, v10
	v_or_b32_e32 v26, 0x4000, v6
	v_mov_b32_e32 v27, v7
	v_lshl_add_u64 v[8:9], v[4:5], 0, v[8:9]
	v_addc_co_u32_e32 v15, vcc, 0, v11, vcc
	v_lshl_add_u64 v[28:29], v[4:5], 0, v[26:27]
	s_mov_b32 s93, 0xc000
	global_load_dwordx2 v[26:27], v[8:9], off nt
	global_load_dword v138, v[14:15], off nt
	s_nop 0
	global_load_dwordx2 v[28:29], v[28:29], off nt
	s_nop 0
	global_load_dword v140, v[12:13], off offset:2048 nt
	s_mov_b64 s[0:1], 0xc000
	v_add_co_u32_e32 v12, vcc, s93, v10
	v_lshl_add_u64 v[8:9], v[10:11], 0, s[0:1]
	s_nop 0
	v_addc_co_u32_e32 v13, vcc, 0, v11, vcc
	v_or_b32_e32 v14, 0x5000, v6
	v_mov_b32_e32 v15, v7
	s_mov_b64 s[0:1], 0xf000
	v_lshl_add_u64 v[14:15], v[4:5], 0, v[14:15]
	global_load_dword v141, v[12:13], off nt
	global_load_dwordx2 v[30:31], v[14:15], off nt
	global_load_dword v142, v[8:9], off offset:2048 nt
	v_lshl_add_u64 v[8:9], v[10:11], 0, s[0:1]
	s_mov_b32 s0, 0xf000
	v_add_co_u32_e32 v12, vcc, s0, v10
	global_load_dword v143, v[8:9], off offset:2048 nt
	s_nop 0
	v_addc_co_u32_e32 v13, vcc, 0, v11, vcc
	v_or_b32_e32 v8, 0x6000, v6
	v_mov_b32_e32 v9, v7
	s_mov_b32 s52, 0x12000
	v_lshl_add_u64 v[8:9], v[4:5], 0, v[8:9]
	global_load_dword v144, v[12:13], off nt
	global_load_dwordx2 v[32:33], v[8:9], off nt
	v_add_co_u32_e32 v12, vcc, s52, v10
	v_or_b32_e32 v6, 0x7000, v6
	s_nop 0
	v_addc_co_u32_e32 v13, vcc, 0, v11, vcc
	s_mov_b32 s53, 0x15000
	s_ashr_i32 s79, s78, 31
	s_mov_b64 s[0:1], 0x12000
	v_lshl_add_u64 v[4:5], v[4:5], 0, v[6:7]
	s_mov_b64 s[94:95], 0x15000
	v_add_co_u32_e32 v6, vcc, s53, v10
	s_lshl_b64 s[6:7], s[78:79], 15
	v_lshlrev_b32_e32 v3, 2, v206
	v_lshl_add_u64 v[8:9], v[10:11], 0, s[0:1]
	global_load_dword v149, v[12:13], off nt
	global_load_dword v150, v[8:9], off offset:2048 nt
	global_load_dwordx2 v[38:39], v[4:5], off nt
	v_lshl_add_u64 v[4:5], v[10:11], 0, s[94:95]
	v_addc_co_u32_e32 v7, vcc, 0, v11, vcc
	s_add_u32 s6, s70, s6
	v_and_b32_e32 v139, 0x7c, v3
	global_load_dword v152, v[6:7], off nt
	global_load_dword v153, v[4:5], off offset:2048 nt
	s_addc_u32 s7, s71, s7
	v_lshlrev_b32_e32 v4, 1, v139
	v_mov_b32_e32 v5, v19
	v_and_b32_e32 v8, 0xf80, v3
	v_lshl_add_u64 v[6:7], s[6:7], 0, v[4:5]
	v_lshlrev_b32_e32 v10, 1, v8
	v_mov_b32_e32 v11, v19
	v_add_u32_e32 v9, 0x800, v3
	s_movk_i32 s33, 0x2000
	v_lshl_add_u64 v[10:11], v[6:7], 0, v[10:11]
	v_and_b32_e32 v12, 0x1f80, v9
	v_add_u32_e32 v9, 0x1800, v3
	v_lshlrev_b32_e32 v14, 1, v12
	v_mov_b32_e32 v15, v19
	v_add_co_u32_e32 v34, vcc, s33, v10
	v_and_b32_e32 v72, 0x3f80, v9
	s_movk_i32 s92, 0x4000
	v_lshl_add_u64 v[14:15], v[6:7], 0, v[14:15]
	v_addc_co_u32_e32 v35, vcc, 0, v11, vcc
; #define LAS __attribute__((address_space(3)))
; __device__ void phase_hgrn_out(const Params& p, LAS unsigned char* lds) {
;     const int tid = threadIdx.x, lane = tid & 63, w = tid >> 6, fr = lane & 15, fq = lane >> 4;
;     LAS bf16_t* Qe = (LAS bf16_t*)(lds);
;     LAS bf16_t* Ke = (LAS bf16_t*)(lds + 17408);
;     LAS bf16_t* St = (LAS bf16_t*)(lds + 34816);
;     LAS bf16_t* Vt = (LAS bf16_t*)(lds + 69632);
;     LAS bf16_t* Pm = (LAS bf16_t*)(lds + 88064);
;     LAS float* tots = (LAS float*)(lds + 97280);
;     LAS float* ssq = (LAS float*)(lds + 101376);
;     const float* logf = (const float*)(p.ws + WS_LOGF);
;     const bf16_t* proj = (const bf16_t*)(p.ws + WS_B0);
;     const bf16_t* us = (const bf16_t*)p.out;
;     bf16_t* mix = (bf16_t*)(p.ws + WS_H);
;     const int kp = lane, sg = w;
;     f32x2 c[8]; unsigned vv[8], qv[8]; u32x2 sv[8];
;     ...
;     if ((int)blockIdx.x < 4096) HG_LOAD_PRE(blockIdx.x);
;     for (int item = blockIdx.x; item < 4096; item += gridDim.x) {
;         const int bh = item >> 7, n = item & 127, b = bh >> 3, h = bh & 7;
	v_lshlrev_b32_e32 v36, 1, v72
	v_mov_b32_e32 v37, v19
	v_lshl_add_u64 v[36:37], v[6:7], 0, v[36:37]
	global_load_dwordx2 v[54:55], v[10:11], off nt
	global_load_dwordx2 v[56:57], v[14:15], off nt
	global_load_dwordx2 v[58:59], v[34:35], off nt
	global_load_dwordx2 v[60:61], v[36:37], off nt
	v_add_co_u32_e32 v14, vcc, s92, v10
	v_add_u32_e32 v9, 0x2800, v3
	v_add_u32_e32 v3, 0x3800, v3
	v_addc_co_u32_e32 v15, vcc, 0, v11, vcc
	v_and_b32_e32 v74, 0x3f80, v9
	v_and_b32_e32 v76, 0x7f80, v3
	v_lshlrev_b32_e32 v34, 1, v74
	v_mov_b32_e32 v35, v19
	v_add_co_u32_e32 v10, vcc, s51, v10
	v_lshlrev_b32_e32 v36, 1, v76
	v_mov_b32_e32 v37, v19
	v_lshl_add_u64 v[34:35], v[6:7], 0, v[34:35]
	v_addc_co_u32_e32 v11, vcc, 0, v11, vcc
	v_lshl_add_u64 v[6:7], v[6:7], 0, v[36:37]
	global_load_dwordx2 v[80:81], v[14:15], off nt
	global_load_dwordx2 v[82:83], v[34:35], off nt
	global_load_dwordx2 v[84:85], v[10:11], off nt
	global_load_dwordx2 v[86:87], v[6:7], off nt
	v_writelane_b32 v250, s76, 44
	v_and_b32_e32 v62, 15, v206
	v_lshlrev_b32_e32 v0, 1, v1
	s_add_i32 s6, 0, 0x17c00
	v_mul_u32_u24_e32 v3, 0x120, v1
	s_add_i32 s7, 0, 0x11000
	v_add_u32_e32 v7, 0, v4
	v_lshrrev_b32_e32 v9, 7, v206
	s_mov_b64 s[8:9], s[96:97]
	v_lshl_add_u64 v[42:43], s[70:71], 0, v[4:5]
	v_and_b32_e32 v4, 48, v206
	v_cmp_gt_u32_e64 s[46:47], 16, v1
	v_mul_u32_u24_e32 v1, 0x440, v176
	v_writelane_b32 v250, s77, 45
	v_lshlrev_b32_e32 v6, 4, v176
	v_bfe_u32 v11, v206, 6, 1
	v_lshl_or_b32 v34, v9, 4, v62
	v_lshrrev_b32_e32 v10, 2, v206
	s_add_u32 s96, s8, 0xc0
	v_lshl_add_u64 v[40:41], s[4:5], 0, v[18:19]
	v_add_u32_e32 v13, 0, v4
	s_movk_i32 s4, 0x110
	v_lshlrev_b32_e32 v1, 1, v1
	v_add3_u32 v147, s7, v3, v6
	v_lshrrev_b32_e32 v3, 5, v206
	v_and_b32_e32 v10, 12, v10
	v_writelane_b32 v250, s8, 46
	s_addc_u32 s97, s9, 0
	v_lshlrev_b32_e32 v5, 1, v11
	v_mad_u32_u24 v151, v34, s4, v13
	s_add_i32 s4, 0, 0x15800
	v_add3_u32 v157, 0, v2, v1
	v_lshlrev_b32_e32 v2, 5, v11
	v_lshlrev_b32_e32 v36, 2, v3
	s_movk_i32 s5, 0x90
	v_mov_b32_e32 v14, s4
	v_mul_u32_u24_e32 v1, 0x110, v3
	v_cmp_le_u32_e64 s[22:23], v5, v9
	v_or_b32_e32 v3, v2, v62
	v_cmp_lt_u32_e64 s[24:25], v5, v9
	v_or_b32_e32 v5, 16, v2
	v_or_b32_e32 v2, v2, v10
	v_add_u32_e32 v145, s6, v18
	v_lshlrev_b32_e32 v6, 6, v11
	v_mad_u32_u24 v14, v34, s5, v14
	v_or_b32_e32 v18, 2, v2
	v_add_u32_e32 v154, v14, v4
	v_add_u32_e32 v65, s7, v4
	v_or_b32_e32 v4, v6, v10
	v_cmp_gt_u32_e64 s[30:31], v18, v34
	v_or_b32_e32 v18, 3, v2
	v_lshl_add_u32 v148, v139, 2, s6
	s_add_i32 s6, 0, 0x18c00
	v_cmp_gt_u32_e64 s[34:35], v18, v34
	v_lshlrev_b32_e32 v18, 2, v4
	v_or_b32_e32 v15, v6, v62
	v_or_b32_e32 v9, v5, v62
	v_lshl_add_u64 v[62:63], s[62:63], 0, v[18:19]
	s_add_u32 s62, s64, 0x1000
	v_lshl_add_u32 v155, v34, 3, s6
	v_cmp_gt_u32_e64 s[26:27], v2, v34
	v_cmp_lt_u32_e64 s[28:29], v2, v34
	v_lshl_add_u32 v158, v2, 1, v14
	v_or_b32_e32 v2, v5, v10
	s_addc_u32 s63, s65, 0
	v_writelane_b32 v250, s9, 47
	v_lshl_add_u32 v156, v11, 2, v155
	s_movk_i32 s8, 0x7f
	s_movk_i32 s10, 0xbf
	s_movk_i32 s12, 0xff
	s_movk_i32 s14, 0x13f
	s_movk_i32 s16, 0x17f
	s_movk_i32 s18, 0x1bf
	s_movk_i32 s20, 0x1ff
	v_cmp_gt_u32_e32 vcc, 32, v206
	v_add_u32_e32 v44, -2, v36
	v_add_u32_e32 v46, -1, v36
	v_mul_u32_u24_e32 v3, 0x110, v3
	v_mul_u32_u24_e32 v9, 0x110, v9
	v_mul_u32_u24_e32 v11, 0x110, v15
	v_mul_u32_u24_e32 v15, 0x90, v15
	v_or_b32_e32 v5, 2, v2
	v_or_b32_e32 v14, 3, v2
	s_add_u32 s84, s64, 0x2000
	v_lshlrev_b32_e32 v66, 1, v0
	v_mbcnt_lo_u32_b32 v0, -1, 0
	s_mov_b32 s48, s78
	v_lshl_add_u32 v146, v176, 9, v145
	v_mov_b32_e32 v35, v19
	v_cmp_gt_u32_e64 s[56:57], 64, v206
	v_cmp_lt_u32_e64 s[58:59], s8, v206
	v_cmp_lt_u32_e64 s[60:61], s10, v206
	v_cmp_lt_u32_e64 s[66:67], s12, v206
	v_cmp_lt_u32_e64 s[90:91], s14, v206
	v_cmp_lt_u32_e64 s[16:17], s16, v206
	v_cmp_lt_u32_e64 s[18:19], s18, v206
	v_cmp_lt_u32_e64 s[20:21], s20, v206
	v_ashrrev_i32_e32 v45, 31, v44
	v_ashrrev_i32_e32 v47, 31, v46
	v_or_b32_e32 v48, 1, v36
	v_mov_b32_e32 v49, v19
	v_or_b32_e32 v50, 2, v36
	v_mov_b32_e32 v51, v19
	v_or_b32_e32 v52, 3, v36
	v_mov_b32_e32 v53, v19
	v_cmp_gt_u32_e64 s[36:37], v2, v34
	s_addc_u32 s85, s65, 0
	v_add_u32_e32 v159, v7, v1
	v_lshlrev_b32_e32 v18, 1, v10
	v_lshlrev_b32_e32 v64, 1, v6
	s_xor_b64 s[76:77], vcc, -1
	v_lshlrev_b32_e32 v68, 1, v8
	v_lshlrev_b32_e32 v70, 1, v12
	v_lshlrev_b32_e32 v72, 1, v72
	v_lshlrev_b32_e32 v74, 1, v74
	v_lshlrev_b32_e32 v76, 1, v76
	v_add_u32_e32 v160, v13, v3
	v_add_u32_e32 v161, v13, v9
	v_add_u32_e32 v162, v13, v11
	v_add_u32_e32 v163, v65, v15
	v_mbcnt_hi_u32_b32 v164, -1, v0
	v_mov_b32_e32 v165, 0x358637bd
	v_lshlrev_b32_e32 v78, 1, v4
	s_mov_b32 s64, 0xffff0000
	v_cmp_lt_u32_e64 s[38:39], v2, v34
	v_cmp_gt_u32_e64 s[40:41], v5, v34
	v_cmp_gt_u32_e64 s[42:43], v14, v34
	v_writelane_b32 v250, s48, 48
	s_nop 1
	v_writelane_b32 v250, s49, 49
	global_load_dword v225, v224, s[62:63]
	global_load_dword v225, v224, s[62:63]
	global_load_dword v225, v224, s[62:63]
	global_load_dword v225, v224, s[62:63]
	global_load_dword v225, v224, s[62:63]
	global_load_dword v225, v224, s[62:63]
	global_load_dword v225, v224, s[62:63]
	global_load_dword v225, v224, s[62:63]
	s_branch .LBB0_452
.LBB0_451:
	s_or_b64 exec, exec, s[48:49]
	s_waitcnt lgkmcnt(0)
	s_barrier
	ds_read_b64 v[180:181], v155
	v_lshlrev_b64 v[132:133], 12, v[132:133]
	s_cmp_lg_u64 s[80:81], 0
	s_cbranch_scc1 .Lp4_drain
	s_waitcnt vmcnt(32)
	s_branch .Lp4_cont

; __device__ __forceinline__ unsigned cvt_pk_bf16(float lo, float hi) { unsigned r; asm volatile("v_cvt_pk_bf16_f32 %0, %1, %2" : "=v"(r) : "v"(lo), "v"(hi)); return r; }
; __device__ __forceinline__ float bf_lo(unsigned u) { return __uint_as_float(u << 16); }
; __device__ __forceinline__ float bf_hi(unsigned u) { return __uint_as_float(u & 0xffff0000u); }
; __device__ __forceinline__ float silu_f(float v) { return v * __builtin_amdgcn_rcpf(1.0f + __expf(-v)); }
; __device__ void phase_hgrn_out(const Params& p, LAS unsigned char* lds) {
;     ...
;         const float rstd = rsqrtf((ssq[tl * 2] + ssq[tl * 2 + 1]) * (1.0f / 128.0f) + EPS);
; #pragma unroll
;         for (int i = 0; i < 4; ++i) {
;             const int v0 = 16 * (4 * hf + i) + 4 * fq;
;             const f32x4 nw = *(const f32x4*)(p.hgrn_norm_w + v0);
;             u32x2 o;
;             o.x = cvt_pk_bf16(ao[i][0] * rstd * nw[0] * silu_f(bf_lo(gg[i].x)), ao[i][1] * rstd * nw[1] * silu_f(bf_hi(gg[i].x)));
;             o.y = cvt_pk_bf16(ao[i][2] * rstd * nw[2] * silu_f(bf_lo(gg[i].y)), ao[i][3] * rstd * nw[3] * silu_f(bf_hi(gg[i].y)));
;             *(u32x2*)(mix + (t0 + tl) * D + h * 128 + v0) = o;
.Lp4_cont:
	v_lshlrev_b32_e32 v170, 16, v130
	v_and_b32_e32 v172, 0xffff0000, v130
	v_lshlrev_b32_e32 v174, 16, v131
	v_and_b32_e32 v178, 0xffff0000, v131
	v_lshl_add_u64 v[130:131], s[86:87], 0, v[132:133]
	s_waitcnt lgkmcnt(0)
	v_add_f32_e32 v77, v180, v181
	v_mov_b32_e32 v79, v19
	v_mul_f32_e32 v69, 0xbfb8aa3b, v170
	v_mul_f32_e32 v73, 0xbfb8aa3b, v174
	v_lshl_add_u64 v[130:131], v[130:131], 0, s[54:55]
	v_fmamk_f32 v77, v77, 0x3c000000, v165
	s_mov_b32 s48, 0x800000
	v_mul_f32_e32 v71, 0xbfb8aa3b, v172
	v_mul_f32_e32 v75, 0xbfb8aa3b, v178
	v_exp_f32_e32 v69, v69
	v_exp_f32_e32 v73, v73
	v_lshl_add_u64 v[130:131], v[130:131], 0, v[78:79]
	v_mul_f32_e32 v79, 0x4b800000, v77
	v_cmp_gt_f32_e32 vcc, s48, v77
	v_exp_f32_e32 v71, v71
	v_exp_f32_e32 v75, v75
	v_cndmask_b32_e32 v77, v77, v79, vcc
	v_rsq_f32_e32 v77, v77
	v_add_f32_e32 v69, 1.0, v69
	v_add_f32_e32 v73, 1.0, v73
	v_add_f32_e32 v71, 1.0, v71
	v_add_f32_e32 v75, 1.0, v75
	v_rcp_f32_e32 v132, v69
	v_rcp_f32_e32 v180, v73
	v_mul_f32_e32 v69, 0x45800000, v77
	v_cndmask_b32_e32 v69, v77, v69, vcc
	v_mul_f32_e32 v171, v12, v69
	v_mul_f32_e32 v175, v14, v69
	v_mul_f32_e32 v173, v13, v69
	v_mul_f32_e32 v179, v15, v69
	v_mul_f32_e32 v5, v5, v69
	v_mul_f32_e32 v7, v7, v69
	v_mul_f32_e32 v1, v1, v69
	v_mul_f32_e32 v3, v3, v69
	v_readlane_b32 s0, v250, 25
	v_lshlrev_b32_e32 v65, 2, v65
	v_readlane_b32 s12, v250, 37
	v_readlane_b32 s13, v250, 38
	v_lshlrev_b64 v[90:91], 12, v[90:91]
	v_mov_b32_e32 v89, v19
	v_lshlrev_b32_e32 v79, 16, v97
	v_and_b32_e32 v177, 0xffff0000, v97
	v_lshlrev_b32_e32 v182, 16, v92
	v_and_b32_e32 v183, 0xffff0000, v92
	v_lshlrev_b32_e32 v184, 16, v93
	v_and_b32_e32 v185, 0xffff0000, v93
	s_andn2_b64 vcc, exec, s[80:81]
	v_readlane_b32 s1, v250, 26
	v_readlane_b32 s2, v250, 27
	v_readlane_b32 s3, v250, 28
	v_readlane_b32 s4, v250, 29
	v_readlane_b32 s5, v250, 30
	v_readlane_b32 s6, v250, 31
	v_readlane_b32 s7, v250, 32
	v_readlane_b32 s8, v250, 33
	v_readlane_b32 s9, v250, 34
	v_readlane_b32 s10, v250, 35
	v_readlane_b32 s11, v250, 36
	v_readlane_b32 s14, v250, 39
	v_readlane_b32 s15, v250, 40
	v_mov_b32_e32 v167, v209
	v_mov_b32_e32 v169, v211
	v_mov_b32_e32 v133, v208
	v_rcp_f32_e32 v166, v71
	v_mov_b32_e32 v181, v210
	v_rcp_f32_e32 v168, v75
	v_pk_mul_f32 v[12:13], v[132:133], v[170:171]
	v_pk_mul_f32 v[14:15], v[180:181], v[174:175]
	v_mul_f32_e32 v71, v12, v13
	v_mul_f32_e32 v73, v14, v15
	v_pk_mul_f32 v[12:13], v[166:167], v[172:173]
	v_pk_mul_f32 v[14:15], v[168:169], v[178:179]
	v_mul_f32_e32 v12, v12, v13
	v_mul_f32_e32 v13, v14, v15
	v_cvt_pk_bf16_f32 v12, v71, v12
	v_cvt_pk_bf16_f32 v13, v73, v13
	global_store_dwordx2 v[130:131], v[12:13], off
	v_lshlrev_b32_e32 v132, 16, v128
	v_lshlrev_b32_e32 v166, 16, v129
	v_and_b32_e32 v128, 0xffff0000, v128
	v_and_b32_e32 v168, 0xffff0000, v129
	v_mul_f32_e32 v71, 0xbfb8aa3b, v132
	v_mul_f32_e32 v75, 0xbfb8aa3b, v166
	v_mul_f32_e32 v73, 0xbfb8aa3b, v128
	v_mul_f32_e32 v77, 0xbfb8aa3b, v168
	v_exp_f32_e32 v71, v71
	v_exp_f32_e32 v75, v75
	v_exp_f32_e32 v73, v73
	v_exp_f32_e32 v77, v77
	v_add_f32_e32 v71, 1.0, v71
	v_add_f32_e32 v75, 1.0, v75
	v_add_f32_e32 v73, 1.0, v73
	v_add_f32_e32 v77, 1.0, v77
	v_rcp_f32_e32 v170, v71
	v_rcp_f32_e32 v172, v75
	v_mul_f32_e32 v133, v8, v69
	v_mul_f32_e32 v167, v10, v69
	v_mul_f32_e32 v129, v9, v69
	v_mul_f32_e32 v169, v11, v69
	v_lshlrev_b32_e32 v174, 16, v100
	v_and_b32_e32 v175, 0xffff0000, v100
	v_lshlrev_b32_e32 v100, 16, v101
	v_and_b32_e32 v101, 0xffff0000, v101
	v_lshlrev_b32_e32 v178, 16, v94
	v_and_b32_e32 v179, 0xffff0000, v94
	v_lshlrev_b32_e32 v180, 16, v95
	v_and_b32_e32 v181, 0xffff0000, v95
	v_lshlrev_b32_e32 v75, 16, v96
	v_mov_b32_e32 v13, v213
	v_mov_b32_e32 v15, v215
	v_mov_b32_e32 v171, v212
	v_rcp_f32_e32 v12, v73
	v_mov_b32_e32 v173, v214
	v_rcp_f32_e32 v14, v77
	v_pk_mul_f32 v[8:9], v[170:171], v[132:133]
	v_pk_mul_f32 v[10:11], v[172:173], v[166:167]
	v_mul_f32_e32 v71, v8, v9
	v_mul_f32_e32 v73, v10, v11
	v_pk_mul_f32 v[8:9], v[12:13], v[128:129]
	v_pk_mul_f32 v[10:11], v[14:15], v[168:169]
	v_mul_f32_e32 v8, v8, v9
	v_mul_f32_e32 v9, v10, v11
	v_cvt_pk_bf16_f32 v8, v71, v8
	v_cvt_pk_bf16_f32 v9, v73, v9
	global_store_dwordx2 v[130:131], v[8:9], off offset:32
	v_lshlrev_b32_e32 v12, 16, v126
	v_lshlrev_b32_e32 v14, 16, v127
	v_mul_f32_e32 v13, 0xbfb8aa3b, v12
	v_mul_f32_e32 v15, 0xbfb8aa3b, v14
	v_exp_f32_e32 v13, v13
	v_exp_f32_e32 v15, v15
	v_mul_f32_e32 v129, v4, v69
	v_mul_f32_e32 v133, v6, v69
	v_add_f32_e32 v13, 1.0, v13
	v_add_f32_e32 v15, 1.0, v15
	v_rcp_f32_e32 v128, v13
	v_rcp_f32_e32 v132, v15
	v_mul_f32_e32 v167, v2, v69
	v_lshlrev_b32_e32 v168, 16, v114
	v_and_b32_e32 v169, 0xffff0000, v114
	v_lshlrev_b32_e32 v170, 16, v110
	v_and_b32_e32 v171, 0xffff0000, v110
	v_lshlrev_b32_e32 v114, 16, v115
	v_and_b32_e32 v115, 0xffff0000, v115
	v_lshlrev_b32_e32 v110, 16, v111
	v_and_b32_e32 v111, 0xffff0000, v111
	v_lshlrev_b32_e32 v172, 16, v104
	v_and_b32_e32 v173, 0xffff0000, v104
	v_lshlrev_b32_e32 v104, 16, v105
	v_and_b32_e32 v105, 0xffff0000, v105
	v_pk_mul_f32 v[100:101], v[104:105], v[100:101]
	v_lshl_add_u64 v[104:105], s[86:87], 0, v[90:91]
	v_and_b32_e32 v77, 0xffff0000, v96
	v_lshl_add_u64 v[104:105], v[104:105], 0, v[88:89]
	v_mov_b32_e32 v9, v217
	v_mov_b32_e32 v11, v219
	v_mov_b32_e32 v13, v216
	v_and_b32_e32 v8, 0xffff0000, v126
	v_mov_b32_e32 v15, v218
	v_and_b32_e32 v10, 0xffff0000, v127
	v_mul_f32_e32 v4, 0xbfb8aa3b, v8
	v_mul_f32_e32 v6, 0xbfb8aa3b, v10
	v_exp_f32_e32 v4, v4
	v_exp_f32_e32 v6, v6
	v_pk_mul_f32 v[12:13], v[128:129], v[12:13]
	v_pk_mul_f32 v[14:15], v[132:133], v[14:15]
	v_add_f32_e32 v4, 1.0, v4
	v_add_f32_e32 v6, 1.0, v6
; __device__ __forceinline__ unsigned cvt_pk_bf16(float lo, float hi) { unsigned r; asm volatile("v_cvt_pk_bf16_f32 %0, %1, %2" : "=v"(r) : "v"(lo), "v"(hi)); return r; }
; __device__ __forceinline__ float bf_lo(unsigned u) { return __uint_as_float(u << 16); }
; __device__ __forceinline__ float bf_hi(unsigned u) { return __uint_as_float(u & 0xffff0000u); }
; __device__ __forceinline__ float silu_f(float v) { return v * __builtin_amdgcn_rcpf(1.0f + __expf(-v)); }
; __device__ void phase_hgrn_out(const Params& p, LAS unsigned char* lds) {
;     ...
;             u32x2 o;
;             o.x = cvt_pk_bf16(ao[i][0] * rstd * nw[0] * silu_f(bf_lo(gg[i].x)), ao[i][1] * rstd * nw[1] * silu_f(bf_hi(gg[i].x)));
;             o.y = cvt_pk_bf16(ao[i][2] * rstd * nw[2] * silu_f(bf_lo(gg[i].y)), ao[i][3] * rstd * nw[3] * silu_f(bf_hi(gg[i].y)));
;             *(u32x2*)(mix + (t0 + tl) * D + h * 128 + v0) = o;
;         }
;         {
;             const f32x4 w0 = *(const f32x4*)(p.sconv_w + cc_), w1 = *(const f32x4*)(p.sconv_w + 1024 + cc_), w2 = *(const f32x4*)(p.sconv_w + 2048 + cc_);
;             f32x4 z[6];
; #pragma unroll
;             for (int r = 0; r < 6; ++r) z[r] = (f32x4){bf_lo(za[r].x) * bf_lo(zb[r].x), bf_hi(za[r].x) * bf_hi(zb[r].x), bf_lo(za[r].y) * bf_lo(zb[r].y), bf_hi(za[r].y) * bf_hi(zb[r].y)};
; #pragma unroll
;             for (int i = 0; i < 4; ++i) {
;                 const size_t t = t0 + 4 * tr + i;
;                 const f32x4 y = w0 * z[i] + w1 * z[i + 1] + w2 * z[i + 2];
;                 u32x2 o; o.x = cvt_pk_bf16(bf_lo(cbv[i].x) * y[0], bf_hi(cbv[i].x) * y[1]); o.y = cvt_pk_bf16(bf_lo(cbv[i].y) * y[2], bf_hi(cbv[i].y) * y[3]);
;                 *(u32x2*)(mix + t * D + 1024 + cc_) = o;
;             }
;         }
	v_rcp_f32_e32 v4, v4
	v_rcp_f32_e32 v6, v6
	v_mul_f32_e32 v12, v12, v13
	v_mul_f32_e32 v13, v14, v15
	v_pk_mul_f32 v[4:5], v[4:5], v[8:9]
	v_pk_mul_f32 v[6:7], v[6:7], v[10:11]
	v_mul_f32_e32 v4, v4, v5
	v_mul_f32_e32 v5, v6, v7
	v_cvt_pk_bf16_f32 v4, v12, v4
	v_cvt_pk_bf16_f32 v5, v13, v5
	global_store_dwordx2 v[130:131], v[4:5], off offset:64
	v_lshlrev_b32_e32 v126, 16, v102
	v_lshlrev_b32_e32 v128, 16, v103
	v_mul_f32_e32 v133, v0, v69
	v_mul_f32_e32 v71, 0xbfb8aa3b, v126
	v_mul_f32_e32 v73, 0xbfb8aa3b, v128
	v_exp_f32_e32 v71, v71
	v_exp_f32_e32 v73, v73
	v_lshlrev_b32_e32 v8, 16, v120
	v_and_b32_e32 v9, 0xffff0000, v120
	v_add_f32_e32 v71, 1.0, v71
	v_add_f32_e32 v73, 1.0, v73
	v_rcp_f32_e32 v132, v71
	v_rcp_f32_e32 v166, v73
	v_lshlrev_b32_e32 v10, 16, v118
	v_and_b32_e32 v11, 0xffff0000, v118
	v_lshlrev_b32_e32 v12, 16, v121
	v_and_b32_e32 v13, 0xffff0000, v121
	v_lshlrev_b32_e32 v14, 16, v119
	v_and_b32_e32 v15, 0xffff0000, v119
	v_lshlrev_b32_e32 v118, 16, v124
	v_and_b32_e32 v119, 0xffff0000, v124
	v_lshlrev_b32_e32 v120, 16, v122
	v_and_b32_e32 v121, 0xffff0000, v122
	v_lshlrev_b32_e32 v124, 16, v125
	v_and_b32_e32 v125, 0xffff0000, v125
	v_lshlrev_b32_e32 v122, 16, v123
	v_and_b32_e32 v123, 0xffff0000, v123
	v_pk_mul_f32 v[8:9], v[8:9], v[10:11]
	v_pk_mul_f32 v[10:11], v[12:13], v[14:15]
	v_pk_mul_f32 v[12:13], v[118:119], v[120:121]
	v_pk_mul_f32 v[14:15], v[124:125], v[122:123]
	v_and_b32_e32 v73, 0xffff0000, v109
	v_mov_b32_e32 v5, v221
	v_mov_b32_e32 v7, v223
	v_mov_b32_e32 v127, v220
	v_and_b32_e32 v4, 0xffff0000, v102
	v_mov_b32_e32 v129, v222
	v_and_b32_e32 v6, 0xffff0000, v103
	v_mul_f32_e32 v0, 0xbfb8aa3b, v4
	v_mul_f32_e32 v2, 0xbfb8aa3b, v6
	v_exp_f32_e32 v0, v0
	v_exp_f32_e32 v2, v2
	v_pk_mul_f32 v[102:103], v[132:133], v[126:127]
	v_pk_mul_f32 v[126:127], v[166:167], v[128:129]
	v_add_f32_e32 v0, 1.0, v0
	v_add_f32_e32 v2, 1.0, v2
	v_rcp_f32_e32 v0, v0
	v_rcp_f32_e32 v2, v2
	v_mul_f32_e32 v69, v102, v103
	v_mul_f32_e32 v71, v126, v127
	v_pk_mul_f32 v[0:1], v[0:1], v[4:5]
	v_pk_mul_f32 v[2:3], v[2:3], v[6:7]
	v_mul_f32_e32 v0, v0, v1
	v_mul_f32_e32 v1, v2, v3
	v_cvt_pk_bf16_f32 v0, v69, v0
	v_cvt_pk_bf16_f32 v1, v71, v1
	global_store_dwordx2 v[130:131], v[0:1], off offset:96
	v_mov_b32_e32 v0, v226
	v_mov_b32_e32 v1, v227
	v_mov_b32_e32 v2, v228
	v_mov_b32_e32 v3, v229
	v_mov_b32_e32 v4, v230
	v_mov_b32_e32 v5, v231
	v_mov_b32_e32 v6, v232
	v_mov_b32_e32 v7, v233
	v_mov_b32_e32 v126, v234
	v_mov_b32_e32 v127, v235
	v_mov_b32_e32 v128, v236
	v_mov_b32_e32 v129, v237
	v_lshlrev_b32_e32 v102, 16, v116
	v_and_b32_e32 v103, 0xffff0000, v116
	v_lshlrev_b32_e32 v130, 16, v112
	v_and_b32_e32 v131, 0xffff0000, v112
	v_lshlrev_b32_e32 v116, 16, v117
	v_and_b32_e32 v117, 0xffff0000, v117
	v_lshlrev_b32_e32 v112, 16, v113
	v_and_b32_e32 v113, 0xffff0000, v113
	v_lshlrev_b32_e32 v132, 16, v106
	v_and_b32_e32 v133, 0xffff0000, v106
	v_lshlrev_b32_e32 v166, 16, v98
	v_and_b32_e32 v167, 0xffff0000, v98
	v_lshlrev_b32_e32 v106, 16, v107
	v_and_b32_e32 v107, 0xffff0000, v107
	v_lshlrev_b32_e32 v98, 16, v99
	v_and_b32_e32 v99, 0xffff0000, v99
	v_pk_mul_f32 v[94:95], v[116:117], v[112:113]
	v_pk_mul_f32 v[98:99], v[106:107], v[98:99]
	v_pk_mul_f32 v[106:107], v[114:115], v[110:111]
	v_or_b32_e32 v110, 0x1000, v90
	v_mov_b32_e32 v111, v91
	v_or_b32_e32 v112, 0x2000, v90
	v_mov_b32_e32 v113, v91
	v_or_b32_e32 v90, 0x3000, v90
	v_pk_mul_f32 v[92:93], v[102:103], v[130:131]
	v_pk_mul_f32 v[96:97], v[132:133], v[166:167]
	v_pk_mul_f32 v[102:103], v[168:169], v[170:171]
	v_lshl_add_u64 v[110:111], s[86:87], 0, v[110:111]
	v_lshl_add_u64 v[112:113], s[86:87], 0, v[112:113]
	v_lshl_add_u64 v[90:91], s[86:87], 0, v[90:91]
	v_lshl_add_u64 v[110:111], v[110:111], 0, v[88:89]
	v_lshl_add_u64 v[112:113], v[112:113], 0, v[88:89]
	v_lshl_add_u64 v[88:89], v[90:91], 0, v[88:89]
	v_lshlrev_b32_e32 v65, 16, v108
	v_and_b32_e32 v69, 0xffff0000, v108
	v_lshlrev_b32_e32 v71, 16, v109
	v_pk_mul_f32 v[108:109], v[172:173], v[174:175]
	v_pk_mul_f32 v[90:91], v[14:15], v[6:7]
	v_pk_mul_f32 v[114:115], v[12:13], v[4:5]
	v_pk_mul_f32 v[118:119], v[92:93], v[4:5]
	v_pk_mul_f32 v[122:123], v[96:97], v[4:5]
	v_pk_mul_f32 v[4:5], v[102:103], v[4:5]
	v_pk_mul_f32 v[116:117], v[94:95], v[6:7]
	v_pk_mul_f32 v[120:121], v[98:99], v[6:7]
	v_pk_mul_f32 v[6:7], v[106:107], v[6:7]
	v_pk_fma_f32 v[8:9], v[8:9], v[0:1], v[114:115]
	v_pk_fma_f32 v[10:11], v[10:11], v[2:3], v[90:91]
	v_pk_fma_f32 v[12:13], v[12:13], v[0:1], v[118:119]
	v_pk_fma_f32 v[90:91], v[92:93], v[0:1], v[122:123]
	v_pk_fma_f32 v[0:1], v[96:97], v[0:1], v[4:5]
	v_pk_fma_f32 v[14:15], v[14:15], v[2:3], v[116:117]
	v_pk_fma_f32 v[114:115], v[94:95], v[2:3], v[120:121]
	v_pk_fma_f32 v[2:3], v[98:99], v[2:3], v[6:7]
	v_pk_fma_f32 v[4:5], v[94:95], v[128:129], v[10:11]
	v_pk_fma_f32 v[6:7], v[92:93], v[126:127], v[8:9]
	v_pk_fma_f32 v[0:1], v[108:109], v[126:127], v[0:1]
	v_pk_fma_f32 v[8:9], v[98:99], v[128:129], v[14:15]
	v_pk_fma_f32 v[10:11], v[96:97], v[126:127], v[12:13]
	v_mul_f32_e32 v6, v6, v65
	v_mul_f32_e32 v7, v7, v69
	v_mul_f32_e32 v4, v4, v71
	v_mul_f32_e32 v5, v5, v73
	v_mul_f32_e32 v65, v0, v182
	v_mul_f32_e32 v69, v1, v183
	v_cvt_pk_bf16_f32 v0, v6, v7
	v_cvt_pk_bf16_f32 v1, v4, v5
	v_pk_fma_f32 v[12:13], v[106:107], v[128:129], v[114:115]
	v_pk_fma_f32 v[14:15], v[102:103], v[126:127], v[90:91]
	v_mul_f32_e32 v10, v10, v75
	v_mul_f32_e32 v11, v11, v77
	v_mul_f32_e32 v8, v8, v79
	v_mul_f32_e32 v9, v9, v177
	global_store_dwordx2 v[104:105], v[0:1], off offset:2048
	v_cvt_pk_bf16_f32 v0, v10, v11
	v_cvt_pk_bf16_f32 v1, v8, v9
	v_pk_fma_f32 v[2:3], v[100:101], v[128:129], v[2:3]
	v_mul_f32_e32 v14, v14, v178
	v_mul_f32_e32 v15, v15, v179
	v_mul_f32_e32 v12, v12, v180
	v_mul_f32_e32 v13, v13, v181
	global_store_dwordx2 v[110:111], v[0:1], off offset:2048
	v_cvt_pk_bf16_f32 v0, v14, v15
	v_cvt_pk_bf16_f32 v1, v12, v13
	v_mul_f32_e32 v2, v2, v184
	v_mul_f32_e32 v3, v3, v185
	global_store_dwordx2 v[112:113], v[0:1], off offset:2048
	v_cvt_pk_bf16_f32 v0, v65, v69
	v_cvt_pk_bf16_f32 v1, v2, v3
	global_store_dwordx2 v[88:89], v[0:1], off offset:2048
	s_waitcnt lgkmcnt(0)
	s_barrier
	s_cbranch_vccz .LBB0_464
; #define LAS __attribute__((address_space(3)))
; __device__ __forceinline__ unsigned cvt_pk_bf16(float lo, float hi) { unsigned r; asm volatile("v_cvt_pk_bf16_f32 %0, %1, %2" : "=v"(r) : "v"(lo), "v"(hi)); return r; }
; __device__ __forceinline__ float bf_lo(unsigned u) { return __uint_as_float(u << 16); }
; __device__ __forceinline__ float bf_hi(unsigned u) { return __uint_as_float(u & 0xffff0000u); }
; #define LDS_BARRIER() do { asm volatile("s_waitcnt lgkmcnt(0)" ::: "memory"); __builtin_amdgcn_s_barrier(); asm volatile("" ::: "memory"); } while (0)
; __device__ void phase_hgrn_out(const Params& p, LAS unsigned char* lds) {
;     ...
;         f32x2 kk[8];
; #pragma unroll
;         for (int i = 0; i < 8; ++i) { kk[i].x = 1.0f - __expf(c[i].x); kk[i].y = 1.0f - __expf(c[i].y); }
; #pragma unroll
;         for (int i = 1; i < 8; ++i) c[i] += c[i - 1];
;         *(LAS f32x2*)(tots + sg * 128 + 2 * kp) = c[7];
;         LDS_BARRIER();
;         f32x2 off = {0.f, 0.f}, tot = {0.f, 0.f};
; #pragma unroll
;         for (int g = 0; g < 8; ++g) { const f32x2 tv = *(const LAS f32x2*)(tots + g * 128 + 2 * kp); if (g < sg) off += tv; tot += tv; }
;         const f32x2 ref = tot * 0.5f;
; #pragma unroll
;         for (int i = 0; i < 8; ++i) {
;             const float bx = off.x + c[i].x - ref.x, by = off.y + c[i].y - ref.y;
;             const int t = 8 * sg + i;
;             *(LAS unsigned*)(Qe + t * 136 + 2 * kp) = cvt_pk_bf16(bf_lo(qv[i]) * __expf(bx), bf_hi(qv[i]) * __expf(by));
;             *(LAS unsigned*)(Ke + t * 136 + 2 * kp) = cvt_pk_bf16(kk[i].x * __expf(-bx), kk[i].y * __expf(-by));
;         }
.LBB0_452:
	s_waitcnt vmcnt(39)
	v_mul_f32_e32 v0, 0x3fb8aa3b, v20
	v_exp_f32_e32 v0, v0
	s_waitcnt vmcnt(38)
	v_lshlrev_b32_e32 v79, 16, v17
	s_ashr_i32 s80, s78, 10
	s_and_b32 s48, s78, 0x7f
	v_sub_f32_e32 v65, 1.0, v0
	v_mul_f32_e32 v0, 0x3fb8aa3b, v21
	v_exp_f32_e32 v0, v0
	s_ashr_i32 s81, s80, 31
	s_lshl_b32 s49, s48, 6
	s_lshl_b64 s[80:81], s[80:81], 13
	v_sub_f32_e32 v69, 1.0, v0
	s_waitcnt vmcnt(36)
	v_mul_f32_e32 v0, 0x3fb8aa3b, v22
	v_exp_f32_e32 v0, v0
	s_or_b32 s80, s80, s49
	v_lshl_add_u64 v[132:133], s[80:81], 0, v[34:35]
	s_and_b32 s65, s78, 0x380
	v_sub_f32_e32 v71, 1.0, v0
	v_mul_f32_e32 v0, 0x3fb8aa3b, v23
	v_exp_f32_e32 v0, v0
	v_pk_add_f32 v[22:23], v[20:21], v[22:23]
	s_lshl_b32 s54, s65, 1
	s_cmp_lg_u32 s48, 0
	v_sub_f32_e32 v73, 1.0, v0
	s_waitcnt vmcnt(34)
	v_mul_f32_e32 v0, 0x3fb8aa3b, v24
	v_exp_f32_e32 v0, v0
	s_cselect_b64 s[48:49], -1, 0
	v_mov_b32_e32 v120, 0
	v_mov_b32_e32 v121, 0
	v_sub_f32_e32 v75, 1.0, v0
	v_mul_f32_e32 v0, 0x3fb8aa3b, v25
	v_exp_f32_e32 v0, v0
	v_pk_add_f32 v[24:25], v[22:23], v[24:25]
	v_mov_b32_e32 v118, 0
	v_mov_b32_e32 v119, 0
	v_sub_f32_e32 v77, 1.0, v0
	s_waitcnt vmcnt(30)
	v_mul_f32_e32 v0, 0x3fb8aa3b, v26
	v_exp_f32_e32 v0, v0
	s_nop 0
	v_sub_f32_e32 v13, 1.0, v0
	v_mul_f32_e32 v0, 0x3fb8aa3b, v27
	v_exp_f32_e32 v0, v0
	v_pk_add_f32 v[26:27], v[24:25], v[26:27]
	v_sub_f32_e32 v12, 1.0, v0
	s_waitcnt vmcnt(28)
	v_mul_f32_e32 v0, 0x3fb8aa3b, v28
	v_exp_f32_e32 v0, v0
	s_nop 0
	v_sub_f32_e32 v11, 1.0, v0
	v_mul_f32_e32 v0, 0x3fb8aa3b, v29
	v_exp_f32_e32 v0, v0
	v_pk_add_f32 v[28:29], v[26:27], v[28:29]
	v_sub_f32_e32 v10, 1.0, v0
	s_waitcnt vmcnt(25)
	v_mul_f32_e32 v0, 0x3fb8aa3b, v30
	v_exp_f32_e32 v0, v0
	s_nop 0
	v_sub_f32_e32 v9, 1.0, v0
	v_mul_f32_e32 v0, 0x3fb8aa3b, v31
	v_exp_f32_e32 v0, v0
	v_pk_add_f32 v[30:31], v[28:29], v[30:31]
	v_sub_f32_e32 v8, 1.0, v0
	s_waitcnt vmcnt(21)
	v_mul_f32_e32 v0, 0x3fb8aa3b, v32
	v_exp_f32_e32 v0, v0
	s_nop 0
	v_sub_f32_e32 v7, 1.0, v0
	v_mul_f32_e32 v0, 0x3fb8aa3b, v33
	v_exp_f32_e32 v0, v0
	v_pk_add_f32 v[32:33], v[30:31], v[32:33]
	v_sub_f32_e32 v6, 1.0, v0
	s_waitcnt vmcnt(18)
	v_mul_f32_e32 v0, 0x3fb8aa3b, v38
	v_exp_f32_e32 v0, v0
	s_nop 0
	v_sub_f32_e32 v5, 1.0, v0
	v_mul_f32_e32 v0, 0x3fb8aa3b, v39
	v_exp_f32_e32 v0, v0
	v_pk_add_f32 v[38:39], v[32:33], v[38:39]
	ds_write_b64 v146, v[38:39]
	s_waitcnt lgkmcnt(0)
	s_barrier
	v_sub_f32_e32 v4, 1.0, v0
	ds_read2st64_b64 v[0:3], v145 offset1:1
	s_waitcnt lgkmcnt(0)
	v_pk_add_f32 v[0:1], v[0:1], 0 op_sel_hi:[1,0]
	s_nop 0
	v_cndmask_b32_e64 v15, v1, 0, s[56:57]
	v_cndmask_b32_e64 v14, v0, 0, s[56:57]
	v_pk_add_f32 v[88:89], v[2:3], v[14:15]
	s_nop 0
	v_cndmask_b32_e64 v15, v15, v89, s[58:59]
	v_cndmask_b32_e64 v14, v14, v88, s[58:59]
	v_pk_add_f32 v[88:89], v[0:1], v[2:3]
	ds_read2st64_b64 v[0:3], v145 offset0:2 offset1:3
	s_waitcnt lgkmcnt(0)
	v_pk_add_f32 v[90:91], v[0:1], v[14:15]
	s_nop 0
	v_cndmask_b32_e64 v15, v15, v91, s[60:61]
	v_cndmask_b32_e64 v14, v14, v90, s[60:61]
	v_pk_add_f32 v[0:1], v[88:89], v[0:1]
	v_pk_add_f32 v[88:89], v[2:3], v[14:15]
	s_nop 0
	v_cndmask_b32_e64 v15, v15, v89, s[66:67]
	v_cndmask_b32_e64 v14, v14, v88, s[66:67]
	v_pk_add_f32 v[88:89], v[0:1], v[2:3]
	ds_read2st64_b64 v[0:3], v145 offset0:4 offset1:5
	s_waitcnt lgkmcnt(0)
	v_pk_add_f32 v[90:91], v[0:1], v[14:15]
	s_nop 0
	v_cndmask_b32_e64 v15, v15, v91, s[90:91]
	v_cndmask_b32_e64 v14, v14, v90, s[90:91]
	v_pk_add_f32 v[0:1], v[88:89], v[0:1]
	v_pk_add_f32 v[88:89], v[2:3], v[14:15]
	s_nop 0
	v_cndmask_b32_e64 v15, v15, v89, s[16:17]
	v_cndmask_b32_e64 v14, v14, v88, s[16:17]
	v_pk_add_f32 v[88:89], v[0:1], v[2:3]
	ds_read2st64_b64 v[0:3], v145 offset0:6 offset1:7
	s_waitcnt lgkmcnt(0)
	v_pk_add_f32 v[90:91], v[0:1], v[14:15]
	s_nop 0
	v_cndmask_b32_e64 v15, v15, v91, s[18:19]
	v_cndmask_b32_e64 v14, v14, v90, s[18:19]
	v_pk_add_f32 v[88:89], v[88:89], v[0:1]
	v_pk_add_f32 v[0:1], v[2:3], v[14:15]
	v_pk_add_f32 v[2:3], v[88:89], v[2:3]
	v_cndmask_b32_e64 v1, v15, v1, s[20:21]
	v_cndmask_b32_e64 v0, v14, v0, s[20:21]
	v_pk_add_f32 v[14:15], v[20:21], v[0:1]
	s_nop 0
	v_pk_fma_f32 v[14:15], v[2:3], 0.5, v[14:15] op_sel_hi:[1,0,1] neg_lo:[1,0,0] neg_hi:[1,0,0]
	s_nop 0
	v_mul_f32_e32 v88, 0x3fb8aa3b, v14
	v_mul_f32_e32 v14, 0xbfb8aa3b, v14
	v_exp_f32_e32 v88, v88
	v_mul_f32_e32 v89, 0x3fb8aa3b, v15
	v_exp_f32_e32 v14, v14
	v_mul_f32_e32 v15, 0xbfb8aa3b, v15
	v_exp_f32_e32 v89, v89
	v_exp_f32_e32 v15, v15
	v_mul_f32_e32 v79, v88, v79
	v_and_b32_e32 v88, 0xffff0000, v17
	v_mul_f32_e32 v14, v65, v14
	v_mul_f32_e32 v88, v89, v88
	v_cvt_pk_bf16_f32 v79, v79, v88
	ds_write_b32 v157, v79
	v_mul_f32_e32 v15, v69, v15
	v_cvt_pk_bf16_f32 v14, v14, v15
	ds_write_b32 v157, v14 offset:17408
	v_pk_add_f32 v[14:15], v[22:23], v[0:1]
	v_lshlrev_b32_e32 v65, 16, v134
	v_pk_fma_f32 v[14:15], v[2:3], 0.5, v[14:15] op_sel_hi:[1,0,1] neg_lo:[1,0,0] neg_hi:[1,0,0]
	s_nop 0
	v_mul_f32_e32 v69, 0x3fb8aa3b, v14
	v_mul_f32_e32 v14, 0xbfb8aa3b, v14
	v_exp_f32_e32 v69, v69
	v_mul_f32_e32 v79, 0x3fb8aa3b, v15
	v_exp_f32_e32 v14, v14
	v_mul_f32_e32 v15, 0xbfb8aa3b, v15
	v_exp_f32_e32 v79, v79
	v_exp_f32_e32 v15, v15
	v_mul_f32_e32 v65, v69, v65
	v_and_b32_e32 v69, 0xffff0000, v134
	v_mul_f32_e32 v14, v71, v14
	v_mul_f32_e32 v69, v79, v69
	v_cvt_pk_bf16_f32 v65, v65, v69
	ds_write_b32 v157, v65 offset:272
	v_mul_f32_e32 v15, v73, v15
	v_cvt_pk_bf16_f32 v14, v14, v15
	ds_write_b32 v157, v14 offset:17680
	v_pk_add_f32 v[14:15], v[24:25], v[0:1]
	v_lshlrev_b32_e32 v65, 16, v135
	v_pk_fma_f32 v[14:15], v[2:3], 0.5, v[14:15] op_sel_hi:[1,0,1] neg_lo:[1,0,0] neg_hi:[1,0,0]
	s_nop 0
	v_mul_f32_e32 v69, 0x3fb8aa3b, v14
; #define LAS __attribute__((address_space(3)))
; __device__ __forceinline__ unsigned cvt_pk_bf16(float lo, float hi) { unsigned r; asm volatile("v_cvt_pk_bf16_f32 %0, %1, %2" : "=v"(r) : "v"(lo), "v"(hi)); return r; }
; __device__ __forceinline__ float bf_lo(unsigned u) { return __uint_as_float(u << 16); }
; __device__ __forceinline__ float bf_hi(unsigned u) { return __uint_as_float(u & 0xffff0000u); }
; __device__ void phase_hgrn_out(const Params& p, LAS unsigned char* lds) {
;     ...
;         for (int i = 0; i < 8; ++i) {
;             const float bx = off.x + c[i].x - ref.x, by = off.y + c[i].y - ref.y;
;             const int t = 8 * sg + i;
;             *(LAS unsigned*)(Qe + t * 136 + 2 * kp) = cvt_pk_bf16(bf_lo(qv[i]) * __expf(bx), bf_hi(qv[i]) * __expf(by));
;             *(LAS unsigned*)(Ke + t * 136 + 2 * kp) = cvt_pk_bf16(kk[i].x * __expf(-bx), kk[i].y * __expf(-by));
;         }
;         {
;             u32x4 v0, v1;
;             v0.x = (vv[0] & 0xffffu) | (vv[1] << 16); v0.y = (vv[2] & 0xffffu) | (vv[3] << 16); v0.z = (vv[4] & 0xffffu) | (vv[5] << 16); v0.w = (vv[6] & 0xffffu) | (vv[7] << 16);
;             v1.x = (vv[0] >> 16) | (vv[1] & 0xffff0000u); v1.y = (vv[2] >> 16) | (vv[3] & 0xffff0000u); v1.z = (vv[4] >> 16) | (vv[5] & 0xffff0000u); v1.w = (vv[6] >> 16) | (vv[7] & 0xffff0000u);
;             *(LAS u32x4*)(Vt + (2 * kp) * 72 + 8 * sg) = v0; *(LAS u32x4*)(Vt + (2 * kp + 1) * 72 + 8 * sg) = v1;
;         }
;         {
;             const int k4 = (tid & 31) * 4;
;             f32x4 tt = {0.f, 0.f, 0.f, 0.f};
; #pragma unroll
;             for (int g = 0; g < 8; ++g) tt += *(const LAS f32x4*)(tots + g * 128 + k4);
	v_mul_f32_e32 v14, 0xbfb8aa3b, v14
	v_exp_f32_e32 v69, v69
	v_mul_f32_e32 v71, 0x3fb8aa3b, v15
	v_exp_f32_e32 v14, v14
	v_mul_f32_e32 v15, 0xbfb8aa3b, v15
	v_exp_f32_e32 v71, v71
	v_exp_f32_e32 v15, v15
	v_mul_f32_e32 v65, v69, v65
	v_and_b32_e32 v69, 0xffff0000, v135
	v_mul_f32_e32 v14, v75, v14
	v_mul_f32_e32 v69, v71, v69
	v_cvt_pk_bf16_f32 v65, v65, v69
	ds_write_b32 v157, v65 offset:544
	v_mul_f32_e32 v15, v77, v15
	v_cvt_pk_bf16_f32 v14, v14, v15
	ds_write_b32 v157, v14 offset:17952
	v_pk_add_f32 v[14:15], v[26:27], v[0:1]
	v_lshlrev_b32_e32 v65, 16, v138
	v_pk_fma_f32 v[14:15], v[2:3], 0.5, v[14:15] op_sel_hi:[1,0,1] neg_lo:[1,0,0] neg_hi:[1,0,0]
	s_nop 0
	v_mul_f32_e32 v69, 0x3fb8aa3b, v14
	v_mul_f32_e32 v14, 0xbfb8aa3b, v14
	v_exp_f32_e32 v14, v14
	v_exp_f32_e32 v69, v69
	v_mul_f32_e32 v71, 0x3fb8aa3b, v15
	v_exp_f32_e32 v71, v71
	v_mul_f32_e32 v13, v13, v14
	v_mul_f32_e32 v14, 0xbfb8aa3b, v15
	v_exp_f32_e32 v14, v14
	v_mul_f32_e32 v65, v69, v65
	v_and_b32_e32 v69, 0xffff0000, v138
	v_mul_f32_e32 v69, v71, v69
	v_mul_f32_e32 v12, v12, v14
	v_cvt_pk_bf16_f32 v65, v65, v69
	ds_write_b32 v157, v65 offset:816
	v_cvt_pk_bf16_f32 v12, v13, v12
	ds_write_b32 v157, v12 offset:18224
	v_pk_add_f32 v[12:13], v[28:29], v[0:1]
	v_lshlrev_b32_e32 v14, 16, v141
	v_pk_fma_f32 v[12:13], v[2:3], 0.5, v[12:13] op_sel_hi:[1,0,1] neg_lo:[1,0,0] neg_hi:[1,0,0]
	s_nop 0
	v_mul_f32_e32 v15, 0x3fb8aa3b, v12
	v_mul_f32_e32 v12, 0xbfb8aa3b, v12
	v_exp_f32_e32 v12, v12
	v_exp_f32_e32 v15, v15
	v_mul_f32_e32 v65, 0x3fb8aa3b, v13
	v_exp_f32_e32 v65, v65
	v_mul_f32_e32 v11, v11, v12
	v_mul_f32_e32 v12, 0xbfb8aa3b, v13
	v_exp_f32_e32 v12, v12
	v_mul_f32_e32 v14, v15, v14
	v_and_b32_e32 v15, 0xffff0000, v141
	v_mul_f32_e32 v15, v65, v15
	v_mul_f32_e32 v10, v10, v12
	v_cvt_pk_bf16_f32 v14, v14, v15
	ds_write_b32 v157, v14 offset:1088
	v_cvt_pk_bf16_f32 v10, v11, v10
	ds_write_b32 v157, v10 offset:18496
	v_pk_add_f32 v[10:11], v[30:31], v[0:1]
	v_lshlrev_b32_e32 v12, 16, v144
	v_pk_fma_f32 v[10:11], v[2:3], 0.5, v[10:11] op_sel_hi:[1,0,1] neg_lo:[1,0,0] neg_hi:[1,0,0]
	v_mov_b32_e32 v65, v19
	v_mul_f32_e32 v13, 0x3fb8aa3b, v10
	v_mul_f32_e32 v10, 0xbfb8aa3b, v10
	v_exp_f32_e32 v10, v10
	v_exp_f32_e32 v13, v13
	v_mul_f32_e32 v14, 0x3fb8aa3b, v11
	v_exp_f32_e32 v14, v14
	v_mul_f32_e32 v9, v9, v10
	v_mul_f32_e32 v10, 0xbfb8aa3b, v11
	v_exp_f32_e32 v10, v10
	v_mul_f32_e32 v12, v13, v12
	v_and_b32_e32 v13, 0xffff0000, v144
	v_mul_f32_e32 v13, v14, v13
	v_mul_f32_e32 v8, v8, v10
	v_cvt_pk_bf16_f32 v12, v12, v13
	ds_write_b32 v157, v12 offset:1360
	v_cvt_pk_bf16_f32 v8, v9, v8
	ds_write_b32 v157, v8 offset:18768
	v_pk_add_f32 v[8:9], v[32:33], v[0:1]
	v_lshlrev_b32_e32 v10, 16, v149
	v_pk_fma_f32 v[8:9], v[2:3], 0.5, v[8:9] op_sel_hi:[1,0,1] neg_lo:[1,0,0] neg_hi:[1,0,0]
	v_pk_add_f32 v[0:1], v[38:39], v[0:1]
	v_mul_f32_e32 v11, 0x3fb8aa3b, v8
	v_mul_f32_e32 v8, 0xbfb8aa3b, v8
	v_exp_f32_e32 v8, v8
	v_exp_f32_e32 v11, v11
	v_mul_f32_e32 v12, 0x3fb8aa3b, v9
	v_exp_f32_e32 v12, v12
	v_mul_f32_e32 v7, v7, v8
	v_mul_f32_e32 v8, 0xbfb8aa3b, v9
	v_exp_f32_e32 v8, v8
	v_mul_f32_e32 v10, v11, v10
	v_and_b32_e32 v11, 0xffff0000, v149
	v_pk_fma_f32 v[0:1], v[2:3], 0.5, v[0:1] op_sel_hi:[1,0,1] neg_lo:[1,0,0] neg_hi:[1,0,0]
	v_mul_f32_e32 v6, v6, v8
	v_mul_f32_e32 v11, v12, v11
	v_cvt_pk_bf16_f32 v10, v10, v11
	ds_write_b32 v157, v10 offset:1632
	v_cvt_pk_bf16_f32 v6, v7, v6
	v_mul_f32_e32 v3, 0x3fb8aa3b, v0
	v_mul_f32_e32 v0, 0xbfb8aa3b, v0
	ds_write_b32 v157, v6 offset:19040
	v_exp_f32_e32 v3, v3
	v_mul_f32_e32 v6, 0x3fb8aa3b, v1
	v_exp_f32_e32 v0, v0
	v_mul_f32_e32 v1, 0xbfb8aa3b, v1
	v_exp_f32_e32 v6, v6
	v_exp_f32_e32 v1, v1
	s_waitcnt vmcnt(17)
	v_lshlrev_b32_e32 v2, 16, v152
	v_mul_f32_e32 v2, v3, v2
	v_and_b32_e32 v3, 0xffff0000, v152
	v_mul_f32_e32 v0, v5, v0
	v_mul_f32_e32 v3, v6, v3
	v_cvt_pk_bf16_f32 v2, v2, v3
	ds_write_b32 v157, v2 offset:1904
	v_mul_f32_e32 v1, v4, v1
	v_cvt_pk_bf16_f32 v0, v0, v1
	ds_write_b32 v157, v0 offset:19312
	v_and_b32_e32 v0, 0xffff, v67
	v_and_b32_e32 v1, 0xffff, v136
	v_and_b32_e32 v2, 0xffff, v142
	v_and_b32_e32 v3, 0xffff, v150
	v_lshl_or_b32 v0, v137, 16, v0
	v_lshl_or_b32 v1, v140, 16, v1
	v_lshl_or_b32 v2, v143, 16, v2
	s_waitcnt vmcnt(16)
	v_lshl_or_b32 v3, v153, 16, v3
	v_lshrrev_b32_e32 v4, 16, v67
	v_lshrrev_b32_e32 v5, 16, v136
	v_lshrrev_b32_e32 v6, 16, v142
	v_lshrrev_b32_e32 v7, 16, v150
	v_and_or_b32 v4, v137, s64, v4
	v_and_or_b32 v5, v140, s64, v5
	v_and_or_b32 v6, v143, s64, v6
	v_and_or_b32 v7, v153, s64, v7
	ds_write_b128 v147, v[0:3]
	ds_write_b128 v147, v[4:7] offset:144
	ds_read_b128 v[0:3], v148
	s_waitcnt lgkmcnt(0)
	v_pk_add_f32 v[4:5], v[2:3], 0 op_sel_hi:[1,0]
	v_pk_add_f32 v[6:7], v[0:1], 0 op_sel_hi:[1,0]
	ds_read_b128 v[0:3], v148 offset:512
	s_waitcnt lgkmcnt(0)
	v_pk_add_f32 v[4:5], v[4:5], v[2:3]
	v_pk_add_f32 v[6:7], v[6:7], v[0:1]
	ds_read_b128 v[0:3], v148 offset:1024
	s_waitcnt lgkmcnt(0)
	v_pk_add_f32 v[4:5], v[4:5], v[2:3]
	v_pk_add_f32 v[6:7], v[6:7], v[0:1]
	ds_read_b128 v[0:3], v148 offset:1536
	s_waitcnt lgkmcnt(0)
; #define LAS __attribute__((address_space(3)))
; __device__ __forceinline__ unsigned cvt_pk_bf16(float lo, float hi) { unsigned r; asm volatile("v_cvt_pk_bf16_f32 %0, %1, %2" : "=v"(r) : "v"(lo), "v"(hi)); return r; }
; __device__ __forceinline__ float bf_lo(unsigned u) { return __uint_as_float(u << 16); }
; __device__ __forceinline__ float bf_hi(unsigned u) { return __uint_as_float(u & 0xffff0000u); }
; __device__ void phase_hgrn_out(const Params& p, LAS unsigned char* lds) {
;     ...
;             const f32x4 er = {__expf(0.5f * tt[0]), __expf(0.5f * tt[1]), __expf(0.5f * tt[2]), __expf(0.5f * tt[3])};
; #pragma unroll
;             for (int i = 0; i < 8; ++i) {
;                 const int v = (tid >> 5) + 16 * i;
;                 u32x2 o; o.x = cvt_pk_bf16(bf_lo(sv[i].x) * er[0], bf_hi(sv[i].x) * er[1]); o.y = cvt_pk_bf16(bf_lo(sv[i].y) * er[2], bf_hi(sv[i].y) * er[3]);
;                 *(LAS u32x2*)(St + v * 136 + k4) = o;
;             }
;         }
;         const int tb = w >> 1, hf = w & 1, tl = 16 * tb + fr;
;         u32x2 gg[4];
; #pragma unroll
;         for (int i = 0; i < 4; ++i) gg[i] = __builtin_nontemporal_load((const u32x2*)(proj + (t0 + tl) * PJ + 2048 + h * 128 + 16 * (4 * hf + i) + 4 * fq));
;         const int cc_ = h * 128 + (tid & 31) * 4, tr = tid >> 5;
;         u32x2 za[6], zb[6], cbv[4];
; #pragma unroll
;         for (int r = 0; r < 6; ++r) {
;             const int tt = 4 * tr + r - 2;
;             if (tt < 0 && n == 0) { za[r] = (u32x2){0u, 0u}; zb[r] = (u32x2){0u, 0u}; }
;             else { const bf16_t* rp = proj + (size_t)((long)t0 + tt) * PJ; za[r] = __builtin_nontemporal_load((const u32x2*)(rp + 4096 + cc_)); zb[r] = __builtin_nontemporal_load((const u32x2*)(rp + 5120 + cc_)); }
;         }
; #pragma unroll
;         for (int i = 0; i < 4; ++i) cbv[i] = __builtin_nontemporal_load((const u32x2*)(proj + (t0 + 4 * tr + i) * PJ + 3072 + cc_));
	v_pk_add_f32 v[4:5], v[4:5], v[2:3]
	v_pk_add_f32 v[6:7], v[6:7], v[0:1]
	ds_read_b128 v[0:3], v148 offset:2048
	s_waitcnt lgkmcnt(0)
	v_pk_add_f32 v[4:5], v[4:5], v[2:3]
	v_pk_add_f32 v[6:7], v[6:7], v[0:1]
	ds_read_b128 v[0:3], v148 offset:2560
	s_waitcnt lgkmcnt(0)
	v_pk_add_f32 v[4:5], v[4:5], v[2:3]
	v_pk_add_f32 v[6:7], v[6:7], v[0:1]
	ds_read_b128 v[0:3], v148 offset:3072
	s_waitcnt lgkmcnt(0)
	v_pk_add_f32 v[4:5], v[4:5], v[2:3]
	v_pk_add_f32 v[6:7], v[6:7], v[0:1]
	ds_read_b128 v[0:3], v148 offset:3584
	s_waitcnt lgkmcnt(0)
	v_pk_add_f32 v[0:1], v[6:7], v[0:1]
	s_nop 0
	v_mul_f32_e32 v0, 0.5, v0
	v_mul_f32_e32 v0, 0x3fb8aa3b, v0
	v_pk_add_f32 v[2:3], v[4:5], v[2:3]
	v_exp_f32_e32 v4, v0
	v_mul_f32_e32 v0, 0.5, v1
	v_mul_f32_e32 v0, 0x3fb8aa3b, v0
	v_exp_f32_e32 v5, v0
	v_mul_f32_e32 v0, 0.5, v2
	v_mul_f32_e32 v0, 0x3fb8aa3b, v0
	v_exp_f32_e32 v2, v0
	v_mul_f32_e32 v0, 0.5, v3
	v_mul_f32_e32 v0, 0x3fb8aa3b, v0
	v_exp_f32_e32 v3, v0
	s_waitcnt vmcnt(15)
	v_lshlrev_b32_e32 v0, 16, v54
	v_and_b32_e32 v1, 0xffff0000, v54
	v_mul_f32_e32 v0, v4, v0
	v_mul_f32_e32 v1, v5, v1
	v_cvt_pk_bf16_f32 v0, v0, v1
	v_lshlrev_b32_e32 v1, 16, v55
	v_mul_f32_e32 v1, v2, v1
	v_and_b32_e32 v6, 0xffff0000, v55
	v_mul_f32_e32 v6, v3, v6
	v_cvt_pk_bf16_f32 v1, v1, v6
	ds_write_b64 v159, v[0:1] offset:34816
	s_waitcnt vmcnt(14)
	v_lshlrev_b32_e32 v0, 16, v56
	v_and_b32_e32 v1, 0xffff0000, v56
	v_mul_f32_e32 v0, v4, v0
	v_mul_f32_e32 v1, v5, v1
	v_cvt_pk_bf16_f32 v0, v0, v1
	v_lshlrev_b32_e32 v1, 16, v57
	v_mul_f32_e32 v1, v2, v1
	v_and_b32_e32 v6, 0xffff0000, v57
	v_mul_f32_e32 v6, v3, v6
	v_cvt_pk_bf16_f32 v1, v1, v6
	ds_write_b64 v159, v[0:1] offset:39168
	s_waitcnt vmcnt(13)
	v_lshlrev_b32_e32 v0, 16, v58
	v_and_b32_e32 v1, 0xffff0000, v58
	v_mul_f32_e32 v0, v4, v0
	v_mul_f32_e32 v1, v5, v1
	v_cvt_pk_bf16_f32 v0, v0, v1
	v_lshlrev_b32_e32 v1, 16, v59
	v_mul_f32_e32 v1, v2, v1
	v_and_b32_e32 v6, 0xffff0000, v59
	v_mul_f32_e32 v6, v3, v6
	v_cvt_pk_bf16_f32 v1, v1, v6
	ds_write_b64 v159, v[0:1] offset:43520
	s_waitcnt vmcnt(12)
	v_lshlrev_b32_e32 v0, 16, v60
	v_and_b32_e32 v1, 0xffff0000, v60
	v_mul_f32_e32 v0, v4, v0
	v_mul_f32_e32 v1, v5, v1
	v_cvt_pk_bf16_f32 v0, v0, v1
	v_lshlrev_b32_e32 v1, 16, v61
	v_mul_f32_e32 v1, v2, v1
	v_and_b32_e32 v6, 0xffff0000, v61
	v_mul_f32_e32 v6, v3, v6
	v_cvt_pk_bf16_f32 v1, v1, v6
	ds_write_b64 v159, v[0:1] offset:47872
	s_waitcnt vmcnt(11)
	v_lshlrev_b32_e32 v0, 16, v80
	v_and_b32_e32 v1, 0xffff0000, v80
	v_mul_f32_e32 v0, v4, v0
	v_mul_f32_e32 v1, v5, v1
	v_cvt_pk_bf16_f32 v0, v0, v1
	v_lshlrev_b32_e32 v1, 16, v81
	v_mul_f32_e32 v1, v2, v1
	v_and_b32_e32 v6, 0xffff0000, v81
	v_mul_f32_e32 v6, v3, v6
	v_cvt_pk_bf16_f32 v1, v1, v6
	ds_write_b64 v159, v[0:1] offset:52224
	s_waitcnt vmcnt(10)
	v_lshlrev_b32_e32 v0, 16, v82
	v_and_b32_e32 v1, 0xffff0000, v82
	v_mul_f32_e32 v0, v4, v0
	v_mul_f32_e32 v1, v5, v1
	v_cvt_pk_bf16_f32 v0, v0, v1
	v_lshlrev_b32_e32 v1, 16, v83
	v_mul_f32_e32 v1, v2, v1
	v_and_b32_e32 v6, 0xffff0000, v83
	v_mul_f32_e32 v6, v3, v6
	v_cvt_pk_bf16_f32 v1, v1, v6
	ds_write_b64 v159, v[0:1] offset:56576
	s_waitcnt vmcnt(9)
	v_lshlrev_b32_e32 v0, 16, v84
	v_and_b32_e32 v1, 0xffff0000, v84
	v_mul_f32_e32 v0, v4, v0
	v_mul_f32_e32 v1, v5, v1
	v_cvt_pk_bf16_f32 v0, v0, v1
	v_lshlrev_b32_e32 v1, 16, v85
	v_mul_f32_e32 v1, v2, v1
	v_and_b32_e32 v6, 0xffff0000, v85
	v_mul_f32_e32 v6, v3, v6
	v_cvt_pk_bf16_f32 v1, v1, v6
	ds_write_b64 v159, v[0:1] offset:60928
	s_waitcnt vmcnt(8)
	v_lshlrev_b32_e32 v0, 16, v86
	v_and_b32_e32 v1, 0xffff0000, v86
	v_mul_f32_e32 v0, v4, v0
	v_mul_f32_e32 v1, v5, v1
	v_cvt_pk_bf16_f32 v0, v0, v1
	v_lshlrev_b32_e32 v1, 16, v87
	v_mul_f32_e32 v1, v2, v1
	v_and_b32_e32 v2, 0xffff0000, v87
	v_mul_f32_e32 v2, v3, v2
	v_cvt_pk_bf16_f32 v1, v1, v2
	ds_write_b64 v159, v[0:1] offset:65280
	v_mov_b64_e32 v[0:1], s[44:45]
	v_mad_u64_u32 v[0:1], s[82:83], v132, s50, v[0:1]
	v_mad_i32_i24 v1, v133, s50, v1
	v_lshl_add_u64 v[0:1], v[0:1], 0, s[54:55]
	v_lshl_add_u64 v[0:1], v[0:1], 0, v[18:19]
	v_lshl_add_u64 v[0:1], v[0:1], 0, v[64:65]
	s_mov_b64 s[82:83], 0x1000
	v_lshl_add_u64 v[2:3], v[0:1], 0, s[82:83]
	v_add_co_u32_e32 v0, vcc, 0x1000, v0
	v_or_b32_e32 v65, s65, v139
	s_nop 0
	v_addc_co_u32_e32 v1, vcc, 0, v1, vcc
	global_load_dwordx2 v[130:131], v[0:1], off nt
	global_load_dwordx2 v[128:129], v[2:3], off offset:32 nt
	global_load_dwordx2 v[126:127], v[2:3], off offset:64 nt
	global_load_dwordx2 v[102:103], v[2:3], off offset:96 nt
	s_or_b64 s[82:83], s[76:77], s[48:49]
	v_lshlrev_b32_e32 v88, 1, v65
	s_and_saveexec_b64 s[48:49], s[82:83]
	s_cbranch_execz .LBB0_454
	v_lshl_add_u64 v[0:1], s[80:81], 0, v[44:45]
	v_mov_b64_e32 v[2:3], s[44:45]
	v_mad_u64_u32 v[2:3], vcc, v0, s50, v[2:3]
	v_mov_b32_e32 v0, v3
	v_mad_u64_u32 v[0:1], vcc, v1, s50, v[0:1]
	v_mov_b32_e32 v3, v0
	v_mov_b32_e32 v89, v19
	v_lshl_add_u64 v[0:1], v[2:3], 0, v[88:89]
	v_add_co_u32_e32 v0, vcc, 0x2000, v0
	s_nop 1
	v_addc_co_u32_e32 v1, vcc, 0, v1, vcc
	global_load_dwordx2 v[120:121], v[0:1], off nt
	global_load_dwordx2 v[118:119], v[0:1], off offset:2048 nt

; __device__ void phase_hgrn_out(const Params& p, LAS unsigned char* lds) {
;     ...
;         for (int i = 0; i < 4; ++i) gg[i] = __builtin_nontemporal_load((const u32x2*)(proj + (t0 + tl) * PJ + 2048 + h * 128 + 16 * (4 * hf + i) + 4 * fq));
;         const int cc_ = h * 128 + (tid & 31) * 4, tr = tid >> 5;
;         u32x2 za[6], zb[6], cbv[4];
; #pragma unroll
;         for (int r = 0; r < 6; ++r) {
;             const int tt = 4 * tr + r - 2;
;             if (tt < 0 && n == 0) { za[r] = (u32x2){0u, 0u}; zb[r] = (u32x2){0u, 0u}; }
;             else { const bf16_t* rp = proj + (size_t)((long)t0 + tt) * PJ; za[r] = __builtin_nontemporal_load((const u32x2*)(rp + 4096 + cc_)); zb[r] = __builtin_nontemporal_load((const u32x2*)(rp + 5120 + cc_)); }
;         }
; #pragma unroll
;         for (int i = 0; i < 4; ++i) cbv[i] = __builtin_nontemporal_load((const u32x2*)(proj + (t0 + 4 * tr + i) * PJ + 3072 + cc_));
;         if (item + (int)gridDim.x < 4096) HG_LOAD_PRE(item + (int)gridDim.x);
;     ...
;             const f32x4 w0 = *(const f32x4*)(p.sconv_w + cc_), w1 = *(const f32x4*)(p.sconv_w + 1024 + cc_), w2 = *(const f32x4*)(p.sconv_w + 2048 + cc_);
.LBB0_456:
	s_or_b64 exec, exec, s[48:49]
	v_lshl_add_u64 v[90:91], s[80:81], 0, v[36:37]
	v_mov_b64_e32 v[0:1], s[44:45]
	v_mad_u64_u32 v[2:3], s[48:49], v90, s50, v[0:1]
	v_mov_b32_e32 v4, v3
	v_lshl_add_u64 v[6:7], s[80:81], 0, v[48:49]
	v_mad_u64_u32 v[4:5], s[48:49], v91, s50, v[4:5]
	v_mad_u64_u32 v[8:9], s[48:49], v6, s50, v[0:1]
	v_mov_b32_e32 v3, v4
	v_mov_b32_e32 v89, v19
	v_mov_b32_e32 v6, v9
	v_lshl_add_u64 v[2:3], v[2:3], 0, v[88:89]
	v_mad_u64_u32 v[6:7], s[48:49], v7, s50, v[6:7]
	v_add_co_u32_e32 v4, vcc, s33, v2
	v_mov_b32_e32 v9, v6
	s_nop 0
	v_addc_co_u32_e32 v5, vcc, 0, v3, vcc
	v_lshl_add_u64 v[6:7], v[8:9], 0, v[88:89]
	v_add_co_u32_e32 v6, vcc, s33, v6
	s_nop 1
	v_addc_co_u32_e32 v7, vcc, 0, v7, vcc
	global_load_dwordx2 v[116:117], v[4:5], off nt
	global_load_dwordx2 v[112:113], v[4:5], off offset:2048 nt
	global_load_dwordx2 v[106:107], v[6:7], off nt
	global_load_dwordx2 v[98:99], v[6:7], off offset:2048 nt
	v_lshl_add_u64 v[4:5], s[80:81], 0, v[50:51]
	v_mad_u64_u32 v[6:7], s[48:49], v4, s50, v[0:1]
	v_mov_b32_e32 v4, v7
	v_mad_u64_u32 v[4:5], s[48:49], v5, s50, v[4:5]
	v_mov_b32_e32 v7, v4
	v_lshl_add_u64 v[4:5], v[6:7], 0, v[88:89]
	v_lshl_add_u64 v[6:7], s[80:81], 0, v[52:53]
	v_mad_u64_u32 v[0:1], s[48:49], v6, s50, v[0:1]
	v_mov_b32_e32 v6, v1
	v_mad_u64_u32 v[6:7], s[48:49], v7, s50, v[6:7]
	v_add_co_u32_e32 v4, vcc, s33, v4
	v_mov_b32_e32 v1, v6
	s_nop 0
	v_addc_co_u32_e32 v5, vcc, 0, v5, vcc
	v_lshl_add_u64 v[0:1], v[0:1], 0, v[88:89]
	v_add_co_u32_e32 v0, vcc, s33, v0
	s_movk_i32 s48, 0x1000
	s_nop 0
	v_addc_co_u32_e32 v1, vcc, 0, v1, vcc
	global_load_dwordx2 v[114:115], v[4:5], off nt
	global_load_dwordx2 v[110:111], v[4:5], off offset:2048 nt
	global_load_dwordx2 v[104:105], v[0:1], off nt
	global_load_dwordx2 v[100:101], v[0:1], off offset:2048 nt
	v_add_co_u32_e32 v0, vcc, s48, v2
	s_nop 1
	v_addc_co_u32_e32 v1, vcc, 0, v3, vcc
	v_add_co_u32_e32 v4, vcc, s92, v2
	s_nop 1
	v_addc_co_u32_e32 v5, vcc, 0, v3, vcc
	v_add_co_u32_e32 v6, vcc, 0x7000, v2
	s_nop 1
	v_addc_co_u32_e32 v7, vcc, 0, v3, vcc
	v_add_co_u32_e32 v2, vcc, 0xa000, v2
	s_nop 1
	v_addc_co_u32_e32 v3, vcc, 0, v3, vcc
	global_load_dwordx2 v[108:109], v[0:1], off offset:2048 nt
	global_load_dwordx2 v[96:97], v[4:5], off offset:2048 nt
	global_load_dwordx2 v[94:95], v[6:7], off offset:2048 nt
	global_load_dwordx2 v[92:93], v[2:3], off offset:2048 nt
	v_lshlrev_b32_e32 v224, 2, v65
	s_nop 0
	global_load_dwordx4 v[226:229], v224, s[62:63] offset:-4096
	global_load_dwordx4 v[230:233], v224, s[62:63]
	global_load_dwordx4 v[234:237], v224, s[84:85]
	s_load_dword s48, s[96:97], 0x0
	s_waitcnt lgkmcnt(0)
	s_add_i32 s78, s48, s78
	s_cmpk_gt_i32 s78, 0xfff
	s_cselect_b64 s[80:81], -1, 0
	s_and_b64 vcc, exec, s[80:81]
	s_cbranch_vccnz .LBB0_458
	s_ashr_i32 s48, s78, 10
	s_lshl_b32 s79, s78, 6
	s_ashr_i32 s49, s48, 31
	s_and_b32 s79, s79, 0x1fc0
	s_and_b32 s65, s78, 0x380
	s_lshl_b64 s[48:49], s[48:49], 13
	v_add_u32_e32 v0, s79, v16
	v_mov_b32_e32 v1, v19
	v_lshl_add_u64 v[0:1], s[48:49], 0, v[0:1]
	s_lshl_b32 s48, s65, 2
	s_mov_b32 s49, s55
	v_mov_b64_e32 v[8:9], s[44:45]
	v_lshl_add_u64 v[2:3], v[40:41], 0, s[48:49]
	v_mad_u64_u32 v[8:9], s[48:49], v0, s50, v[8:9]
	v_lshlrev_b64 v[4:5], 12, v[0:1]
	v_mad_i32_i24 v9, v1, s50, v9
	s_lshl_b32 s48, s65, 1
	s_mov_b32 s49, s55
	v_lshl_add_u64 v[0:1], v[8:9], 0, s[48:49]
	v_mov_b32_e32 v67, v19
	v_or_b32_e32 v8, 0x1000, v4
	v_mov_b32_e32 v9, v5
	v_lshl_add_u64 v[6:7], v[2:3], 0, v[4:5]
	v_lshl_add_u64 v[0:1], v[0:1], 0, v[66:67]
	v_lshl_add_u64 v[8:9], v[2:3], 0, v[8:9]
	global_load_dwordx2 v[20:21], v[6:7], off nt
	global_load_dword v17, v[0:1], off nt
	global_load_dword v67, v[0:1], off offset:2048 nt
	global_load_dwordx2 v[22:23], v[8:9], off nt
	s_mov_b64 s[0:1], 0x3000
	v_add_co_u32_e32 v8, vcc, s50, v0
	v_lshl_add_u64 v[6:7], v[0:1], 0, s[0:1]
	s_nop 0
	v_addc_co_u32_e32 v9, vcc, 0, v1, vcc
	s_mov_b64 s[0:1], 0x6000
	v_or_b32_e32 v10, 0x2000, v4
	v_mov_b32_e32 v11, v5
	v_lshl_add_u64 v[12:13], v[0:1], 0, s[0:1]
	v_add_co_u32_e32 v14, vcc, s51, v0
	s_mov_b64 s[0:1], 0x9000
	v_lshl_add_u64 v[10:11], v[2:3], 0, v[10:11]
	v_addc_co_u32_e32 v15, vcc, 0, v1, vcc
	global_load_dword v134, v[8:9], off nt
	global_load_dwordx2 v[24:25], v[10:11], off nt
	global_load_dword v135, v[14:15], off nt
	global_load_dword v136, v[12:13], off offset:2048 nt
	global_load_dword v137, v[6:7], off offset:2048 nt
	v_lshl_add_u64 v[8:9], v[0:1], 0, s[0:1]
	s_mov_b32 s0, 0x9000
	v_or_b32_e32 v6, 0x3000, v4
	v_mov_b32_e32 v7, v5
	v_add_co_u32_e32 v10, vcc, s0, v0
	v_lshl_add_u64 v[6:7], v[2:3], 0, v[6:7]
	s_nop 0
	v_addc_co_u32_e32 v11, vcc, 0, v1, vcc
	v_or_b32_e32 v12, 0x4000, v4
	v_mov_b32_e32 v13, v5
	v_lshl_add_u64 v[12:13], v[2:3], 0, v[12:13]
	global_load_dwordx2 v[26:27], v[6:7], off nt
	global_load_dword v138, v[10:11], off nt
	global_load_dwordx2 v[28:29], v[12:13], off nt
	global_load_dword v140, v[8:9], off offset:2048 nt
	s_mov_b64 s[0:1], 0xc000
	v_add_co_u32_e32 v8, vcc, s93, v0
	v_lshl_add_u64 v[6:7], v[0:1], 0, s[0:1]
	s_nop 0
	v_addc_co_u32_e32 v9, vcc, 0, v1, vcc
	v_or_b32_e32 v10, 0x5000, v4
	v_mov_b32_e32 v11, v5
	s_mov_b64 s[0:1], 0xf000
	v_lshl_add_u64 v[10:11], v[2:3], 0, v[10:11]
	global_load_dword v141, v[8:9], off nt
	global_load_dwordx2 v[30:31], v[10:11], off nt
	global_load_dword v142, v[6:7], off offset:2048 nt
	v_lshl_add_u64 v[6:7], v[0:1], 0, s[0:1]
	s_mov_b32 s0, 0xf000
	v_add_co_u32_e32 v8, vcc, s0, v0
	global_load_dword v143, v[6:7], off offset:2048 nt
	s_nop 0
	v_addc_co_u32_e32 v9, vcc, 0, v1, vcc
	v_or_b32_e32 v6, 0x6000, v4
	v_mov_b32_e32 v7, v5
	v_lshl_add_u64 v[6:7], v[2:3], 0, v[6:7]
	global_load_dword v144, v[8:9], off nt
	global_load_dwordx2 v[32:33], v[6:7], off nt
	v_add_co_u32_e32 v8, vcc, s52, v0
	v_or_b32_e32 v4, 0x7000, v4
	s_mov_b64 s[0:1], 0x12000
	v_addc_co_u32_e32 v9, vcc, 0, v1, vcc
	v_lshl_add_u64 v[2:3], v[2:3], 0, v[4:5]
	v_lshl_add_u64 v[6:7], v[0:1], 0, s[0:1]
	global_load_dword v149, v[8:9], off nt
	global_load_dword v150, v[6:7], off offset:2048 nt
	global_load_dwordx2 v[38:39], v[2:3], off nt
	v_lshl_add_u64 v[2:3], v[0:1], 0, s[94:95]
	v_add_co_u32_e32 v0, vcc, s53, v0
	s_ashr_i32 s79, s78, 31
	s_nop 0
	v_addc_co_u32_e32 v1, vcc, 0, v1, vcc
	s_lshl_b64 s[48:49], s[78:79], 15
	global_load_dword v152, v[0:1], off nt
	global_load_dword v153, v[2:3], off offset:2048 nt
	v_lshl_add_u64 v[0:1], v[42:43], 0, s[48:49]
	v_mov_b32_e32 v69, v19
	v_lshl_add_u64 v[2:3], v[0:1], 0, v[68:69]
	v_mov_b32_e32 v71, v19
	v_add_co_u32_e32 v6, vcc, s33, v2
	v_lshl_add_u64 v[4:5], v[0:1], 0, v[70:71]
	s_nop 0
	v_addc_co_u32_e32 v7, vcc, 0, v3, vcc
	v_mov_b32_e32 v73, v19
	v_lshl_add_u64 v[8:9], v[0:1], 0, v[72:73]
	global_load_dwordx2 v[54:55], v[2:3], off nt
	global_load_dwordx2 v[56:57], v[4:5], off nt
	global_load_dwordx2 v[58:59], v[6:7], off nt
	global_load_dwordx2 v[60:61], v[8:9], off nt
	v_add_co_u32_e32 v4, vcc, 0x4000, v2
	v_mov_b32_e32 v75, v19
	s_nop 0
	v_addc_co_u32_e32 v5, vcc, 0, v3, vcc
	v_add_co_u32_e32 v2, vcc, 0x6000, v2
	v_mov_b32_e32 v77, v19
	v_lshl_add_u64 v[6:7], v[0:1], 0, v[74:75]
	v_addc_co_u32_e32 v3, vcc, 0, v3, vcc
	v_lshl_add_u64 v[0:1], v[0:1], 0, v[76:77]
	global_load_dwordx2 v[80:81], v[4:5], off nt
	global_load_dwordx2 v[82:83], v[6:7], off nt
	global_load_dwordx2 v[84:85], v[2:3], off nt
	global_load_dwordx2 v[86:87], v[0:1], off nt

;     __device__ __forceinline__ void operator()(Acc& acc, const Unit& u, int wr, int wc, int fr, int fq) const {
;         const int row0 = u.pm * 256 + wr * 64 + fr, c0 = u.pn * 128 + wc * 32 + 8 * fq;
; #pragma unroll
;         for (int ai = 0; ai < 2; ++ai) {
;             float rs[4];
; #pragma unroll
;             for (int m = 0; m < 4; ++m) rs[m] = rsqrtf(rss[row0 + ai * 128 + m * 16] * (1.0f / D) + EPS);
;             const int blk = u.pm * 4 + ai * 2 + wr;
;             unsigned pk[4][4];
; #pragma unroll
;             for (int n = 0; n < 2; ++n) {
;                 const f32x4 w0 = *(const f32x4*)(cw + c0 + 4 * n), w1 = *(const f32x4*)(cw + FF + c0 + 4 * n), w2 = *(const f32x4*)(cw + 2 * FF + c0 + 4 * n), bb = *(const f32x4*)(cbias + c0 + 4 * n);
; #pragma unroll
;                 for (int jp = 0; jp < 2; ++jp) {
;                     const f32x2 w0p = {w0[2 * jp], w0[2 * jp + 1]}, w1p = {w1[2 * jp], w1[2 * jp + 1]}, w2p = {w2[2 * jp], w2[2 * jp + 1]}, bbp = {bb[2 * jp], bb[2 * jp + 1]};
;                     f32x2 gm[4], r1[4], r2[4];
; #pragma unroll
;                     for (int m = 0; m < 4; ++m) {
;                         gm[m] = (f32x2){acc[ai][0][m][n][2 * jp], acc[ai][0][m][n][2 * jp + 1]} * rs[m];
;                         r1[m].x = __int_as_float(__builtin_amdgcn_update_dpp(0, __float_as_int(gm[m].x), 0x121, 0xF, 0xF, false));
;                         r1[m].y = __int_as_float(__builtin_amdgcn_update_dpp(0, __float_as_int(gm[m].y), 0x121, 0xF, 0xF, false));
;                         r2[m].x = __int_as_float(__builtin_amdgcn_update_dpp(0, __float_as_int(gm[m].x), 0x122, 0xF, 0xF, false));
;                         r2[m].y = __int_as_float(__builtin_amdgcn_update_dpp(0, __float_as_int(gm[m].y), 0x122, 0xF, 0xF, false));
;                     }
; #pragma unroll
;                     for (int m = 0; m < 4; ++m) {
;                         const f32x2 q1 = m >= 1 ? r1[m >= 1 ? m - 1 : 0] : (f32x2){0.f, 0.f}, q2 = m >= 1 ? r2[m >= 1 ? m - 1 : 0] : (f32x2){0.f, 0.f};
;                         f32x2 p1, p2;
;                         p1.x = (fr >= 1) ? r1[m].x : q1.x; p1.y = (fr >= 1) ? r1[m].y : q1.y;
;                         p2.x = (fr >= 2) ? r2[m].x : q2.x; p2.y = (fr >= 2) ? r2[m].y : q2.y;
;                         const f32x2 a = w2p * gm[m] + (w1p * p1 + (w0p * p2 + bbp));
;     ...
;             if (fr < 2) {
.LBB0_864:
	v_lshl_add_u32 v204, s58, 8, v153
	v_lshl_or_b32 v205, s59, 7, v187
	v_readlane_b32 s88, v250, 2
	v_readlane_b32 s89, v250, 3
	v_readlane_b32 s90, v250, 4
	v_readlane_b32 s91, v250, 5
	v_lshlrev_b32_e32 v207, 2, v204
	v_lshlrev_b32_e32 v216, 1, v205
	v_lshlrev_b32_e32 v205, 2, v205
	s_lshl_b32 s14, s58, 2
	s_add_i32 s14, s14, s33
	s_nop 0
	global_load_dword v172, v207, s[22:23]
	global_load_dword v173, v207, s[22:23] offset:64
	global_load_dword v174, v207, s[22:23] offset:128
	global_load_dword v175, v207, s[22:23] offset:192
	global_load_dword v178, v207, s[22:23] offset:512
	global_load_dword v179, v207, s[22:23] offset:576
	global_load_dword v180, v207, s[22:23] offset:640
	global_load_dword v181, v207, s[22:23] offset:704
	global_load_dwordx4 v[128:131], v205, s[88:89]
	global_load_dwordx4 v[132:135], v205, s[38:39]
	global_load_dwordx4 v[136:139], v205, s[40:41]
	global_load_dwordx4 v[140:143], v205, s[90:91]
	global_load_dwordx4 v[196:199], v205, s[88:89] offset:16
	global_load_dwordx4 v[200:203], v205, s[38:39] offset:16
	global_load_dwordx4 v[208:211], v205, s[40:41] offset:16
	global_load_dwordx4 v[212:215], v205, s[90:91] offset:16
	v_mad_u32_u24 v207, v204, s81, v216
	s_waitcnt vmcnt(0)
	v_fmamk_f32 v172, v172, 0x3a000000, v194
	v_fmamk_f32 v173, v173, 0x3a000000, v194
	v_fmamk_f32 v174, v174, 0x3a000000, v194
	v_fmamk_f32 v175, v175, 0x3a000000, v194
	v_fmamk_f32 v178, v178, 0x3a000000, v194
	v_fmamk_f32 v179, v179, 0x3a000000, v194
	v_fmamk_f32 v180, v180, 0x3a000000, v194
	v_fmamk_f32 v181, v181, 0x3a000000, v194
	v_rsq_f32_e32 v172, v172
	v_rsq_f32_e32 v173, v173
	v_rsq_f32_e32 v174, v174
	v_rsq_f32_e32 v175, v175
	v_rsq_f32_e32 v178, v178
	v_rsq_f32_e32 v179, v179
	v_rsq_f32_e32 v180, v180
	v_rsq_f32_e32 v181, v181
	v_mul_f32_e32 v128, s42, v128
	v_mul_f32_e32 v129, s42, v129
	v_mul_f32_e32 v130, s42, v130
	v_mul_f32_e32 v131, s42, v131
	v_mul_f32_e32 v132, s42, v132
	v_mul_f32_e32 v133, s42, v133
	v_mul_f32_e32 v134, s42, v134
	v_mul_f32_e32 v135, s42, v135
	v_mul_f32_e32 v136, s42, v136
	v_mul_f32_e32 v137, s42, v137
	v_mul_f32_e32 v138, s42, v138
	v_mul_f32_e32 v139, s42, v139
	v_mul_f32_e32 v140, s42, v140
	v_mul_f32_e32 v141, s42, v141
	v_mul_f32_e32 v142, s42, v142
	v_mul_f32_e32 v143, s42, v143
	v_mul_f32_e32 v196, s42, v196
	v_mul_f32_e32 v197, s42, v197
	v_mul_f32_e32 v198, s42, v198
	v_mul_f32_e32 v199, s42, v199
	v_mul_f32_e32 v200, s42, v200
	v_mul_f32_e32 v201, s42, v201
	v_mul_f32_e32 v202, s42, v202
	v_mul_f32_e32 v203, s42, v203
	v_mul_f32_e32 v208, s42, v208
	v_mul_f32_e32 v209, s42, v209
	v_mul_f32_e32 v210, s42, v210
	v_mul_f32_e32 v211, s42, v211
	v_mul_f32_e32 v212, s42, v212
	v_mul_f32_e32 v213, s42, v213
	v_mul_f32_e32 v214, s42, v214
	v_mul_f32_e32 v215, s42, v215
	v_mul_f32_e32 v182, 0xbf317218, v172
	v_mul_f32_e32 v183, 0xbf317218, v173
	v_mul_f32_e32 v184, 0xbf317218, v174
	v_mul_f32_e32 v185, 0xbf317218, v175
	v_mul_f32_e32 v186, 0xbf317218, v178
	v_mul_f32_e32 v188, 0xbf317218, v179
	v_mul_f32_e32 v190, 0xbf317218, v180
	v_mul_f32_e32 v192, 0xbf317218, v181
	v_cndmask_b32_e64 v164, 0, v132, s[4:5]
	v_cndmask_b32_e64 v168, 0, v128, s[8:9]
	v_cndmask_b32_e64 v165, 0, v133, s[4:5]
	v_cndmask_b32_e64 v169, 0, v129, s[8:9]
	v_cndmask_b32_e64 v166, 0, v134, s[4:5]
	v_cndmask_b32_e64 v170, 0, v130, s[8:9]
	v_cndmask_b32_e64 v167, 0, v135, s[4:5]
	v_cndmask_b32_e64 v171, 0, v131, s[8:9]
	v_mul_f32_e32 v84, v84, v172
	v_mul_f32_e32 v85, v85, v172
	v_mul_f32_e32 v86, v86, v172
	v_mul_f32_e32 v87, v87, v172
	v_mul_f32_e32 v124, v124, v173
	v_mul_f32_e32 v125, v125, v173
	v_mul_f32_e32 v126, v126, v173
	v_mul_f32_e32 v127, v127, v173
	v_mul_f32_e32 v120, v120, v174
	v_mul_f32_e32 v121, v121, v174
	v_mul_f32_e32 v122, v122, v174
	v_mul_f32_e32 v123, v123, v174
	v_mul_f32_e32 v68, v68, v175
	v_mul_f32_e32 v69, v69, v175
	v_mul_f32_e32 v70, v70, v175
	v_mul_f32_e32 v71, v71, v175
	v_mul_f32_e32 v232, v76, v172
	v_mul_f32_e32 v233, v77, v172
	v_mul_f32_e32 v234, v78, v172
	v_mul_f32_e32 v235, v79, v172
	s_add_i32 s15, s14, 0
	v_lshl_add_u32 v228, s15, 1, v152
	v_lshl_add_u32 v229, s15, 1, v154
	v_mad_u32_u24 v230, v228, s83, v205
	v_mad_u32_u24 v231, v229, s83, v205
	s_mov_b64 exec, s[8:9]
	global_store_dwordx4 v230, v[84:87], s[86:87]
	global_store_dwordx4 v230, v[232:235], s[28:29]
	s_mov_b64 exec, s[10:11]
	global_store_dwordx4 v231, v[68:71], s[30:31]
	s_mov_b64 exec, -1
	v_fma_f32 v216, v136, v84, v140
	v_fma_f32 v217, v137, v85, v141
	v_fma_f32 v218, v138, v86, v142
	v_fma_f32 v219, v139, v87, v143
	v_fma_f32 v220, v136, v124, v140
	v_fma_f32 v221, v137, v125, v141
	v_fma_f32 v222, v138, v126, v142
	v_fma_f32 v223, v139, v127, v143
	v_fma_f32 v224, v136, v120, v140
	v_fma_f32 v225, v137, v121, v141
	v_fma_f32 v226, v138, v122, v142
	v_fma_f32 v227, v139, v123, v143
	v_fma_f32 v228, v136, v68, v140
	v_fma_f32 v229, v137, v69, v141
	v_fma_f32 v230, v138, v70, v142
	v_fma_f32 v231, v139, v71, v143
	v_fmac_f32_dpp v216, v84, v132 row_shr:1 row_mask:0xf bank_mask:0xf
	v_fmac_f32_dpp v217, v85, v133 row_shr:1 row_mask:0xf bank_mask:0xf
	v_fmac_f32_dpp v218, v86, v134 row_shr:1 row_mask:0xf bank_mask:0xf
	v_fmac_f32_dpp v219, v87, v135 row_shr:1 row_mask:0xf bank_mask:0xf
	v_fmac_f32_dpp v220, v124, v132 row_shr:1 row_mask:0xf bank_mask:0xf
	v_fmac_f32_dpp v221, v125, v133 row_shr:1 row_mask:0xf bank_mask:0xf
	v_fmac_f32_dpp v222, v126, v134 row_shr:1 row_mask:0xf bank_mask:0xf
	v_fmac_f32_dpp v223, v127, v135 row_shr:1 row_mask:0xf bank_mask:0xf
	v_fmac_f32_dpp v224, v120, v132 row_shr:1 row_mask:0xf bank_mask:0xf
	v_fmac_f32_dpp v225, v121, v133 row_shr:1 row_mask:0xf bank_mask:0xf
; __device__ __forceinline__ unsigned cvt_pk_bf16(float lo, float hi) { unsigned r; asm volatile("v_cvt_pk_bf16_f32 %0, %1, %2" : "=v"(r) : "v"(lo), "v"(hi)); return r; }
;     __device__ __forceinline__ void operator()(Acc& acc, const Unit& u, int wr, int wc, int fr, int fq) const {
;     ...
;                     for (int m = 0; m < 4; ++m) {
;                         const f32x2 q1 = m >= 1 ? r1[m >= 1 ? m - 1 : 0] : (f32x2){0.f, 0.f}, q2 = m >= 1 ? r2[m >= 1 ? m - 1 : 0] : (f32x2){0.f, 0.f};
;                         f32x2 p1, p2;
;                         p1.x = (fr >= 1) ? r1[m].x : q1.x; p1.y = (fr >= 1) ? r1[m].y : q1.y;
;                         p2.x = (fr >= 2) ? r2[m].x : q2.x; p2.y = (fr >= 2) ? r2[m].y : q2.y;
;                         const f32x2 a = w2p * gm[m] + (w1p * p1 + (w0p * p2 + bbp));
;                         const f32x2 na = a * (-1.4426950408889634f);
;                         f32x2 den; den.x = __builtin_amdgcn_exp2f(na.x); den.y = __builtin_amdgcn_exp2f(na.y);
;                         den = den + 1.0f;
;                         f32x2 rc; rc.x = __builtin_amdgcn_rcpf(den.x); rc.y = __builtin_amdgcn_rcpf(den.y);
;                         const f32x2 up = (f32x2){acc[ai][1][m][n][2 * jp], acc[ai][1][m][n][2 * jp + 1]} * rs[m];
;                         const f32x2 ov = (a * rc) * up;
;                         pk[m][2 * n + jp] = cvt_pk_bf16(ov.x, ov.y);
	v_fmac_f32_dpp v226, v122, v134 row_shr:1 row_mask:0xf bank_mask:0xf
	v_fmac_f32_dpp v227, v123, v135 row_shr:1 row_mask:0xf bank_mask:0xf
	v_fmac_f32_dpp v228, v68, v132 row_shr:1 row_mask:0xf bank_mask:0xf
	v_fmac_f32_dpp v229, v69, v133 row_shr:1 row_mask:0xf bank_mask:0xf
	v_fmac_f32_dpp v230, v70, v134 row_shr:1 row_mask:0xf bank_mask:0xf
	v_fmac_f32_dpp v231, v71, v135 row_shr:1 row_mask:0xf bank_mask:0xf
	v_fmac_f32_dpp v216, v84, v128 row_shr:2 row_mask:0xf bank_mask:0xf
	v_fmac_f32_dpp v217, v85, v129 row_shr:2 row_mask:0xf bank_mask:0xf
	v_fmac_f32_dpp v218, v86, v130 row_shr:2 row_mask:0xf bank_mask:0xf
	v_fmac_f32_dpp v219, v87, v131 row_shr:2 row_mask:0xf bank_mask:0xf
	v_fmac_f32_dpp v220, v124, v128 row_shr:2 row_mask:0xf bank_mask:0xf
	v_fmac_f32_dpp v221, v125, v129 row_shr:2 row_mask:0xf bank_mask:0xf
	v_fmac_f32_dpp v222, v126, v130 row_shr:2 row_mask:0xf bank_mask:0xf
	v_fmac_f32_dpp v223, v127, v131 row_shr:2 row_mask:0xf bank_mask:0xf
	v_fmac_f32_dpp v224, v120, v128 row_shr:2 row_mask:0xf bank_mask:0xf
	v_fmac_f32_dpp v225, v121, v129 row_shr:2 row_mask:0xf bank_mask:0xf
	v_fmac_f32_dpp v226, v122, v130 row_shr:2 row_mask:0xf bank_mask:0xf
	v_fmac_f32_dpp v227, v123, v131 row_shr:2 row_mask:0xf bank_mask:0xf
	v_fmac_f32_dpp v228, v68, v128 row_shr:2 row_mask:0xf bank_mask:0xf
	v_fmac_f32_dpp v229, v69, v129 row_shr:2 row_mask:0xf bank_mask:0xf
	v_fmac_f32_dpp v230, v70, v130 row_shr:2 row_mask:0xf bank_mask:0xf
	v_fmac_f32_dpp v231, v71, v131 row_shr:2 row_mask:0xf bank_mask:0xf
	v_fmac_f32_dpp v220, v84, v164 row_ror:1 row_mask:0xf bank_mask:0xf
	v_fmac_f32_dpp v221, v85, v165 row_ror:1 row_mask:0xf bank_mask:0xf
	v_fmac_f32_dpp v222, v86, v166 row_ror:1 row_mask:0xf bank_mask:0xf
	v_fmac_f32_dpp v223, v87, v167 row_ror:1 row_mask:0xf bank_mask:0xf
	v_fmac_f32_dpp v224, v124, v164 row_ror:1 row_mask:0xf bank_mask:0xf
	v_fmac_f32_dpp v225, v125, v165 row_ror:1 row_mask:0xf bank_mask:0xf
	v_fmac_f32_dpp v226, v126, v166 row_ror:1 row_mask:0xf bank_mask:0xf
	v_fmac_f32_dpp v227, v127, v167 row_ror:1 row_mask:0xf bank_mask:0xf
	v_fmac_f32_dpp v228, v120, v164 row_ror:1 row_mask:0xf bank_mask:0xf
	v_fmac_f32_dpp v229, v121, v165 row_ror:1 row_mask:0xf bank_mask:0xf
	v_fmac_f32_dpp v230, v122, v166 row_ror:1 row_mask:0xf bank_mask:0xf
	v_fmac_f32_dpp v231, v123, v167 row_ror:1 row_mask:0xf bank_mask:0xf
	v_fmac_f32_dpp v220, v84, v168 row_ror:2 row_mask:0xf bank_mask:0xf
	v_fmac_f32_dpp v221, v85, v169 row_ror:2 row_mask:0xf bank_mask:0xf
	v_fmac_f32_dpp v222, v86, v170 row_ror:2 row_mask:0xf bank_mask:0xf
	v_fmac_f32_dpp v223, v87, v171 row_ror:2 row_mask:0xf bank_mask:0xf
	v_fmac_f32_dpp v224, v124, v168 row_ror:2 row_mask:0xf bank_mask:0xf
	v_fmac_f32_dpp v225, v125, v169 row_ror:2 row_mask:0xf bank_mask:0xf
	v_fmac_f32_dpp v226, v126, v170 row_ror:2 row_mask:0xf bank_mask:0xf
	v_fmac_f32_dpp v227, v127, v171 row_ror:2 row_mask:0xf bank_mask:0xf
	v_fmac_f32_dpp v228, v120, v168 row_ror:2 row_mask:0xf bank_mask:0xf
	v_fmac_f32_dpp v229, v121, v169 row_ror:2 row_mask:0xf bank_mask:0xf
	v_fmac_f32_dpp v230, v122, v170 row_ror:2 row_mask:0xf bank_mask:0xf
	v_fmac_f32_dpp v231, v123, v171 row_ror:2 row_mask:0xf bank_mask:0xf
	v_exp_f32_e32 v84, v216
	v_exp_f32_e32 v85, v217
	v_exp_f32_e32 v86, v218
	v_exp_f32_e32 v87, v219
	v_exp_f32_e32 v124, v220
	v_exp_f32_e32 v125, v221
	v_exp_f32_e32 v126, v222
	v_exp_f32_e32 v127, v223
	v_exp_f32_e32 v120, v224
	v_exp_f32_e32 v121, v225
	v_exp_f32_e32 v122, v226
	v_exp_f32_e32 v123, v227
	v_exp_f32_e32 v68, v228
	v_exp_f32_e32 v69, v229
	v_exp_f32_e32 v70, v230
	v_exp_f32_e32 v71, v231
	v_add_f32_e32 v84, 1.0, v84
	v_add_f32_e32 v85, 1.0, v85
	v_add_f32_e32 v86, 1.0, v86
	v_add_f32_e32 v87, 1.0, v87
	v_add_f32_e32 v124, 1.0, v124
	v_add_f32_e32 v125, 1.0, v125
	v_add_f32_e32 v126, 1.0, v126
	v_add_f32_e32 v127, 1.0, v127
	v_add_f32_e32 v120, 1.0, v120
	v_add_f32_e32 v121, 1.0, v121
	v_add_f32_e32 v122, 1.0, v122
	v_add_f32_e32 v123, 1.0, v123
	v_add_f32_e32 v68, 1.0, v68
	v_add_f32_e32 v69, 1.0, v69
	v_add_f32_e32 v70, 1.0, v70
	v_add_f32_e32 v71, 1.0, v71
	v_rcp_f32_e32 v84, v84
	v_rcp_f32_e32 v85, v85
	v_rcp_f32_e32 v86, v86
	v_rcp_f32_e32 v87, v87
	v_rcp_f32_e32 v124, v124
	v_rcp_f32_e32 v125, v125
	v_rcp_f32_e32 v126, v126
	v_rcp_f32_e32 v127, v127
	v_rcp_f32_e32 v120, v120
	v_rcp_f32_e32 v121, v121
	v_rcp_f32_e32 v122, v122
	v_rcp_f32_e32 v123, v123
	v_rcp_f32_e32 v68, v68
	v_rcp_f32_e32 v69, v69
	v_rcp_f32_e32 v70, v70
	v_rcp_f32_e32 v71, v71
	v_mul_f32_e32 v76, v76, v182
	v_mul_f32_e32 v77, v77, v182
	v_mul_f32_e32 v78, v78, v182
	v_mul_f32_e32 v79, v79, v182
	v_mul_f32_e32 v116, v116, v183
	v_mul_f32_e32 v117, v117, v183
	v_mul_f32_e32 v118, v118, v183
	v_mul_f32_e32 v119, v119, v183
	v_mul_f32_e32 v112, v112, v184
	v_mul_f32_e32 v113, v113, v184
	v_mul_f32_e32 v114, v114, v184
	v_mul_f32_e32 v115, v115, v184
	v_mul_f32_e32 v108, v108, v185
	v_mul_f32_e32 v109, v109, v185
	v_mul_f32_e32 v110, v110, v185
	v_mul_f32_e32 v111, v111, v185
	v_mul_f32_e32 v216, v216, v84
	v_mul_f32_e32 v217, v217, v85
	v_mul_f32_e32 v218, v218, v86
	v_mul_f32_e32 v219, v219, v87
	v_mul_f32_e32 v220, v220, v124
	v_mul_f32_e32 v221, v221, v125
	v_mul_f32_e32 v222, v222, v126
	v_mul_f32_e32 v223, v223, v127
	v_mul_f32_e32 v224, v224, v120
	v_mul_f32_e32 v225, v225, v121
	v_mul_f32_e32 v226, v226, v122
	v_mul_f32_e32 v227, v227, v123
	v_mul_f32_e32 v228, v228, v68
	v_mul_f32_e32 v229, v229, v69
	v_mul_f32_e32 v230, v230, v70
	v_mul_f32_e32 v231, v231, v71
	v_mul_f32_e32 v216, v216, v76
	v_mul_f32_e32 v217, v217, v77
	v_mul_f32_e32 v218, v218, v78
	v_mul_f32_e32 v219, v219, v79
	v_mul_f32_e32 v220, v220, v116
; __device__ __forceinline__ unsigned cvt_pk_bf16(float lo, float hi) { unsigned r; asm volatile("v_cvt_pk_bf16_f32 %0, %1, %2" : "=v"(r) : "v"(lo), "v"(hi)); return r; }
;     __device__ __forceinline__ void operator()(Acc& acc, const Unit& u, int wr, int wc, int fr, int fq) const {
;     ...
;                         const f32x2 a = w2p * gm[m] + (w1p * p1 + (w0p * p2 + bbp));
;                         const f32x2 na = a * (-1.4426950408889634f);
;                         f32x2 den; den.x = __builtin_amdgcn_exp2f(na.x); den.y = __builtin_amdgcn_exp2f(na.y);
;                         den = den + 1.0f;
;                         f32x2 rc; rc.x = __builtin_amdgcn_rcpf(den.x); rc.y = __builtin_amdgcn_rcpf(den.y);
;                         const f32x2 up = (f32x2){acc[ai][1][m][n][2 * jp], acc[ai][1][m][n][2 * jp + 1]} * rs[m];
;                         const f32x2 ov = (a * rc) * up;
;                         pk[m][2 * n + jp] = cvt_pk_bf16(ov.x, ov.y);
;     ...
;             if (fr < 2) {
;                 const size_t o = ((size_t)blk * 2 + fr) * FF + c0;
;                 *(f32x4*)(gf + o) = acc[ai][0][0][0] * rs[0]; *(f32x4*)(gf + o + 4) = acc[ai][0][0][1] * rs[0];
;                 *(f32x4*)(uf + o) = acc[ai][1][0][0] * rs[0]; *(f32x4*)(uf + o + 4) = acc[ai][1][0][1] * rs[0];
;             }
;             if (fr >= 14) {
;                 const size_t o = ((size_t)blk * 2 + (fr - 14)) * FF + c0;
;                 *(f32x4*)(gl + o) = acc[ai][0][3][0] * rs[3]; *(f32x4*)(gl + o + 4) = acc[ai][0][3][1] * rs[3];
	v_mul_f32_e32 v221, v221, v117
	v_mul_f32_e32 v222, v222, v118
	v_mul_f32_e32 v223, v223, v119
	v_mul_f32_e32 v224, v224, v112
	v_mul_f32_e32 v225, v225, v113
	v_mul_f32_e32 v226, v226, v114
	v_mul_f32_e32 v227, v227, v115
	v_mul_f32_e32 v228, v228, v108
	v_mul_f32_e32 v229, v229, v109
	v_mul_f32_e32 v230, v230, v110
	v_mul_f32_e32 v231, v231, v111
	v_cvt_pk_bf16_f32 v76, v216, v217
	v_cvt_pk_bf16_f32 v77, v218, v219
	v_cvt_pk_bf16_f32 v116, v220, v221
	v_cvt_pk_bf16_f32 v117, v222, v223
	v_cvt_pk_bf16_f32 v112, v224, v225
	v_cvt_pk_bf16_f32 v113, v226, v227
	v_cvt_pk_bf16_f32 v108, v228, v229
	v_cvt_pk_bf16_f32 v109, v230, v231
	v_mul_f32_e32 v24, v24, v178
	v_mul_f32_e32 v25, v25, v178
	v_mul_f32_e32 v26, v26, v178
	v_mul_f32_e32 v27, v27, v178
	v_mul_f32_e32 v60, v60, v179
	v_mul_f32_e32 v61, v61, v179
	v_mul_f32_e32 v62, v62, v179
	v_mul_f32_e32 v63, v63, v179
	v_mul_f32_e32 v56, v56, v180
	v_mul_f32_e32 v57, v57, v180
	v_mul_f32_e32 v58, v58, v180
	v_mul_f32_e32 v59, v59, v180
	v_mul_f32_e32 v4, v4, v181
	v_mul_f32_e32 v5, v5, v181
	v_mul_f32_e32 v6, v6, v181
	v_mul_f32_e32 v7, v7, v181
	v_mul_f32_e32 v232, v12, v178
	v_mul_f32_e32 v233, v13, v178
	v_mul_f32_e32 v234, v14, v178
	v_mul_f32_e32 v235, v15, v178
	s_add_i32 s15, s14, 2
	v_lshl_add_u32 v228, s15, 1, v152
	v_lshl_add_u32 v229, s15, 1, v154
	v_mad_u32_u24 v230, v228, s83, v205
	v_mad_u32_u24 v231, v229, s83, v205
	s_mov_b64 exec, s[8:9]
	global_store_dwordx4 v230, v[24:27], s[86:87]
	global_store_dwordx4 v230, v[232:235], s[28:29]
	s_mov_b64 exec, s[10:11]
	global_store_dwordx4 v231, v[4:7], s[30:31]
	s_mov_b64 exec, -1
	v_fma_f32 v216, v136, v24, v140
	v_fma_f32 v217, v137, v25, v141
	v_fma_f32 v218, v138, v26, v142
	v_fma_f32 v219, v139, v27, v143
	v_fma_f32 v220, v136, v60, v140
	v_fma_f32 v221, v137, v61, v141
	v_fma_f32 v222, v138, v62, v142
	v_fma_f32 v223, v139, v63, v143
	v_fma_f32 v224, v136, v56, v140
	v_fma_f32 v225, v137, v57, v141
	v_fma_f32 v226, v138, v58, v142
	v_fma_f32 v227, v139, v59, v143
	v_fma_f32 v228, v136, v4, v140
	v_fma_f32 v229, v137, v5, v141
	v_fma_f32 v230, v138, v6, v142
	v_fma_f32 v231, v139, v7, v143
	v_fmac_f32_dpp v216, v24, v132 row_shr:1 row_mask:0xf bank_mask:0xf
	v_fmac_f32_dpp v217, v25, v133 row_shr:1 row_mask:0xf bank_mask:0xf
	v_fmac_f32_dpp v218, v26, v134 row_shr:1 row_mask:0xf bank_mask:0xf
	v_fmac_f32_dpp v219, v27, v135 row_shr:1 row_mask:0xf bank_mask:0xf
	v_fmac_f32_dpp v220, v60, v132 row_shr:1 row_mask:0xf bank_mask:0xf
	v_fmac_f32_dpp v221, v61, v133 row_shr:1 row_mask:0xf bank_mask:0xf
	v_fmac_f32_dpp v222, v62, v134 row_shr:1 row_mask:0xf bank_mask:0xf
	v_fmac_f32_dpp v223, v63, v135 row_shr:1 row_mask:0xf bank_mask:0xf
	v_fmac_f32_dpp v224, v56, v132 row_shr:1 row_mask:0xf bank_mask:0xf
	v_fmac_f32_dpp v225, v57, v133 row_shr:1 row_mask:0xf bank_mask:0xf
	v_fmac_f32_dpp v226, v58, v134 row_shr:1 row_mask:0xf bank_mask:0xf
	v_fmac_f32_dpp v227, v59, v135 row_shr:1 row_mask:0xf bank_mask:0xf
	v_fmac_f32_dpp v228, v4, v132 row_shr:1 row_mask:0xf bank_mask:0xf
	v_fmac_f32_dpp v229, v5, v133 row_shr:1 row_mask:0xf bank_mask:0xf
	v_fmac_f32_dpp v230, v6, v134 row_shr:1 row_mask:0xf bank_mask:0xf
	v_fmac_f32_dpp v231, v7, v135 row_shr:1 row_mask:0xf bank_mask:0xf
	v_fmac_f32_dpp v216, v24, v128 row_shr:2 row_mask:0xf bank_mask:0xf
	v_fmac_f32_dpp v217, v25, v129 row_shr:2 row_mask:0xf bank_mask:0xf
	v_fmac_f32_dpp v218, v26, v130 row_shr:2 row_mask:0xf bank_mask:0xf
	v_fmac_f32_dpp v219, v27, v131 row_shr:2 row_mask:0xf bank_mask:0xf
	v_fmac_f32_dpp v220, v60, v128 row_shr:2 row_mask:0xf bank_mask:0xf
	v_fmac_f32_dpp v221, v61, v129 row_shr:2 row_mask:0xf bank_mask:0xf
	v_fmac_f32_dpp v222, v62, v130 row_shr:2 row_mask:0xf bank_mask:0xf
	v_fmac_f32_dpp v223, v63, v131 row_shr:2 row_mask:0xf bank_mask:0xf
	v_fmac_f32_dpp v224, v56, v128 row_shr:2 row_mask:0xf bank_mask:0xf
	v_fmac_f32_dpp v225, v57, v129 row_shr:2 row_mask:0xf bank_mask:0xf
	v_fmac_f32_dpp v226, v58, v130 row_shr:2 row_mask:0xf bank_mask:0xf
	v_fmac_f32_dpp v227, v59, v131 row_shr:2 row_mask:0xf bank_mask:0xf
	v_fmac_f32_dpp v228, v4, v128 row_shr:2 row_mask:0xf bank_mask:0xf
	v_fmac_f32_dpp v229, v5, v129 row_shr:2 row_mask:0xf bank_mask:0xf
	v_fmac_f32_dpp v230, v6, v130 row_shr:2 row_mask:0xf bank_mask:0xf
	v_fmac_f32_dpp v231, v7, v131 row_shr:2 row_mask:0xf bank_mask:0xf
	v_fmac_f32_dpp v220, v24, v164 row_ror:1 row_mask:0xf bank_mask:0xf
	v_fmac_f32_dpp v221, v25, v165 row_ror:1 row_mask:0xf bank_mask:0xf
	v_fmac_f32_dpp v222, v26, v166 row_ror:1 row_mask:0xf bank_mask:0xf
	v_fmac_f32_dpp v223, v27, v167 row_ror:1 row_mask:0xf bank_mask:0xf
	v_fmac_f32_dpp v224, v60, v164 row_ror:1 row_mask:0xf bank_mask:0xf
	v_fmac_f32_dpp v225, v61, v165 row_ror:1 row_mask:0xf bank_mask:0xf
	v_fmac_f32_dpp v226, v62, v166 row_ror:1 row_mask:0xf bank_mask:0xf
	v_fmac_f32_dpp v227, v63, v167 row_ror:1 row_mask:0xf bank_mask:0xf
	v_fmac_f32_dpp v228, v56, v164 row_ror:1 row_mask:0xf bank_mask:0xf
	v_fmac_f32_dpp v229, v57, v165 row_ror:1 row_mask:0xf bank_mask:0xf
	v_fmac_f32_dpp v230, v58, v166 row_ror:1 row_mask:0xf bank_mask:0xf
	v_fmac_f32_dpp v231, v59, v167 row_ror:1 row_mask:0xf bank_mask:0xf
	v_fmac_f32_dpp v220, v24, v168 row_ror:2 row_mask:0xf bank_mask:0xf
	v_fmac_f32_dpp v221, v25, v169 row_ror:2 row_mask:0xf bank_mask:0xf
	v_fmac_f32_dpp v222, v26, v170 row_ror:2 row_mask:0xf bank_mask:0xf
	v_fmac_f32_dpp v223, v27, v171 row_ror:2 row_mask:0xf bank_mask:0xf
	v_fmac_f32_dpp v224, v60, v168 row_ror:2 row_mask:0xf bank_mask:0xf
	v_fmac_f32_dpp v225, v61, v169 row_ror:2 row_mask:0xf bank_mask:0xf
	v_fmac_f32_dpp v226, v62, v170 row_ror:2 row_mask:0xf bank_mask:0xf
; __device__ __forceinline__ unsigned cvt_pk_bf16(float lo, float hi) { unsigned r; asm volatile("v_cvt_pk_bf16_f32 %0, %1, %2" : "=v"(r) : "v"(lo), "v"(hi)); return r; }
;     __device__ __forceinline__ void operator()(Acc& acc, const Unit& u, int wr, int wc, int fr, int fq) const {
;     ...
;                         const f32x2 a = w2p * gm[m] + (w1p * p1 + (w0p * p2 + bbp));
;                         const f32x2 na = a * (-1.4426950408889634f);
;                         f32x2 den; den.x = __builtin_amdgcn_exp2f(na.x); den.y = __builtin_amdgcn_exp2f(na.y);
;                         den = den + 1.0f;
;                         f32x2 rc; rc.x = __builtin_amdgcn_rcpf(den.x); rc.y = __builtin_amdgcn_rcpf(den.y);
;                         const f32x2 up = (f32x2){acc[ai][1][m][n][2 * jp], acc[ai][1][m][n][2 * jp + 1]} * rs[m];
;                         const f32x2 ov = (a * rc) * up;
;                         pk[m][2 * n + jp] = cvt_pk_bf16(ov.x, ov.y);
;                     }
;                 }
;             }
; #pragma unroll
;             for (int m = 0; m < 4; ++m) {
;                 const size_t row = (size_t)(row0 + ai * 128 + m * 16);
;                 if (!(m == 0 && fr < 2)) { u32x4 w; w.x = pk[m][0]; w.y = pk[m][1]; w.z = pk[m][2]; w.w = pk[m][3]; *(u32x4*)(act + row * FF + c0) = w; }
;             }
;             if (fr < 2) {
;                 const size_t o = ((size_t)blk * 2 + fr) * FF + c0;
;                 *(f32x4*)(gf + o) = acc[ai][0][0][0] * rs[0]; *(f32x4*)(gf + o + 4) = acc[ai][0][0][1] * rs[0];
;                 *(f32x4*)(uf + o) = acc[ai][1][0][0] * rs[0]; *(f32x4*)(uf + o + 4) = acc[ai][1][0][1] * rs[0];
;             }
;             if (fr >= 14) {
;                 const size_t o = ((size_t)blk * 2 + (fr - 14)) * FF + c0;
;                 *(f32x4*)(gl + o) = acc[ai][0][3][0] * rs[3]; *(f32x4*)(gl + o + 4) = acc[ai][0][3][1] * rs[3];
	v_fmac_f32_dpp v227, v63, v171 row_ror:2 row_mask:0xf bank_mask:0xf
	v_fmac_f32_dpp v228, v56, v168 row_ror:2 row_mask:0xf bank_mask:0xf
	v_fmac_f32_dpp v229, v57, v169 row_ror:2 row_mask:0xf bank_mask:0xf
	v_fmac_f32_dpp v230, v58, v170 row_ror:2 row_mask:0xf bank_mask:0xf
	v_fmac_f32_dpp v231, v59, v171 row_ror:2 row_mask:0xf bank_mask:0xf
	v_exp_f32_e32 v24, v216
	v_exp_f32_e32 v25, v217
	v_exp_f32_e32 v26, v218
	v_exp_f32_e32 v27, v219
	v_exp_f32_e32 v60, v220
	v_exp_f32_e32 v61, v221
	v_exp_f32_e32 v62, v222
	v_exp_f32_e32 v63, v223
	v_exp_f32_e32 v56, v224
	v_exp_f32_e32 v57, v225
	v_exp_f32_e32 v58, v226
	v_exp_f32_e32 v59, v227
	v_exp_f32_e32 v4, v228
	v_exp_f32_e32 v5, v229
	v_exp_f32_e32 v6, v230
	v_exp_f32_e32 v7, v231
	v_add_f32_e32 v24, 1.0, v24
	v_add_f32_e32 v25, 1.0, v25
	v_add_f32_e32 v26, 1.0, v26
	v_add_f32_e32 v27, 1.0, v27
	v_add_f32_e32 v60, 1.0, v60
	v_add_f32_e32 v61, 1.0, v61
	v_add_f32_e32 v62, 1.0, v62
	v_add_f32_e32 v63, 1.0, v63
	v_add_f32_e32 v56, 1.0, v56
	v_add_f32_e32 v57, 1.0, v57
	v_add_f32_e32 v58, 1.0, v58
	v_add_f32_e32 v59, 1.0, v59
	v_add_f32_e32 v4, 1.0, v4
	v_add_f32_e32 v5, 1.0, v5
	v_add_f32_e32 v6, 1.0, v6
	v_add_f32_e32 v7, 1.0, v7
	v_rcp_f32_e32 v24, v24
	v_rcp_f32_e32 v25, v25
	v_rcp_f32_e32 v26, v26
	v_rcp_f32_e32 v27, v27
	v_rcp_f32_e32 v60, v60
	v_rcp_f32_e32 v61, v61
	v_rcp_f32_e32 v62, v62
	v_rcp_f32_e32 v63, v63
	v_rcp_f32_e32 v56, v56
	v_rcp_f32_e32 v57, v57
	v_rcp_f32_e32 v58, v58
	v_rcp_f32_e32 v59, v59
	v_rcp_f32_e32 v4, v4
	v_rcp_f32_e32 v5, v5
	v_rcp_f32_e32 v6, v6
	v_rcp_f32_e32 v7, v7
	v_mul_f32_e32 v12, v12, v186
	v_mul_f32_e32 v13, v13, v186
	v_mul_f32_e32 v14, v14, v186
	v_mul_f32_e32 v15, v15, v186
	v_mul_f32_e32 v52, v52, v188
	v_mul_f32_e32 v53, v53, v188
	v_mul_f32_e32 v54, v54, v188
	v_mul_f32_e32 v55, v55, v188
	v_mul_f32_e32 v48, v48, v190
	v_mul_f32_e32 v49, v49, v190
	v_mul_f32_e32 v50, v50, v190
	v_mul_f32_e32 v51, v51, v190
	v_mul_f32_e32 v44, v44, v192
	v_mul_f32_e32 v45, v45, v192
	v_mul_f32_e32 v46, v46, v192
	v_mul_f32_e32 v47, v47, v192
	v_mul_f32_e32 v216, v216, v24
	v_mul_f32_e32 v217, v217, v25
	v_mul_f32_e32 v218, v218, v26
	v_mul_f32_e32 v219, v219, v27
	v_mul_f32_e32 v220, v220, v60
	v_mul_f32_e32 v221, v221, v61
	v_mul_f32_e32 v222, v222, v62
	v_mul_f32_e32 v223, v223, v63
	v_mul_f32_e32 v224, v224, v56
	v_mul_f32_e32 v225, v225, v57
	v_mul_f32_e32 v226, v226, v58
	v_mul_f32_e32 v227, v227, v59
	v_mul_f32_e32 v228, v228, v4
	v_mul_f32_e32 v229, v229, v5
	v_mul_f32_e32 v230, v230, v6
	v_mul_f32_e32 v231, v231, v7
	v_mul_f32_e32 v216, v216, v12
	v_mul_f32_e32 v217, v217, v13
	v_mul_f32_e32 v218, v218, v14
	v_mul_f32_e32 v219, v219, v15
	v_mul_f32_e32 v220, v220, v52
	v_mul_f32_e32 v221, v221, v53
	v_mul_f32_e32 v222, v222, v54
	v_mul_f32_e32 v223, v223, v55
	v_mul_f32_e32 v224, v224, v48
	v_mul_f32_e32 v225, v225, v49
	v_mul_f32_e32 v226, v226, v50
	v_mul_f32_e32 v227, v227, v51
	v_mul_f32_e32 v228, v228, v44
	v_mul_f32_e32 v229, v229, v45
	v_mul_f32_e32 v230, v230, v46
	v_mul_f32_e32 v231, v231, v47
	v_cvt_pk_bf16_f32 v12, v216, v217
	v_cvt_pk_bf16_f32 v13, v218, v219
	v_cvt_pk_bf16_f32 v52, v220, v221
	v_cvt_pk_bf16_f32 v53, v222, v223
	v_cvt_pk_bf16_f32 v48, v224, v225
	v_cvt_pk_bf16_f32 v49, v226, v227
	v_cvt_pk_bf16_f32 v44, v228, v229
	v_cvt_pk_bf16_f32 v45, v230, v231
	v_cndmask_b32_e64 v164, 0, v200, s[4:5]
	v_cndmask_b32_e64 v168, 0, v196, s[8:9]
	v_cndmask_b32_e64 v165, 0, v201, s[4:5]
	v_cndmask_b32_e64 v169, 0, v197, s[8:9]
	v_cndmask_b32_e64 v166, 0, v202, s[4:5]
	v_cndmask_b32_e64 v170, 0, v198, s[8:9]
	v_cndmask_b32_e64 v167, 0, v203, s[4:5]
	v_cndmask_b32_e64 v171, 0, v199, s[8:9]
	v_mul_f32_e32 v80, v80, v172
	v_mul_f32_e32 v81, v81, v172
	v_mul_f32_e32 v82, v82, v172
	v_mul_f32_e32 v83, v83, v172
	v_mul_f32_e32 v104, v104, v173
	v_mul_f32_e32 v105, v105, v173
	v_mul_f32_e32 v106, v106, v173
	v_mul_f32_e32 v107, v107, v173
	v_mul_f32_e32 v100, v100, v174
	v_mul_f32_e32 v101, v101, v174
	v_mul_f32_e32 v102, v102, v174
	v_mul_f32_e32 v103, v103, v174
	v_mul_f32_e32 v64, v64, v175
	v_mul_f32_e32 v65, v65, v175
	v_mul_f32_e32 v66, v66, v175
	v_mul_f32_e32 v67, v67, v175
	v_mul_f32_e32 v232, v72, v172
	v_mul_f32_e32 v233, v73, v172
	v_mul_f32_e32 v234, v74, v172
	v_mul_f32_e32 v235, v75, v172
	s_add_i32 s15, s14, 0
	v_lshl_add_u32 v228, s15, 1, v152
	v_lshl_add_u32 v229, s15, 1, v154
	v_mad_u32_u24 v230, v228, s83, v205
	v_mad_u32_u24 v231, v229, s83, v205
	s_mov_b64 exec, s[8:9]
	global_store_dwordx4 v230, v[80:83], s[86:87] offset:16
	global_store_dwordx4 v230, v[232:235], s[28:29] offset:16
	s_mov_b64 exec, s[10:11]
	global_store_dwordx4 v231, v[64:67], s[30:31] offset:16
	s_mov_b64 exec, -1
	v_fma_f32 v216, v208, v80, v212
	v_fma_f32 v217, v209, v81, v213
	v_fma_f32 v218, v210, v82, v214
	v_fma_f32 v219, v211, v83, v215
	v_fma_f32 v220, v208, v104, v212
	v_fma_f32 v221, v209, v105, v213
	v_fma_f32 v222, v210, v106, v214
	v_fma_f32 v223, v211, v107, v215
	v_fma_f32 v224, v208, v100, v212
	v_fma_f32 v225, v209, v101, v213
	v_fma_f32 v226, v210, v102, v214
	v_fma_f32 v227, v211, v103, v215
	v_fma_f32 v228, v208, v64, v212
	v_fma_f32 v229, v209, v65, v213
	v_fma_f32 v230, v210, v66, v214
	v_fma_f32 v231, v211, v67, v215
	v_fmac_f32_dpp v216, v80, v200 row_shr:1 row_mask:0xf bank_mask:0xf
	v_fmac_f32_dpp v217, v81, v201 row_shr:1 row_mask:0xf bank_mask:0xf
	v_fmac_f32_dpp v218, v82, v202 row_shr:1 row_mask:0xf bank_mask:0xf
	v_fmac_f32_dpp v219, v83, v203 row_shr:1 row_mask:0xf bank_mask:0xf
	v_fmac_f32_dpp v220, v104, v200 row_shr:1 row_mask:0xf bank_mask:0xf
	v_fmac_f32_dpp v221, v105, v201 row_shr:1 row_mask:0xf bank_mask:0xf
; __device__ __forceinline__ unsigned cvt_pk_bf16(float lo, float hi) { unsigned r; asm volatile("v_cvt_pk_bf16_f32 %0, %1, %2" : "=v"(r) : "v"(lo), "v"(hi)); return r; }
;     __device__ __forceinline__ void operator()(Acc& acc, const Unit& u, int wr, int wc, int fr, int fq) const {
;     ...
;                     for (int m = 0; m < 4; ++m) {
;                         const f32x2 q1 = m >= 1 ? r1[m >= 1 ? m - 1 : 0] : (f32x2){0.f, 0.f}, q2 = m >= 1 ? r2[m >= 1 ? m - 1 : 0] : (f32x2){0.f, 0.f};
;                         f32x2 p1, p2;
;                         p1.x = (fr >= 1) ? r1[m].x : q1.x; p1.y = (fr >= 1) ? r1[m].y : q1.y;
;                         p2.x = (fr >= 2) ? r2[m].x : q2.x; p2.y = (fr >= 2) ? r2[m].y : q2.y;
;                         const f32x2 a = w2p * gm[m] + (w1p * p1 + (w0p * p2 + bbp));
;                         const f32x2 na = a * (-1.4426950408889634f);
;                         f32x2 den; den.x = __builtin_amdgcn_exp2f(na.x); den.y = __builtin_amdgcn_exp2f(na.y);
;                         den = den + 1.0f;
;                         f32x2 rc; rc.x = __builtin_amdgcn_rcpf(den.x); rc.y = __builtin_amdgcn_rcpf(den.y);
;                         const f32x2 up = (f32x2){acc[ai][1][m][n][2 * jp], acc[ai][1][m][n][2 * jp + 1]} * rs[m];
;                         const f32x2 ov = (a * rc) * up;
;                         pk[m][2 * n + jp] = cvt_pk_bf16(ov.x, ov.y);
	v_fmac_f32_dpp v222, v106, v202 row_shr:1 row_mask:0xf bank_mask:0xf
	v_fmac_f32_dpp v223, v107, v203 row_shr:1 row_mask:0xf bank_mask:0xf
	v_fmac_f32_dpp v224, v100, v200 row_shr:1 row_mask:0xf bank_mask:0xf
	v_fmac_f32_dpp v225, v101, v201 row_shr:1 row_mask:0xf bank_mask:0xf
	v_fmac_f32_dpp v226, v102, v202 row_shr:1 row_mask:0xf bank_mask:0xf
	v_fmac_f32_dpp v227, v103, v203 row_shr:1 row_mask:0xf bank_mask:0xf
	v_fmac_f32_dpp v228, v64, v200 row_shr:1 row_mask:0xf bank_mask:0xf
	v_fmac_f32_dpp v229, v65, v201 row_shr:1 row_mask:0xf bank_mask:0xf
	v_fmac_f32_dpp v230, v66, v202 row_shr:1 row_mask:0xf bank_mask:0xf
	v_fmac_f32_dpp v231, v67, v203 row_shr:1 row_mask:0xf bank_mask:0xf
	v_fmac_f32_dpp v216, v80, v196 row_shr:2 row_mask:0xf bank_mask:0xf
	v_fmac_f32_dpp v217, v81, v197 row_shr:2 row_mask:0xf bank_mask:0xf
	v_fmac_f32_dpp v218, v82, v198 row_shr:2 row_mask:0xf bank_mask:0xf
	v_fmac_f32_dpp v219, v83, v199 row_shr:2 row_mask:0xf bank_mask:0xf
	v_fmac_f32_dpp v220, v104, v196 row_shr:2 row_mask:0xf bank_mask:0xf
	v_fmac_f32_dpp v221, v105, v197 row_shr:2 row_mask:0xf bank_mask:0xf
	v_fmac_f32_dpp v222, v106, v198 row_shr:2 row_mask:0xf bank_mask:0xf
	v_fmac_f32_dpp v223, v107, v199 row_shr:2 row_mask:0xf bank_mask:0xf
	v_fmac_f32_dpp v224, v100, v196 row_shr:2 row_mask:0xf bank_mask:0xf
	v_fmac_f32_dpp v225, v101, v197 row_shr:2 row_mask:0xf bank_mask:0xf
	v_fmac_f32_dpp v226, v102, v198 row_shr:2 row_mask:0xf bank_mask:0xf
	v_fmac_f32_dpp v227, v103, v199 row_shr:2 row_mask:0xf bank_mask:0xf
	v_fmac_f32_dpp v228, v64, v196 row_shr:2 row_mask:0xf bank_mask:0xf
	v_fmac_f32_dpp v229, v65, v197 row_shr:2 row_mask:0xf bank_mask:0xf
	v_fmac_f32_dpp v230, v66, v198 row_shr:2 row_mask:0xf bank_mask:0xf
	v_fmac_f32_dpp v231, v67, v199 row_shr:2 row_mask:0xf bank_mask:0xf
	v_fmac_f32_dpp v220, v80, v164 row_ror:1 row_mask:0xf bank_mask:0xf
	v_fmac_f32_dpp v221, v81, v165 row_ror:1 row_mask:0xf bank_mask:0xf
	v_fmac_f32_dpp v222, v82, v166 row_ror:1 row_mask:0xf bank_mask:0xf
	v_fmac_f32_dpp v223, v83, v167 row_ror:1 row_mask:0xf bank_mask:0xf
	v_fmac_f32_dpp v224, v104, v164 row_ror:1 row_mask:0xf bank_mask:0xf
	v_fmac_f32_dpp v225, v105, v165 row_ror:1 row_mask:0xf bank_mask:0xf
	v_fmac_f32_dpp v226, v106, v166 row_ror:1 row_mask:0xf bank_mask:0xf
	v_fmac_f32_dpp v227, v107, v167 row_ror:1 row_mask:0xf bank_mask:0xf
	v_fmac_f32_dpp v228, v100, v164 row_ror:1 row_mask:0xf bank_mask:0xf
	v_fmac_f32_dpp v229, v101, v165 row_ror:1 row_mask:0xf bank_mask:0xf
	v_fmac_f32_dpp v230, v102, v166 row_ror:1 row_mask:0xf bank_mask:0xf
	v_fmac_f32_dpp v231, v103, v167 row_ror:1 row_mask:0xf bank_mask:0xf
	v_fmac_f32_dpp v220, v80, v168 row_ror:2 row_mask:0xf bank_mask:0xf
	v_fmac_f32_dpp v221, v81, v169 row_ror:2 row_mask:0xf bank_mask:0xf
	v_fmac_f32_dpp v222, v82, v170 row_ror:2 row_mask:0xf bank_mask:0xf
	v_fmac_f32_dpp v223, v83, v171 row_ror:2 row_mask:0xf bank_mask:0xf
	v_fmac_f32_dpp v224, v104, v168 row_ror:2 row_mask:0xf bank_mask:0xf
	v_fmac_f32_dpp v225, v105, v169 row_ror:2 row_mask:0xf bank_mask:0xf
	v_fmac_f32_dpp v226, v106, v170 row_ror:2 row_mask:0xf bank_mask:0xf
	v_fmac_f32_dpp v227, v107, v171 row_ror:2 row_mask:0xf bank_mask:0xf
	v_fmac_f32_dpp v228, v100, v168 row_ror:2 row_mask:0xf bank_mask:0xf
	v_fmac_f32_dpp v229, v101, v169 row_ror:2 row_mask:0xf bank_mask:0xf
	v_fmac_f32_dpp v230, v102, v170 row_ror:2 row_mask:0xf bank_mask:0xf
	v_fmac_f32_dpp v231, v103, v171 row_ror:2 row_mask:0xf bank_mask:0xf
	v_exp_f32_e32 v80, v216
	v_exp_f32_e32 v81, v217
	v_exp_f32_e32 v82, v218
	v_exp_f32_e32 v83, v219
	v_exp_f32_e32 v104, v220
	v_exp_f32_e32 v105, v221
	v_exp_f32_e32 v106, v222
	v_exp_f32_e32 v107, v223
	v_exp_f32_e32 v100, v224
	v_exp_f32_e32 v101, v225
	v_exp_f32_e32 v102, v226
	v_exp_f32_e32 v103, v227
	v_exp_f32_e32 v64, v228
	v_exp_f32_e32 v65, v229
	v_exp_f32_e32 v66, v230
	v_exp_f32_e32 v67, v231
	v_add_f32_e32 v80, 1.0, v80
	v_add_f32_e32 v81, 1.0, v81
	v_add_f32_e32 v82, 1.0, v82
	v_add_f32_e32 v83, 1.0, v83
	v_add_f32_e32 v104, 1.0, v104
	v_add_f32_e32 v105, 1.0, v105
	v_add_f32_e32 v106, 1.0, v106
	v_add_f32_e32 v107, 1.0, v107
	v_add_f32_e32 v100, 1.0, v100
	v_add_f32_e32 v101, 1.0, v101
	v_add_f32_e32 v102, 1.0, v102
	v_add_f32_e32 v103, 1.0, v103
	v_add_f32_e32 v64, 1.0, v64
	v_add_f32_e32 v65, 1.0, v65
	v_add_f32_e32 v66, 1.0, v66
	v_add_f32_e32 v67, 1.0, v67
	v_rcp_f32_e32 v80, v80
	v_rcp_f32_e32 v81, v81
	v_rcp_f32_e32 v82, v82
	v_rcp_f32_e32 v83, v83
	v_rcp_f32_e32 v104, v104
	v_rcp_f32_e32 v105, v105
	v_rcp_f32_e32 v106, v106
	v_rcp_f32_e32 v107, v107
	v_rcp_f32_e32 v100, v100
	v_rcp_f32_e32 v101, v101
	v_rcp_f32_e32 v102, v102
	v_rcp_f32_e32 v103, v103
	v_rcp_f32_e32 v64, v64
	v_rcp_f32_e32 v65, v65
	v_rcp_f32_e32 v66, v66
	v_rcp_f32_e32 v67, v67
	v_mul_f32_e32 v72, v72, v182
	v_mul_f32_e32 v73, v73, v182
	v_mul_f32_e32 v74, v74, v182
	v_mul_f32_e32 v75, v75, v182
	v_mul_f32_e32 v96, v96, v183
	v_mul_f32_e32 v97, v97, v183
	v_mul_f32_e32 v98, v98, v183
	v_mul_f32_e32 v99, v99, v183
	v_mul_f32_e32 v92, v92, v184
	v_mul_f32_e32 v93, v93, v184
	v_mul_f32_e32 v94, v94, v184
	v_mul_f32_e32 v95, v95, v184
	v_mul_f32_e32 v88, v88, v185
	v_mul_f32_e32 v89, v89, v185
	v_mul_f32_e32 v90, v90, v185
	v_mul_f32_e32 v91, v91, v185
	v_mul_f32_e32 v216, v216, v80
	v_mul_f32_e32 v217, v217, v81
	v_mul_f32_e32 v218, v218, v82
	v_mul_f32_e32 v219, v219, v83
	v_mul_f32_e32 v220, v220, v104
	v_mul_f32_e32 v221, v221, v105
	v_mul_f32_e32 v222, v222, v106
	v_mul_f32_e32 v223, v223, v107
	v_mul_f32_e32 v224, v224, v100
	v_mul_f32_e32 v225, v225, v101
	v_mul_f32_e32 v226, v226, v102
	v_mul_f32_e32 v227, v227, v103
; __device__ __forceinline__ unsigned cvt_pk_bf16(float lo, float hi) { unsigned r; asm volatile("v_cvt_pk_bf16_f32 %0, %1, %2" : "=v"(r) : "v"(lo), "v"(hi)); return r; }
;     __device__ __forceinline__ void operator()(Acc& acc, const Unit& u, int wr, int wc, int fr, int fq) const {
;     ...
;                         const f32x2 up = (f32x2){acc[ai][1][m][n][2 * jp], acc[ai][1][m][n][2 * jp + 1]} * rs[m];
;                         const f32x2 ov = (a * rc) * up;
;                         pk[m][2 * n + jp] = cvt_pk_bf16(ov.x, ov.y);
;                     }
;                 }
;             }
; #pragma unroll
;             for (int m = 0; m < 4; ++m) {
;                 const size_t row = (size_t)(row0 + ai * 128 + m * 16);
;                 if (!(m == 0 && fr < 2)) { u32x4 w; w.x = pk[m][0]; w.y = pk[m][1]; w.z = pk[m][2]; w.w = pk[m][3]; *(u32x4*)(act + row * FF + c0) = w; }
;             }
;             if (fr < 2) {
;                 const size_t o = ((size_t)blk * 2 + fr) * FF + c0;
;                 *(f32x4*)(gf + o) = acc[ai][0][0][0] * rs[0]; *(f32x4*)(gf + o + 4) = acc[ai][0][0][1] * rs[0];
;                 *(f32x4*)(uf + o) = acc[ai][1][0][0] * rs[0]; *(f32x4*)(uf + o + 4) = acc[ai][1][0][1] * rs[0];
;             }
;             if (fr >= 14) {
;                 const size_t o = ((size_t)blk * 2 + (fr - 14)) * FF + c0;
;                 *(f32x4*)(gl + o) = acc[ai][0][3][0] * rs[3]; *(f32x4*)(gl + o + 4) = acc[ai][0][3][1] * rs[3];
	v_mul_f32_e32 v228, v228, v64
	v_mul_f32_e32 v229, v229, v65
	v_mul_f32_e32 v230, v230, v66
	v_mul_f32_e32 v231, v231, v67
	v_mul_f32_e32 v216, v216, v72
	v_mul_f32_e32 v217, v217, v73
	v_mul_f32_e32 v218, v218, v74
	v_mul_f32_e32 v219, v219, v75
	v_mul_f32_e32 v220, v220, v96
	v_mul_f32_e32 v221, v221, v97
	v_mul_f32_e32 v222, v222, v98
	v_mul_f32_e32 v223, v223, v99
	v_mul_f32_e32 v224, v224, v92
	v_mul_f32_e32 v225, v225, v93
	v_mul_f32_e32 v226, v226, v94
	v_mul_f32_e32 v227, v227, v95
	v_mul_f32_e32 v228, v228, v88
	v_mul_f32_e32 v229, v229, v89
	v_mul_f32_e32 v230, v230, v90
	v_mul_f32_e32 v231, v231, v91
	v_cvt_pk_bf16_f32 v78, v216, v217
	v_cvt_pk_bf16_f32 v79, v218, v219
	v_cvt_pk_bf16_f32 v118, v220, v221
	v_cvt_pk_bf16_f32 v119, v222, v223
	v_cvt_pk_bf16_f32 v114, v224, v225
	v_cvt_pk_bf16_f32 v115, v226, v227
	v_cvt_pk_bf16_f32 v110, v228, v229
	v_cvt_pk_bf16_f32 v111, v230, v231
	s_mov_b32 s16, s26
	s_mov_b32 s17, s27
	s_mov_b64 exec, s[6:7]
	global_store_dwordx4 v207, v[76:79], s[16:17]
	s_mov_b64 exec, -1
	s_add_u32 s16, s26, 0x2c000
	s_addc_u32 s17, s27, 0
	global_store_dwordx4 v207, v[116:119], s[16:17]
	s_add_u32 s16, s26, 0x58000
	s_addc_u32 s17, s27, 0
	global_store_dwordx4 v207, v[112:115], s[16:17]
	s_add_u32 s16, s26, 0x84000
	s_addc_u32 s17, s27, 0
	global_store_dwordx4 v207, v[108:111], s[16:17]
	v_mul_f32_e32 v16, v16, v178
	v_mul_f32_e32 v17, v17, v178
	v_mul_f32_e32 v18, v18, v178
	v_mul_f32_e32 v19, v19, v178
	v_mul_f32_e32 v40, v40, v179
	v_mul_f32_e32 v41, v41, v179
	v_mul_f32_e32 v42, v42, v179
	v_mul_f32_e32 v43, v43, v179
	v_mul_f32_e32 v36, v36, v180
	v_mul_f32_e32 v37, v37, v180
	v_mul_f32_e32 v38, v38, v180
	v_mul_f32_e32 v39, v39, v180
	v_mul_f32_e32 v0, v0, v181
	v_mul_f32_e32 v1, v1, v181
	v_mul_f32_e32 v2, v2, v181
	v_mul_f32_e32 v3, v3, v181
	v_mul_f32_e32 v232, v8, v178
	v_mul_f32_e32 v233, v9, v178
	v_mul_f32_e32 v234, v10, v178
	v_mul_f32_e32 v235, v11, v178
	s_add_i32 s15, s14, 2
	v_lshl_add_u32 v228, s15, 1, v152
	v_lshl_add_u32 v229, s15, 1, v154
	v_mad_u32_u24 v230, v228, s83, v205
	v_mad_u32_u24 v231, v229, s83, v205
	s_mov_b64 exec, s[8:9]
	global_store_dwordx4 v230, v[16:19], s[86:87] offset:16
	global_store_dwordx4 v230, v[232:235], s[28:29] offset:16
	s_mov_b64 exec, s[10:11]
	global_store_dwordx4 v231, v[0:3], s[30:31] offset:16
	s_mov_b64 exec, -1
	v_fma_f32 v216, v208, v16, v212
	v_fma_f32 v217, v209, v17, v213
	v_fma_f32 v218, v210, v18, v214
	v_fma_f32 v219, v211, v19, v215
	v_fma_f32 v220, v208, v40, v212
	v_fma_f32 v221, v209, v41, v213
	v_fma_f32 v222, v210, v42, v214
	v_fma_f32 v223, v211, v43, v215
	v_fma_f32 v224, v208, v36, v212
	v_fma_f32 v225, v209, v37, v213
	v_fma_f32 v226, v210, v38, v214
	v_fma_f32 v227, v211, v39, v215
	v_fma_f32 v228, v208, v0, v212
	v_fma_f32 v229, v209, v1, v213
	v_fma_f32 v230, v210, v2, v214
	v_fma_f32 v231, v211, v3, v215
	v_fmac_f32_dpp v216, v16, v200 row_shr:1 row_mask:0xf bank_mask:0xf
	v_fmac_f32_dpp v217, v17, v201 row_shr:1 row_mask:0xf bank_mask:0xf
	v_fmac_f32_dpp v218, v18, v202 row_shr:1 row_mask:0xf bank_mask:0xf
	v_fmac_f32_dpp v219, v19, v203 row_shr:1 row_mask:0xf bank_mask:0xf
	v_fmac_f32_dpp v220, v40, v200 row_shr:1 row_mask:0xf bank_mask:0xf
	v_fmac_f32_dpp v221, v41, v201 row_shr:1 row_mask:0xf bank_mask:0xf
	v_fmac_f32_dpp v222, v42, v202 row_shr:1 row_mask:0xf bank_mask:0xf
	v_fmac_f32_dpp v223, v43, v203 row_shr:1 row_mask:0xf bank_mask:0xf
	v_fmac_f32_dpp v224, v36, v200 row_shr:1 row_mask:0xf bank_mask:0xf
	v_fmac_f32_dpp v225, v37, v201 row_shr:1 row_mask:0xf bank_mask:0xf
	v_fmac_f32_dpp v226, v38, v202 row_shr:1 row_mask:0xf bank_mask:0xf
	v_fmac_f32_dpp v227, v39, v203 row_shr:1 row_mask:0xf bank_mask:0xf
	v_fmac_f32_dpp v228, v0, v200 row_shr:1 row_mask:0xf bank_mask:0xf
	v_fmac_f32_dpp v229, v1, v201 row_shr:1 row_mask:0xf bank_mask:0xf
	v_fmac_f32_dpp v230, v2, v202 row_shr:1 row_mask:0xf bank_mask:0xf
	v_fmac_f32_dpp v231, v3, v203 row_shr:1 row_mask:0xf bank_mask:0xf
	v_fmac_f32_dpp v216, v16, v196 row_shr:2 row_mask:0xf bank_mask:0xf
	v_fmac_f32_dpp v217, v17, v197 row_shr:2 row_mask:0xf bank_mask:0xf
	v_fmac_f32_dpp v218, v18, v198 row_shr:2 row_mask:0xf bank_mask:0xf
	v_fmac_f32_dpp v219, v19, v199 row_shr:2 row_mask:0xf bank_mask:0xf
	v_fmac_f32_dpp v220, v40, v196 row_shr:2 row_mask:0xf bank_mask:0xf
	v_fmac_f32_dpp v221, v41, v197 row_shr:2 row_mask:0xf bank_mask:0xf
	v_fmac_f32_dpp v222, v42, v198 row_shr:2 row_mask:0xf bank_mask:0xf
	v_fmac_f32_dpp v223, v43, v199 row_shr:2 row_mask:0xf bank_mask:0xf
	v_fmac_f32_dpp v224, v36, v196 row_shr:2 row_mask:0xf bank_mask:0xf
	v_fmac_f32_dpp v225, v37, v197 row_shr:2 row_mask:0xf bank_mask:0xf
	v_fmac_f32_dpp v226, v38, v198 row_shr:2 row_mask:0xf bank_mask:0xf
	v_fmac_f32_dpp v227, v39, v199 row_shr:2 row_mask:0xf bank_mask:0xf
	v_fmac_f32_dpp v228, v0, v196 row_shr:2 row_mask:0xf bank_mask:0xf
	v_fmac_f32_dpp v229, v1, v197 row_shr:2 row_mask:0xf bank_mask:0xf
	v_fmac_f32_dpp v230, v2, v198 row_shr:2 row_mask:0xf bank_mask:0xf
	v_fmac_f32_dpp v231, v3, v199 row_shr:2 row_mask:0xf bank_mask:0xf
	v_fmac_f32_dpp v220, v16, v164 row_ror:1 row_mask:0xf bank_mask:0xf
; __device__ __forceinline__ unsigned cvt_pk_bf16(float lo, float hi) { unsigned r; asm volatile("v_cvt_pk_bf16_f32 %0, %1, %2" : "=v"(r) : "v"(lo), "v"(hi)); return r; }
;     __device__ __forceinline__ void operator()(Acc& acc, const Unit& u, int wr, int wc, int fr, int fq) const {
;     ...
;                     for (int m = 0; m < 4; ++m) {
;                         const f32x2 q1 = m >= 1 ? r1[m >= 1 ? m - 1 : 0] : (f32x2){0.f, 0.f}, q2 = m >= 1 ? r2[m >= 1 ? m - 1 : 0] : (f32x2){0.f, 0.f};
;                         f32x2 p1, p2;
;                         p1.x = (fr >= 1) ? r1[m].x : q1.x; p1.y = (fr >= 1) ? r1[m].y : q1.y;
;                         p2.x = (fr >= 2) ? r2[m].x : q2.x; p2.y = (fr >= 2) ? r2[m].y : q2.y;
;                         const f32x2 a = w2p * gm[m] + (w1p * p1 + (w0p * p2 + bbp));
;                         const f32x2 na = a * (-1.4426950408889634f);
;                         f32x2 den; den.x = __builtin_amdgcn_exp2f(na.x); den.y = __builtin_amdgcn_exp2f(na.y);
;                         den = den + 1.0f;
;                         f32x2 rc; rc.x = __builtin_amdgcn_rcpf(den.x); rc.y = __builtin_amdgcn_rcpf(den.y);
;                         const f32x2 up = (f32x2){acc[ai][1][m][n][2 * jp], acc[ai][1][m][n][2 * jp + 1]} * rs[m];
;                         const f32x2 ov = (a * rc) * up;
;                         pk[m][2 * n + jp] = cvt_pk_bf16(ov.x, ov.y);
;                     }
;                 }
;             }
; #pragma unroll
;             for (int m = 0; m < 4; ++m) {
;                 const size_t row = (size_t)(row0 + ai * 128 + m * 16);
;                 if (!(m == 0 && fr < 2)) { u32x4 w; w.x = pk[m][0]; w.y = pk[m][1]; w.z = pk[m][2]; w.w = pk[m][3]; *(u32x4*)(act + row * FF + c0) = w; }
;             }
	v_fmac_f32_dpp v221, v17, v165 row_ror:1 row_mask:0xf bank_mask:0xf
	v_fmac_f32_dpp v222, v18, v166 row_ror:1 row_mask:0xf bank_mask:0xf
	v_fmac_f32_dpp v223, v19, v167 row_ror:1 row_mask:0xf bank_mask:0xf
	v_fmac_f32_dpp v224, v40, v164 row_ror:1 row_mask:0xf bank_mask:0xf
	v_fmac_f32_dpp v225, v41, v165 row_ror:1 row_mask:0xf bank_mask:0xf
	v_fmac_f32_dpp v226, v42, v166 row_ror:1 row_mask:0xf bank_mask:0xf
	v_fmac_f32_dpp v227, v43, v167 row_ror:1 row_mask:0xf bank_mask:0xf
	v_fmac_f32_dpp v228, v36, v164 row_ror:1 row_mask:0xf bank_mask:0xf
	v_fmac_f32_dpp v229, v37, v165 row_ror:1 row_mask:0xf bank_mask:0xf
	v_fmac_f32_dpp v230, v38, v166 row_ror:1 row_mask:0xf bank_mask:0xf
	v_fmac_f32_dpp v231, v39, v167 row_ror:1 row_mask:0xf bank_mask:0xf
	v_fmac_f32_dpp v220, v16, v168 row_ror:2 row_mask:0xf bank_mask:0xf
	v_fmac_f32_dpp v221, v17, v169 row_ror:2 row_mask:0xf bank_mask:0xf
	v_fmac_f32_dpp v222, v18, v170 row_ror:2 row_mask:0xf bank_mask:0xf
	v_fmac_f32_dpp v223, v19, v171 row_ror:2 row_mask:0xf bank_mask:0xf
	v_fmac_f32_dpp v224, v40, v168 row_ror:2 row_mask:0xf bank_mask:0xf
	v_fmac_f32_dpp v225, v41, v169 row_ror:2 row_mask:0xf bank_mask:0xf
	v_fmac_f32_dpp v226, v42, v170 row_ror:2 row_mask:0xf bank_mask:0xf
	v_fmac_f32_dpp v227, v43, v171 row_ror:2 row_mask:0xf bank_mask:0xf
	v_fmac_f32_dpp v228, v36, v168 row_ror:2 row_mask:0xf bank_mask:0xf
	v_fmac_f32_dpp v229, v37, v169 row_ror:2 row_mask:0xf bank_mask:0xf
	v_fmac_f32_dpp v230, v38, v170 row_ror:2 row_mask:0xf bank_mask:0xf
	v_fmac_f32_dpp v231, v39, v171 row_ror:2 row_mask:0xf bank_mask:0xf
	v_exp_f32_e32 v16, v216
	v_exp_f32_e32 v17, v217
	v_exp_f32_e32 v18, v218
	v_exp_f32_e32 v19, v219
	v_exp_f32_e32 v40, v220
	v_exp_f32_e32 v41, v221
	v_exp_f32_e32 v42, v222
	v_exp_f32_e32 v43, v223
	v_exp_f32_e32 v36, v224
	v_exp_f32_e32 v37, v225
	v_exp_f32_e32 v38, v226
	v_exp_f32_e32 v39, v227
	v_exp_f32_e32 v0, v228
	v_exp_f32_e32 v1, v229
	v_exp_f32_e32 v2, v230
	v_exp_f32_e32 v3, v231
	v_add_f32_e32 v16, 1.0, v16
	v_add_f32_e32 v17, 1.0, v17
	v_add_f32_e32 v18, 1.0, v18
	v_add_f32_e32 v19, 1.0, v19
	v_add_f32_e32 v40, 1.0, v40
	v_add_f32_e32 v41, 1.0, v41
	v_add_f32_e32 v42, 1.0, v42
	v_add_f32_e32 v43, 1.0, v43
	v_add_f32_e32 v36, 1.0, v36
	v_add_f32_e32 v37, 1.0, v37
	v_add_f32_e32 v38, 1.0, v38
	v_add_f32_e32 v39, 1.0, v39
	v_add_f32_e32 v0, 1.0, v0
	v_add_f32_e32 v1, 1.0, v1
	v_add_f32_e32 v2, 1.0, v2
	v_add_f32_e32 v3, 1.0, v3
	v_rcp_f32_e32 v16, v16
	v_rcp_f32_e32 v17, v17
	v_rcp_f32_e32 v18, v18
	v_rcp_f32_e32 v19, v19
	v_rcp_f32_e32 v40, v40
	v_rcp_f32_e32 v41, v41
	v_rcp_f32_e32 v42, v42
	v_rcp_f32_e32 v43, v43
	v_rcp_f32_e32 v36, v36
	v_rcp_f32_e32 v37, v37
	v_rcp_f32_e32 v38, v38
	v_rcp_f32_e32 v39, v39
	v_rcp_f32_e32 v0, v0
	v_rcp_f32_e32 v1, v1
	v_rcp_f32_e32 v2, v2
	v_rcp_f32_e32 v3, v3
	v_mul_f32_e32 v8, v8, v186
	v_mul_f32_e32 v9, v9, v186
	v_mul_f32_e32 v10, v10, v186
	v_mul_f32_e32 v11, v11, v186
	v_mul_f32_e32 v32, v32, v188
	v_mul_f32_e32 v33, v33, v188
	v_mul_f32_e32 v34, v34, v188
	v_mul_f32_e32 v35, v35, v188
	v_mul_f32_e32 v28, v28, v190
	v_mul_f32_e32 v29, v29, v190
	v_mul_f32_e32 v30, v30, v190
	v_mul_f32_e32 v31, v31, v190
	v_mul_f32_e32 v20, v20, v192
	v_mul_f32_e32 v21, v21, v192
	v_mul_f32_e32 v22, v22, v192
	v_mul_f32_e32 v23, v23, v192
	v_mul_f32_e32 v216, v216, v16
	v_mul_f32_e32 v217, v217, v17
	v_mul_f32_e32 v218, v218, v18
	v_mul_f32_e32 v219, v219, v19
	v_mul_f32_e32 v220, v220, v40
	v_mul_f32_e32 v221, v221, v41
	v_mul_f32_e32 v222, v222, v42
	v_mul_f32_e32 v223, v223, v43
	v_mul_f32_e32 v224, v224, v36
	v_mul_f32_e32 v225, v225, v37
	v_mul_f32_e32 v226, v226, v38
	v_mul_f32_e32 v227, v227, v39
	v_mul_f32_e32 v228, v228, v0
	v_mul_f32_e32 v229, v229, v1
	v_mul_f32_e32 v230, v230, v2
	v_mul_f32_e32 v231, v231, v3
	v_mul_f32_e32 v216, v216, v8
	v_mul_f32_e32 v217, v217, v9
	v_mul_f32_e32 v218, v218, v10
	v_mul_f32_e32 v219, v219, v11
	v_mul_f32_e32 v220, v220, v32
	v_mul_f32_e32 v221, v221, v33
	v_mul_f32_e32 v222, v222, v34
	v_mul_f32_e32 v223, v223, v35
	v_mul_f32_e32 v224, v224, v28
	v_mul_f32_e32 v225, v225, v29
	v_mul_f32_e32 v226, v226, v30
	v_mul_f32_e32 v227, v227, v31
	v_mul_f32_e32 v228, v228, v20
	v_mul_f32_e32 v229, v229, v21
	v_mul_f32_e32 v230, v230, v22
	v_mul_f32_e32 v231, v231, v23
	v_cvt_pk_bf16_f32 v14, v216, v217
	v_cvt_pk_bf16_f32 v15, v218, v219
	v_cvt_pk_bf16_f32 v54, v220, v221
	v_cvt_pk_bf16_f32 v55, v222, v223
	v_cvt_pk_bf16_f32 v50, v224, v225
	v_cvt_pk_bf16_f32 v51, v226, v227
	v_cvt_pk_bf16_f32 v46, v228, v229
	v_cvt_pk_bf16_f32 v47, v230, v231
	s_add_u32 s16, s26, 0x160000
	s_addc_u32 s17, s27, 0
	s_mov_b64 exec, s[6:7]
	global_store_dwordx4 v207, v[12:15], s[16:17]
	s_mov_b64 exec, -1
	s_add_u32 s16, s26, 0x18c000
	s_addc_u32 s17, s27, 0
	global_store_dwordx4 v207, v[52:55], s[16:17]
	s_add_u32 s16, s26, 0x1b8000
	s_addc_u32 s17, s27, 0
	global_store_dwordx4 v207, v[48:51], s[16:17]
	s_add_u32 s16, s26, 0x1e4000
	s_addc_u32 s17, s27, 0
	global_store_dwordx4 v207, v[44:47], s[16:17]
	s_andn2_b64 vcc, exec, s[12:13]
	s_mov_b64 s[12:13], -1
	s_cbranch_vccnz .LBB0_857
	s_branch .LBB0_877
